# attention steps: lane^32 exchanges via v_permlane32_swap instead of ds_bpermute; V-fragment lgkmcnt wait moved to first PV MFMA
# baseline (speedup 1.0000x reference)
; #define MFMA(a, b, c) __builtin_amdgcn_mfma_f32_32x32x16_bf16((a), (b), (c), 0, 0, 0)
; template <int DQK, bool MASKED, int MODE, class MF>
; DI void attn_step(const bf16_t* sK, const bf16_t* sVt, const bf16x8 (&qf)[DQK / 16], f32x16& o0, f32x16& o1, float& m, float& l,
;                   float sc, const MF& mf, int lane, f32x16 (&s)[2], float invl, bool lanevalid = true) {
;     ...
;   constexpr int KST = DQK + 8;
;   bf16x8 kf[2][DQK / 16];
; #pragma unroll
;   for (int sub = 0; sub < 2; ++sub)
; #pragma unroll
;     for (int ks = 0; ks < DQK / 16; ++ks) kf[sub][ks] = *(const bf16x8*)(sK + (sub * 32 + pr) * KST + ks * 16 + 8 * h);
;   __builtin_amdgcn_sched_barrier(0);
; #pragma unroll
;   for (int q = 0; q < 16; ++q) { s[0][q] = 0.f; s[1][q] = 0.f; }
; #pragma unroll
;   for (int ks = 0; ks < DQK / 16; ++ks) {
;     s[0] = MFMA(kf[0][ks], qf[ks], s[0]);
;     s[1] = MFMA(kf[1][ks], qf[ks], s[1]);
;   }
;   bf16x8 vf[2][2][2];
;   if (MODE != 1) {
; #pragma unroll
;     for (int sub = 0; sub < 2; ++sub)
; #pragma unroll
;       for (int s2 = 0; s2 < 2; ++s2) {
;         vf[sub][s2][0] = *(const bf16x8*)(sVt + r * 72 + sub * 32 + s2 * 16 + 8 * h);
;         vf[sub][s2][1] = *(const bf16x8*)(sVt + (32 + r) * 72 + sub * 32 + s2 * 16 + 8 * h);
;       }
;     __builtin_amdgcn_sched_barrier(0);
;   }
;   float mxr = -3.0e38f;
; #pragma unroll
;   for (int sub = 0; sub < 2; ++sub)
; #pragma unroll
;     for (int q = 0; q < 16; ++q) {
;       if (MASKED) { const int kk = sub * 32 + 16 * (q >> 3) + 8 * h + (q & 7); s[sub][q] = mf(kk) ? s[sub][q] : -3.0e38f; }
;       if (MODE != 2) mxr = fmaxf(mxr, s[sub][q]);
.LBB0_350:
	s_mulk_i32 s0, 0x4800
	v_add_u32_e32 v40, s0, v163
	ds_read_b128 v[32:35], v40
	ds_read_b128 v[96:99], v40 offset:32
	ds_read_b128 v[100:103], v40 offset:64
	ds_read_b128 v[104:107], v40 offset:96
	ds_read_b128 v[36:39], v40 offset:4608
	ds_read_b128 v[108:111], v40 offset:4640
	ds_read_b128 v[112:115], v40 offset:4672
	ds_read_b128 v[178:181], v40 offset:4704
	v_add_u32_e32 v116, s0, v137
	s_waitcnt lgkmcnt(7)
	v_mfma_f32_32x32x16_bf16 v[48:63], v[32:35], v[64:67], 0
	s_waitcnt lgkmcnt(3)
	v_mfma_f32_32x32x16_bf16 v[32:47], v[36:39], v[64:67], 0
	v_mfma_f32_32x32x16_bf16 v[48:63], v[96:99], v[68:71], v[48:63]
	v_add3_u32 v96, v116, v164, v171
	v_add3_u32 v97, v116, v165, v171
	s_waitcnt lgkmcnt(2)
	v_mfma_f32_32x32x16_bf16 v[32:47], v[108:111], v[68:71], v[32:47]
	v_mfma_f32_32x32x16_bf16 v[48:63], v[100:103], v[72:75], v[48:63]
	s_waitcnt lgkmcnt(1)
	v_mfma_f32_32x32x16_bf16 v[32:47], v[112:115], v[72:75], v[32:47]
	v_mfma_f32_32x32x16_bf16 v[48:63], v[104:107], v[76:79], v[48:63]
	ds_read_b128 v[124:127], v96 offset:9216
	ds_read_b128 v[116:119], v96 offset:9248
	ds_read_b128 v[120:123], v97 offset:9216
	ds_read_b128 v[112:115], v97 offset:9248
	ds_read_b128 v[108:111], v96 offset:9280
	ds_read_b128 v[100:103], v96 offset:9312
	ds_read_b128 v[104:107], v97 offset:9280
	ds_read_b128 v[96:99], v97 offset:9312
	s_waitcnt lgkmcnt(8)
	v_mfma_f32_32x32x16_bf16 v[32:47], v[178:181], v[76:79], v[32:47]
	v_add_u32_e32 v128, s38, v162
	v_cmp_le_u32_e32 vcc, v128, v150
	v_cmp_gt_i32_e64 s[0:1], v128, v151
	s_and_b64 vcc, vcc, s[0:1]
	v_cndmask_b32_e32 v48, v172, v48, vcc
	v_cmp_lt_u32_e32 vcc, v128, v150
	v_cmp_ge_i32_e64 s[0:1], v128, v151
	s_and_b64 vcc, vcc, s[0:1]
	v_add_u32_e32 v177, 2, v128
	v_cndmask_b32_e32 v49, v172, v49, vcc
	v_cmp_le_u32_e32 vcc, v177, v150
	v_cmp_gt_i32_e64 s[0:1], v177, v151
	s_and_b64 vcc, vcc, s[0:1]
	v_add_u32_e32 v177, 3, v128
	v_cndmask_b32_e32 v50, v172, v50, vcc
	v_cmp_le_u32_e32 vcc, v177, v150
	v_cmp_gt_i32_e64 s[0:1], v177, v151
	s_and_b64 vcc, vcc, s[0:1]
	v_add_u32_e32 v177, 4, v128
	v_cndmask_b32_e32 v51, v172, v51, vcc
	v_cmp_le_u32_e32 vcc, v177, v150
	v_cmp_gt_i32_e64 s[0:1], v177, v151
	s_and_b64 vcc, vcc, s[0:1]
	v_add_u32_e32 v177, 5, v128
	v_cndmask_b32_e32 v52, v172, v52, vcc
	v_cmp_le_u32_e32 vcc, v177, v150
	v_cmp_gt_i32_e64 s[0:1], v177, v151
	s_and_b64 vcc, vcc, s[0:1]
	v_add_u32_e32 v177, 6, v128
	v_cndmask_b32_e32 v53, v172, v53, vcc
	v_cmp_le_u32_e32 vcc, v177, v150
	v_cmp_gt_i32_e64 s[0:1], v177, v151
	v_add_u32_e32 v177, s38, v161
	s_and_b64 vcc, vcc, s[0:1]
	v_or_b32_e32 v178, 7, v177
	v_cndmask_b32_e32 v54, v172, v54, vcc
	v_cmp_le_u32_e32 vcc, v178, v150
	v_cmp_gt_i32_e64 s[0:1], v178, v151
	s_and_b64 vcc, vcc, s[0:1]
	v_add_u32_e32 v178, 16, v128
	v_cndmask_b32_e32 v55, v172, v55, vcc
	v_cmp_le_u32_e32 vcc, v178, v150
	v_cmp_gt_i32_e64 s[0:1], v178, v151
	s_and_b64 vcc, vcc, s[0:1]
	v_add_u32_e32 v178, 17, v128
	v_cndmask_b32_e32 v56, v172, v56, vcc
	v_cmp_le_u32_e32 vcc, v178, v150
	v_cmp_gt_i32_e64 s[0:1], v178, v151
	s_and_b64 vcc, vcc, s[0:1]
	v_add_u32_e32 v178, 18, v128
	v_cndmask_b32_e32 v57, v172, v57, vcc
	v_cmp_le_u32_e32 vcc, v178, v150
	v_cmp_gt_i32_e64 s[0:1], v178, v151
	s_and_b64 vcc, vcc, s[0:1]
	v_add_u32_e32 v178, 19, v128
	v_cndmask_b32_e32 v58, v172, v58, vcc
	v_cmp_le_u32_e32 vcc, v178, v150
	v_cmp_gt_i32_e64 s[0:1], v178, v151
	s_and_b64 vcc, vcc, s[0:1]
	v_add_u32_e32 v178, 20, v128
	v_cndmask_b32_e32 v59, v172, v59, vcc
	v_cmp_le_u32_e32 vcc, v178, v150
	v_cmp_gt_i32_e64 s[0:1], v178, v151
	s_and_b64 vcc, vcc, s[0:1]
	v_add_u32_e32 v178, 21, v128
	v_cndmask_b32_e32 v60, v172, v60, vcc
	v_cmp_le_u32_e32 vcc, v178, v150
	v_cmp_gt_i32_e64 s[0:1], v178, v151
	s_and_b64 vcc, vcc, s[0:1]
	v_add_u32_e32 v178, 22, v128
	v_cndmask_b32_e32 v61, v172, v61, vcc
	v_cmp_le_u32_e32 vcc, v178, v150
	v_cmp_gt_i32_e64 s[0:1], v178, v151
	s_and_b64 vcc, vcc, s[0:1]
	v_or_b32_e32 v178, 23, v177
	v_cndmask_b32_e32 v62, v172, v62, vcc
	v_cmp_le_u32_e32 vcc, v178, v150
	v_cmp_gt_i32_e64 s[0:1], v178, v151
	s_and_b64 vcc, vcc, s[0:1]
	v_add_u32_e32 v178, 32, v128
	v_cndmask_b32_e32 v63, v172, v63, vcc
	v_cmp_le_u32_e32 vcc, v178, v150
	v_cmp_gt_i32_e64 s[0:1], v178, v151
	s_and_b64 vcc, vcc, s[0:1]
	v_cndmask_b32_e32 v178, v172, v32, vcc
	v_add_u32_e32 v32, 33, v128
	v_cmp_le_u32_e32 vcc, v32, v150
	v_cmp_gt_i32_e64 s[0:1], v32, v151
	s_and_b64 vcc, vcc, s[0:1]
	v_add_u32_e32 v32, 34, v128
	v_cndmask_b32_e32 v33, v172, v33, vcc
	v_cmp_le_u32_e32 vcc, v32, v150
	v_cmp_gt_i32_e64 s[0:1], v32, v151
	s_and_b64 vcc, vcc, s[0:1]
	v_add_u32_e32 v32, 35, v128
	v_cndmask_b32_e32 v34, v172, v34, vcc
	v_cmp_le_u32_e32 vcc, v32, v150
	v_cmp_gt_i32_e64 s[0:1], v32, v151
	s_and_b64 vcc, vcc, s[0:1]
	v_add_u32_e32 v32, 36, v128
	v_cndmask_b32_e32 v35, v172, v35, vcc
	v_cmp_le_u32_e32 vcc, v32, v150
	v_cmp_gt_i32_e64 s[0:1], v32, v151
	s_and_b64 vcc, vcc, s[0:1]
	v_add_u32_e32 v32, 37, v128
	v_cndmask_b32_e32 v36, v172, v36, vcc
	v_cmp_le_u32_e32 vcc, v32, v150
	v_cmp_gt_i32_e64 s[0:1], v32, v151
	s_and_b64 vcc, vcc, s[0:1]
	v_add_u32_e32 v32, 38, v128
	v_cndmask_b32_e32 v37, v172, v37, vcc
	v_cmp_le_u32_e32 vcc, v32, v150
	v_cmp_gt_i32_e64 s[0:1], v32, v151
	s_and_b64 vcc, vcc, s[0:1]
	v_or_b32_e32 v32, 39, v177
	v_cndmask_b32_e32 v38, v172, v38, vcc
	v_cmp_le_u32_e32 vcc, v32, v150
	v_cmp_gt_i32_e64 s[0:1], v32, v151
	s_and_b64 vcc, vcc, s[0:1]
	v_add_u32_e32 v32, 48, v128
	v_cndmask_b32_e32 v39, v172, v39, vcc
	v_cmp_le_u32_e32 vcc, v32, v150
	v_cmp_gt_i32_e64 s[0:1], v32, v151
	s_and_b64 vcc, vcc, s[0:1]
	v_add_u32_e32 v32, 49, v128
	v_cndmask_b32_e32 v179, v172, v40, vcc
; DI float fexp2(float x) { return __builtin_amdgcn_exp2f(x); }
; DI float shx(float v, int m) { return __shfl_xor(v, m, 64); }
; template <int DQK, bool MASKED, int MODE, class MF>
; DI void attn_step(const bf16_t* sK, const bf16_t* sVt, const bf16x8 (&qf)[DQK / 16], f32x16& o0, f32x16& o1, float& m, float& l,
;                   float sc, const MF& mf, int lane, f32x16 (&s)[2], float invl, bool lanevalid = true) {
;     ...
;   float alpha = 1.f;
;   if (MODE != 2) {
;     float mx = fmaxf(m, mxr * sc);
;     mx = fmaxf(mx, shx(mx, 32));
;     if (!MASKED) mx = lanevalid ? mx : m;
;     alpha = fexp2(m - mx);
;     m = mx;
;   }
;   const float moff = (!MASKED && !lanevalid) ? 1.0e30f : m;
;   float ps = 0.f;
; #pragma unroll
;   for (int sub = 0; sub < 2; ++sub)
; #pragma unroll
;     for (int q = 0; q < 16; ++q) {
;       float pv = fexp2(__builtin_fmaf(s[sub][q], sc, -moff));
;       if (MASKED && MODE != 0) pv = (s[sub][q] > -1.0e38f) ? pv : 0.f;
;       if (MODE == 2) pv *= invl;
;       s[sub][q] = pv;
;       ps += pv;
;     }
;   if (MODE != 2) {
;     ps += shx(ps, 32);
;     l = l * alpha + ps;
;   }
;   if (MODE == 1) return;
;   if (MODE == 0) {
; #pragma unroll
;     for (int q = 0; q < 16; ++q) { o0[q] *= alpha; o1[q] *= alpha; }
	v_cmp_le_u32_e32 vcc, v32, v150
	v_cmp_gt_i32_e64 s[0:1], v32, v151
	s_and_b64 vcc, vcc, s[0:1]
	v_add_u32_e32 v32, 50, v128
	v_cndmask_b32_e32 v41, v172, v41, vcc
	v_cmp_le_u32_e32 vcc, v32, v150
	v_cmp_gt_i32_e64 s[0:1], v32, v151
	s_and_b64 vcc, vcc, s[0:1]
	v_add_u32_e32 v32, 51, v128
	v_cndmask_b32_e32 v42, v172, v42, vcc
	v_cmp_le_u32_e32 vcc, v32, v150
	v_cmp_gt_i32_e64 s[0:1], v32, v151
	s_and_b64 vcc, vcc, s[0:1]
	v_add_u32_e32 v32, 52, v128
	v_cndmask_b32_e32 v43, v172, v43, vcc
	v_cmp_le_u32_e32 vcc, v32, v150
	v_cmp_gt_i32_e64 s[0:1], v32, v151
	s_and_b64 vcc, vcc, s[0:1]
	v_add_u32_e32 v32, 53, v128
	v_cndmask_b32_e32 v44, v172, v44, vcc
	v_cmp_le_u32_e32 vcc, v32, v150
	v_cmp_gt_i32_e64 s[0:1], v32, v151
	s_and_b64 vcc, vcc, s[0:1]
	v_add_u32_e32 v32, 54, v128
	v_cndmask_b32_e32 v45, v172, v45, vcc
	v_cmp_le_u32_e32 vcc, v32, v150
	v_cmp_gt_i32_e64 s[0:1], v32, v151
	s_and_b64 vcc, vcc, s[0:1]
	v_or_b32_e32 v32, 55, v177
	v_cndmask_b32_e32 v46, v172, v46, vcc
	v_cmp_le_u32_e32 vcc, v32, v150
	v_cmp_gt_i32_e64 s[0:1], v32, v151
	v_max3_f32 v32, v48, s43, v49
	v_max3_f32 v32, v32, v50, v51
	v_max3_f32 v32, v32, v52, v53
	v_max3_f32 v32, v32, v54, v55
	v_max3_f32 v32, v32, v56, v57
	v_max3_f32 v32, v32, v58, v59
	v_max3_f32 v32, v32, v60, v61
	v_max3_f32 v32, v32, v62, v63
	v_max3_f32 v32, v32, v178, v33
	v_max3_f32 v32, v32, v34, v35
	v_max3_f32 v32, v32, v36, v37
	v_max3_f32 v32, v32, v38, v39
	v_max3_f32 v32, v32, v179, v41
	s_and_b64 vcc, vcc, s[0:1]
	v_max3_f32 v32, v32, v42, v43
	v_cndmask_b32_e32 v47, v172, v47, vcc
	v_max3_f32 v32, v32, v44, v45
	v_max3_f32 v32, v32, v46, v47
	v_mul_f32_e32 v32, 0x3e38aa3b, v32
	v_max_f32_e32 v40, v176, v176
	v_max_f32_e32 v32, v40, v32
	v_mov_b32_e32 v40, v32
	v_mov_b32_e32 v247, v32
	s_nop 1
	v_permlane32_swap_b32_e32 v40, v247
	v_xor_b32_e32 v40, v40, v247
	v_xor_b32_e32 v40, v40, v32
	s_add_i32 s47, s47, 1
	s_add_i32 s0, s46, s47
	s_add_i32 s38, s38, 64
	s_add_i32 s0, s0, -1
	v_max_f32_e32 v40, v40, v40
	v_max_f32_e32 v32, v32, v40
	v_fma_f32 v40, v48, s44, -v32
	v_exp_f32_e32 v48, v40
	v_fma_f32 v49, v49, s44, -v32
	v_exp_f32_e32 v49, v49
	v_fma_f32 v50, v50, s44, -v32
	v_exp_f32_e32 v50, v50
	v_fma_f32 v51, v51, s44, -v32
	v_exp_f32_e32 v51, v51
	v_fma_f32 v52, v52, s44, -v32
	v_add_f32_e32 v128, 0, v48
	v_exp_f32_e32 v52, v52
	v_fma_f32 v53, v53, s44, -v32
	v_add_f32_e32 v128, v49, v128
	v_exp_f32_e32 v53, v53
	v_fma_f32 v54, v54, s44, -v32
	v_add_f32_e32 v128, v50, v128
	v_exp_f32_e32 v54, v54
	v_fma_f32 v55, v55, s44, -v32
	v_add_f32_e32 v128, v51, v128
	v_exp_f32_e32 v55, v55
	v_fma_f32 v56, v56, s44, -v32
	v_add_f32_e32 v128, v52, v128
	v_exp_f32_e32 v56, v56
	v_fma_f32 v57, v57, s44, -v32
	v_add_f32_e32 v128, v53, v128
	v_exp_f32_e32 v57, v57
	v_fma_f32 v58, v58, s44, -v32
	v_add_f32_e32 v128, v54, v128
	v_exp_f32_e32 v58, v58
	v_fma_f32 v59, v59, s44, -v32
	v_add_f32_e32 v128, v55, v128
	v_exp_f32_e32 v59, v59
	v_fma_f32 v60, v60, s44, -v32
	v_add_f32_e32 v128, v56, v128
	v_exp_f32_e32 v60, v60
	v_fma_f32 v61, v61, s44, -v32
	v_add_f32_e32 v128, v57, v128
	v_exp_f32_e32 v61, v61
	v_fma_f32 v62, v62, s44, -v32
	v_add_f32_e32 v128, v58, v128
	v_exp_f32_e32 v62, v62
	v_fma_f32 v63, v63, s44, -v32
	v_sub_f32_e32 v40, v176, v32
	v_add_f32_e32 v128, v59, v128
	v_exp_f32_e32 v63, v63
	v_fma_f32 v176, v178, s44, -v32
	v_add_f32_e32 v128, v60, v128
	v_exp_f32_e32 v176, v176
	v_fma_f32 v33, v33, s44, -v32
	v_add_f32_e32 v128, v61, v128
	v_exp_f32_e32 v33, v33
	v_fma_f32 v34, v34, s44, -v32
	v_add_f32_e32 v128, v62, v128
	v_exp_f32_e32 v177, v34
	v_fma_f32 v34, v35, s44, -v32
	v_add_f32_e32 v128, v63, v128
	v_exp_f32_e32 v178, v34
	v_fma_f32 v34, v36, s44, -v32
	v_add_f32_e32 v128, v176, v128
	v_exp_f32_e32 v180, v34
	v_fma_f32 v35, v37, s44, -v32
	v_add_f32_e32 v34, v33, v128
	v_exp_f32_e32 v128, v35
	v_fma_f32 v35, v38, s44, -v32
	v_add_f32_e32 v34, v177, v34
	v_exp_f32_e32 v38, v35
	v_fma_f32 v35, v39, s44, -v32
	v_add_f32_e32 v34, v178, v34
	v_exp_f32_e32 v39, v35
	v_add_f32_e32 v34, v180, v34
	v_exp_f32_e32 v40, v40
	v_add_f32_e32 v34, v128, v34
	v_add_f32_e32 v34, v38, v34
	v_add_f32_e32 v181, v39, v34
	v_fma_f32 v34, v179, s44, -v32
	v_exp_f32_e32 v179, v34
	v_pk_mul_f32 v[14:15], v[14:15], v[40:41] op_sel_hi:[1,0]
	v_pk_mul_f32 v[12:13], v[12:13], v[40:41] op_sel_hi:[1,0]
	v_pk_mul_f32 v[10:11], v[10:11], v[40:41] op_sel_hi:[1,0]
	v_pk_mul_f32 v[8:9], v[8:9], v[40:41] op_sel_hi:[1,0]
	v_pk_mul_f32 v[6:7], v[6:7], v[40:41] op_sel_hi:[1,0]
	v_pk_mul_f32 v[4:5], v[4:5], v[40:41] op_sel_hi:[1,0]
	v_pk_mul_f32 v[2:3], v[2:3], v[40:41] op_sel_hi:[1,0]
	v_pk_mul_f32 v[0:1], v[0:1], v[40:41] op_sel_hi:[1,0]
	v_pk_mul_f32 v[30:31], v[30:31], v[40:41] op_sel_hi:[1,0]
	v_cvt_pk_bf16_f32 v34, v48, v49
	v_cvt_pk_bf16_f32 v35, v50, v51
	v_cvt_pk_bf16_f32 v36, v52, v53
	v_cvt_pk_bf16_f32 v37, v54, v55
	v_pk_mul_f32 v[28:29], v[28:29], v[40:41] op_sel_hi:[1,0]
	v_pk_mul_f32 v[26:27], v[26:27], v[40:41] op_sel_hi:[1,0]
	v_pk_mul_f32 v[24:25], v[24:25], v[40:41] op_sel_hi:[1,0]
	v_pk_mul_f32 v[22:23], v[22:23], v[40:41] op_sel_hi:[1,0]
	v_pk_mul_f32 v[20:21], v[20:21], v[40:41] op_sel_hi:[1,0]
	v_pk_mul_f32 v[18:19], v[18:19], v[40:41] op_sel_hi:[1,0]
	v_pk_mul_f32 v[16:17], v[16:17], v[40:41] op_sel_hi:[1,0]
	s_waitcnt lgkmcnt(0)
; #define MFMA(a, b, c) __builtin_amdgcn_mfma_f32_32x32x16_bf16((a), (b), (c), 0, 0, 0)
; DI unsigned pack2(float a, float b) { f32x2_t v = {a, b}; bf16x2_t r = __builtin_convertvector(v, bf16x2_t); return __builtin_bit_cast(unsigned, r); }
; DI float fexp2(float x) { return __builtin_amdgcn_exp2f(x); }
; DI float shx(float v, int m) { return __shfl_xor(v, m, 64); }
; template <int DQK, bool MASKED, int MODE, class MF>
; DI void attn_step(const bf16_t* sK, const bf16_t* sVt, const bf16x8 (&qf)[DQK / 16], f32x16& o0, f32x16& o1, float& m, float& l,
;                   float sc, const MF& mf, int lane, f32x16 (&s)[2], float invl, bool lanevalid = true) {
;     ...
;   float ps = 0.f;
; #pragma unroll
;   for (int sub = 0; sub < 2; ++sub)
; #pragma unroll
;     for (int q = 0; q < 16; ++q) {
;       float pv = fexp2(__builtin_fmaf(s[sub][q], sc, -moff));
;       if (MASKED && MODE != 0) pv = (s[sub][q] > -1.0e38f) ? pv : 0.f;
;       if (MODE == 2) pv *= invl;
;       s[sub][q] = pv;
;       ps += pv;
;     }
;   if (MODE != 2) {
;     ps += shx(ps, 32);
;     l = l * alpha + ps;
;   }
;   if (MODE == 1) return;
;   if (MODE == 0) {
; #pragma unroll
;     for (int q = 0; q < 16; ++q) { o0[q] *= alpha; o1[q] *= alpha; }
;   }
; #pragma unroll
;   for (int sub = 0; sub < 2; ++sub)
; #pragma unroll
;     for (int s2 = 0; s2 < 2; ++s2) {
;       union { bf16x8 v; unsigned u[4]; } pb;
; #pragma unroll
;       for (int e = 0; e < 4; ++e) pb.u[e] = pack2(s[sub][8 * s2 + 2 * e], s[sub][8 * s2 + 2 * e + 1]);
;       o0 = MFMA(vf[sub][s2][0], pb.v, o0);
;       o1 = MFMA(vf[sub][s2][1], pb.v, o1);
;     }
	v_mfma_f32_32x32x16_bf16 v[0:15], v[124:127], v[34:37], v[0:15]
	v_fma_f32 v42, v42, s44, -v32
	v_exp_f32_e32 v42, v42
	v_fma_f32 v43, v43, s44, -v32
	v_exp_f32_e32 v43, v43
	v_fma_f32 v44, v44, s44, -v32
	v_add_f32_e32 v48, v179, v181
	v_exp_f32_e32 v44, v44
	v_mfma_f32_32x32x16_bf16 v[16:31], v[120:123], v[34:37], v[16:31]
	v_fma_f32 v34, v41, s44, -v32
	v_exp_f32_e32 v41, v34
	v_cvt_pk_bf16_f32 v34, v56, v57
	v_cvt_pk_bf16_f32 v35, v58, v59
	v_cvt_pk_bf16_f32 v36, v60, v61
	v_cvt_pk_bf16_f32 v37, v62, v63
	v_add_f32_e32 v48, v41, v48
	s_cmp_ge_u32 s0, s41
	v_mfma_f32_32x32x16_bf16 v[0:15], v[116:119], v[34:37], v[0:15]
	v_mfma_f32_32x32x16_bf16 v[16:31], v[112:115], v[34:37], v[16:31]
	v_add_f32_e32 v34, v42, v48
	v_add_f32_e32 v34, v43, v34
	v_add_f32_e32 v48, v44, v34
	v_cvt_pk_bf16_f32 v34, v176, v33
	v_cvt_pk_bf16_f32 v35, v177, v178
	v_cvt_pk_bf16_f32 v36, v180, v128
	v_cvt_pk_bf16_f32 v37, v38, v39
	v_fma_f32 v33, v45, s44, -v32
	v_fma_f32 v38, v46, s44, -v32
	v_mfma_f32_32x32x16_bf16 v[0:15], v[108:111], v[34:37], v[0:15]
	v_exp_f32_e32 v33, v33
	v_exp_f32_e32 v39, v38
	v_fma_f32 v38, v47, s44, -v32
	v_exp_f32_e32 v45, v38
	v_add_f32_e32 v38, v33, v48
	v_mfma_f32_32x32x16_bf16 v[16:31], v[104:107], v[34:37], v[16:31]
	v_add_f32_e32 v34, v39, v38
	v_cvt_pk_bf16_f32 v36, v179, v41
	v_cvt_pk_bf16_f32 v37, v42, v43
	v_cvt_pk_bf16_f32 v38, v44, v33
	v_cvt_pk_bf16_f32 v39, v39, v45
	v_add_f32_e32 v34, v45, v34
	v_mov_b32_e32 v35, v34
	v_mov_b32_e32 v247, v34
	s_nop 1
	v_permlane32_swap_b32_e32 v35, v247
	v_xor_b32_e32 v35, v35, v247
	v_xor_b32_e32 v35, v35, v34
	v_mfma_f32_32x32x16_bf16 v[0:15], v[100:103], v[36:39], v[0:15]
	s_waitcnt lgkmcnt(0)
	v_add_f32_e32 v34, v34, v35
	v_fmac_f32_e32 v34, v175, v40
	v_mfma_f32_32x32x16_bf16 v[16:31], v[96:99], v[36:39], v[16:31]
	s_cbranch_scc1 .LBB0_337
	v_mov_b32_e32 v175, v34
	v_mov_b32_e32 v176, v32
	s_branch .LBB0_346

; template <int DQK, bool MASKED, int MODE, class MF>
; DI void attn_step(const bf16_t* sK, const bf16_t* sVt, const bf16x8 (&qf)[DQK / 16], f32x16& o0, f32x16& o1, float& m, float& l,
;                   float sc, const MF& mf, int lane, f32x16 (&s)[2], float invl, bool lanevalid = true) {
;     ...
;   constexpr int KST = DQK + 8;
;   bf16x8 kf[2][DQK / 16];
; #pragma unroll
;   for (int sub = 0; sub < 2; ++sub)
; #pragma unroll
;     for (int ks = 0; ks < DQK / 16; ++ks) kf[sub][ks] = *(const bf16x8*)(sK + (sub * 32 + pr) * KST + ks * 16 + 8 * h);
;   __builtin_amdgcn_sched_barrier(0);
; #pragma unroll
;   for (int q = 0; q < 16; ++q) { s[0][q] = 0.f; s[1][q] = 0.f; }
; #pragma unroll
;   for (int ks = 0; ks < DQK / 16; ++ks) {
;     s[0] = MFMA(kf[0][ks], qf[ks], s[0]);
;     s[1] = MFMA(kf[1][ks], qf[ks], s[1]);
;   }
;   bf16x8 vf[2][2][2];
;   if (MODE != 1) {
; #pragma unroll
;     for (int sub = 0; sub < 2; ++sub)
; #pragma unroll
;       for (int s2 = 0; s2 < 2; ++s2) {
;         vf[sub][s2][0] = *(const bf16x8*)(sVt + r * 72 + sub * 32 + s2 * 16 + 8 * h);
;         vf[sub][s2][1] = *(const bf16x8*)(sVt + (32 + r) * 72 + sub * 32 + s2 * 16 + 8 * h);
;       }
;     __builtin_amdgcn_sched_barrier(0);
;   }
;   float mxr = -3.0e38f;
; #pragma unroll
;   for (int sub = 0; sub < 2; ++sub)
; #pragma unroll
;     for (int q = 0; q < 16; ++q) {
;       if (MASKED) { const int kk = sub * 32 + 16 * (q >> 3) + 8 * h + (q & 7); s[sub][q] = mf(kk) ? s[sub][q] : -3.0e38f; }
;       if (MODE != 2) mxr = fmaxf(mxr, s[sub][q]);
;     }
;   float alpha = 1.f;
;   if (MODE != 2) {
;     float mx = fmaxf(m, mxr * sc);
;     mx = fmaxf(mx, shx(mx, 32));
;     if (!MASKED) mx = lanevalid ? mx : m;
;     alpha = fexp2(m - mx);
;     m = mx;
;   }
;   const float moff = (!MASKED && !lanevalid) ? 1.0e30f : m;
;   float ps = 0.f;
; #pragma unroll
;   for (int sub = 0; sub < 2; ++sub)
; #pragma unroll
;     for (int q = 0; q < 16; ++q) {
; DI void phase_attn_mla(const Params& P, bf16_t* og, unsigned char* smem, int L, int G) {
;     ...
;       if (key0 <= t0 + 31) {
;         auto mf = [&](int kk) { return key0 + kk <= t; };
;         if (key0 + 63 > t0) attn_step<96, true, 0>(sK + cb * KVB96, sVt + cb * KVB96, qf, o0, o1, m, l, sc, mf, lane, s, 0.f);
;         else attn_step<96, false, 0>(sK + cb * KVB96, sVt + cb * KVB96, qf, o0, o1, m, l, sc, mf, lane, s, 0.f);
;       }
.LBB0_785:
	v_cmp_le_i32_e32 vcc, s14, v163
	s_and_saveexec_b64 s[22:23], vcc
	s_cbranch_execz .LBB0_791
	s_add_i32 s24, s14, 63
	s_mulk_i32 s40, 0x2c00
	v_cmp_le_i32_e32 vcc, s24, v162
	s_lshl_b32 s39, s40, 1
	v_max_f32_e32 v0, v186, v186
	s_and_saveexec_b64 s[24:25], vcc
	s_xor_b64 s[24:25], exec, s[24:25]
	s_cbranch_execz .LBB0_788
	v_lshl_add_u32 v14, s40, 1, v143
	ds_read_b128 v[2:5], v14
	ds_read_b128 v[6:9], v14 offset:32
	ds_read_b128 v[10:13], v14 offset:64
	ds_read_b128 v[116:119], v14 offset:96
	ds_read_b128 v[120:123], v14 offset:128
	ds_read_b128 v[124:127], v14 offset:160
	ds_read_b128 v[48:51], v14 offset:6656
	ds_read_b128 v[128:131], v14 offset:6688
	ds_read_b128 v[132:135], v14 offset:6720
	ds_read_b128 v[188:191], v14 offset:6752
	ds_read_b128 v[194:197], v14 offset:6784
	ds_read_b128 v[198:201], v14 offset:6816
	s_waitcnt lgkmcnt(11)
	v_mfma_f32_32x32x16_bf16 v[64:79], v[2:5], v[100:103], 0
	v_add3_u32 v2, s39, v172, v156
	v_add3_u32 v3, s39, v173, v156
	s_waitcnt lgkmcnt(10)
	v_mfma_f32_32x32x16_bf16 v[64:79], v[6:9], v[80:83], v[64:79]
	s_waitcnt lgkmcnt(5)
	v_mfma_f32_32x32x16_bf16 v[48:63], v[48:51], v[100:103], 0
	v_mfma_f32_32x32x16_bf16 v[64:79], v[10:13], v[84:87], v[64:79]
	s_waitcnt lgkmcnt(4)
	v_mfma_f32_32x32x16_bf16 v[48:63], v[128:131], v[80:83], v[48:63]
	v_mfma_f32_32x32x16_bf16 v[64:79], v[116:119], v[88:91], v[64:79]
	s_waitcnt lgkmcnt(3)
	v_mfma_f32_32x32x16_bf16 v[48:63], v[132:135], v[84:87], v[48:63]
	v_mfma_f32_32x32x16_bf16 v[64:79], v[120:123], v[92:95], v[64:79]
	s_waitcnt lgkmcnt(2)
	v_mfma_f32_32x32x16_bf16 v[48:63], v[188:191], v[88:91], v[48:63]
	v_mfma_f32_32x32x16_bf16 v[64:79], v[124:127], v[96:99], v[64:79]
	ds_read_b128 v[132:135], v2 offset:13312
	ds_read_b128 v[124:127], v2 offset:13344
	ds_read_b128 v[128:131], v3 offset:13312
	ds_read_b128 v[120:123], v3 offset:13344
	ds_read_b128 v[116:119], v2 offset:13376
	ds_read_b128 v[6:9], v2 offset:13408
	ds_read_b128 v[10:13], v3 offset:13376
	ds_read_b128 v[2:5], v3 offset:13408
	s_waitcnt lgkmcnt(9)
	v_mfma_f32_32x32x16_bf16 v[48:63], v[194:197], v[92:95], v[48:63]
	s_waitcnt lgkmcnt(8)
	v_mfma_f32_32x32x16_bf16 v[48:63], v[198:201], v[96:99], v[48:63]
	v_max3_f32 v14, v64, s36, v65
	v_max3_f32 v14, v14, v66, v67
	v_max3_f32 v14, v14, v68, v69
	v_max3_f32 v14, v14, v70, v71
	v_max3_f32 v14, v14, v72, v73
	v_max3_f32 v14, v14, v74, v75
	v_max3_f32 v14, v14, v76, v77
	v_max3_f32 v14, v14, v78, v79
	s_nop 3
	v_max3_f32 v14, v14, v48, v49
	v_max3_f32 v14, v14, v50, v51
	v_max3_f32 v14, v14, v52, v53
	v_max3_f32 v14, v14, v54, v55
	v_max3_f32 v14, v14, v56, v57
	v_max3_f32 v14, v14, v58, v59
	v_max3_f32 v14, v14, v60, v61
	v_max3_f32 v14, v14, v62, v63
	v_mul_f32_e32 v14, 0x3e16c740, v14
	v_cmp_lt_i32_e32 vcc, v183, v184
	v_max_f32_e32 v0, v0, v14
	s_nop 0
	v_cndmask_b32_e32 v14, v182, v183, vcc
	v_lshlrev_b32_e32 v14, 2, v14
	v_mov_b32_e32 v15, v0
	v_mov_b32_e32 v247, v0
	s_nop 1
	v_permlane32_swap_b32_e32 v15, v247
	v_xor_b32_e32 v15, v15, v247
	v_xor_b32_e32 v15, v15, v0
	v_max_f32_e32 v15, v15, v15
	v_max_f32_e32 v15, v0, v15
	v_fma_f32 v0, v64, s37, -v15
	v_fma_f32 v64, v65, s37, -v15
	v_exp_f32_e32 v65, v0
	v_exp_f32_e32 v64, v64
	v_fma_f32 v0, v66, s37, -v15
	v_exp_f32_e32 v66, v0
	v_fma_f32 v67, v67, s37, -v15
	v_exp_f32_e32 v67, v67
	v_fma_f32 v68, v68, s37, -v15
	v_sub_f32_e32 v0, v186, v15
	v_add_f32_e32 v186, 0, v65
	v_exp_f32_e32 v68, v68
	v_fma_f32 v69, v69, s37, -v15
	v_add_f32_e32 v186, v64, v186
	v_exp_f32_e32 v69, v69
	v_fma_f32 v70, v70, s37, -v15
	v_add_f32_e32 v186, v66, v186
	v_exp_f32_e32 v70, v70
	v_fma_f32 v71, v71, s37, -v15
	v_add_f32_e32 v186, v67, v186
	v_exp_f32_e32 v71, v71
	v_fma_f32 v72, v72, s37, -v15
	v_add_f32_e32 v186, v68, v186
	v_exp_f32_e32 v72, v72
	v_fma_f32 v73, v73, s37, -v15
	v_add_f32_e32 v186, v69, v186
	v_exp_f32_e32 v73, v73
	v_fma_f32 v74, v74, s37, -v15
	v_add_f32_e32 v186, v70, v186
	v_exp_f32_e32 v74, v74
	v_fma_f32 v75, v75, s37, -v15
	v_add_f32_e32 v186, v71, v186
	v_exp_f32_e32 v75, v75
	v_fma_f32 v76, v76, s37, -v15
	v_add_f32_e32 v186, v72, v186
	v_exp_f32_e32 v76, v76
	v_fma_f32 v77, v77, s37, -v15
	v_add_f32_e32 v186, v73, v186
	v_exp_f32_e32 v77, v77
	v_fma_f32 v78, v78, s37, -v15
	v_add_f32_e32 v186, v74, v186
	v_exp_f32_e32 v78, v78
	v_fma_f32 v79, v79, s37, -v15
	v_add_f32_e32 v186, v75, v186
	v_exp_f32_e32 v79, v79
	v_fma_f32 v48, v48, s37, -v15
	v_add_f32_e32 v186, v76, v186
	v_exp_f32_e32 v187, v48
	v_fma_f32 v48, v49, s37, -v15
	v_add_f32_e32 v186, v77, v186
	v_exp_f32_e32 v188, v48
	v_fma_f32 v48, v50, s37, -v15
	v_add_f32_e32 v186, v78, v186
	v_exp_f32_e32 v189, v48
	v_fma_f32 v49, v51, s37, -v15
	v_add_f32_e32 v48, v79, v186
	v_exp_f32_e32 v186, v49
	v_fma_f32 v49, v52, s37, -v15
	v_add_f32_e32 v48, v187, v48
	v_exp_f32_e32 v52, v49
	v_fma_f32 v49, v53, s37, -v15
	v_add_f32_e32 v48, v188, v48
	v_exp_f32_e32 v53, v49
	v_fma_f32 v49, v54, s37, -v15
	v_add_f32_e32 v48, v189, v48
	v_exp_f32_e32 v54, v49
	v_add_f32_e32 v48, v186, v48
	v_add_f32_e32 v48, v52, v48
	v_exp_f32_e32 v0, v0
	v_add_f32_e32 v48, v53, v48
	v_add_f32_e32 v190, v54, v48
	v_fma_f32 v48, v55, s37, -v15
	v_exp_f32_e32 v55, v48
	v_fma_f32 v48, v56, s37, -v15
	v_exp_f32_e32 v56, v48
	v_pk_mul_f32 v[46:47], v[46:47], v[0:1] op_sel_hi:[1,0]
	v_pk_mul_f32 v[44:45], v[44:45], v[0:1] op_sel_hi:[1,0]
	v_pk_mul_f32 v[42:43], v[42:43], v[0:1] op_sel_hi:[1,0]
	v_pk_mul_f32 v[40:41], v[40:41], v[0:1] op_sel_hi:[1,0]
	v_pk_mul_f32 v[38:39], v[38:39], v[0:1] op_sel_hi:[1,0]
	v_pk_mul_f32 v[36:37], v[36:37], v[0:1] op_sel_hi:[1,0]
	v_pk_mul_f32 v[34:35], v[34:35], v[0:1] op_sel_hi:[1,0]
	v_pk_mul_f32 v[32:33], v[32:33], v[0:1] op_sel_hi:[1,0]
	v_cvt_pk_bf16_f32 v48, v65, v64
	v_cvt_pk_bf16_f32 v49, v66, v67
	v_cvt_pk_bf16_f32 v50, v68, v69
	v_cvt_pk_bf16_f32 v51, v70, v71
	v_pk_mul_f32 v[30:31], v[30:31], v[0:1] op_sel_hi:[1,0]
	v_pk_mul_f32 v[28:29], v[28:29], v[0:1] op_sel_hi:[1,0]
	s_waitcnt lgkmcnt(0)
; #define MFMA(a, b, c) __builtin_amdgcn_mfma_f32_32x32x16_bf16((a), (b), (c), 0, 0, 0)
; DI unsigned pack2(float a, float b) { f32x2_t v = {a, b}; bf16x2_t r = __builtin_convertvector(v, bf16x2_t); return __builtin_bit_cast(unsigned, r); }
; DI float fexp2(float x) { return __builtin_amdgcn_exp2f(x); }
; DI float shx(float v, int m) { return __shfl_xor(v, m, 64); }
; template <int DQK, bool MASKED, int MODE, class MF>
; DI void attn_step(const bf16_t* sK, const bf16_t* sVt, const bf16x8 (&qf)[DQK / 16], f32x16& o0, f32x16& o1, float& m, float& l,
;                   float sc, const MF& mf, int lane, f32x16 (&s)[2], float invl, bool lanevalid = true) {
;     ...
;       if (MASKED) { const int kk = sub * 32 + 16 * (q >> 3) + 8 * h + (q & 7); s[sub][q] = mf(kk) ? s[sub][q] : -3.0e38f; }
;     ...
;   float ps = 0.f;
; #pragma unroll
;   for (int sub = 0; sub < 2; ++sub)
; #pragma unroll
;     for (int q = 0; q < 16; ++q) {
;       float pv = fexp2(__builtin_fmaf(s[sub][q], sc, -moff));
;       if (MASKED && MODE != 0) pv = (s[sub][q] > -1.0e38f) ? pv : 0.f;
;       if (MODE == 2) pv *= invl;
;       s[sub][q] = pv;
;       ps += pv;
;     }
;   if (MODE != 2) {
;     ps += shx(ps, 32);
;     l = l * alpha + ps;
;   }
;   if (MODE == 1) return;
;   if (MODE == 0) {
; #pragma unroll
;     for (int q = 0; q < 16; ++q) { o0[q] *= alpha; o1[q] *= alpha; }
;   }
; #pragma unroll
;   for (int sub = 0; sub < 2; ++sub)
; #pragma unroll
;     for (int s2 = 0; s2 < 2; ++s2) {
;       union { bf16x8 v; unsigned u[4]; } pb;
; #pragma unroll
;       for (int e = 0; e < 4; ++e) pb.u[e] = pack2(s[sub][8 * s2 + 2 * e], s[sub][8 * s2 + 2 * e + 1]);
;       o0 = MFMA(vf[sub][s2][0], pb.v, o0);
;       o1 = MFMA(vf[sub][s2][1], pb.v, o1);
;     }
	v_mfma_f32_32x32x16_bf16 v[32:47], v[132:135], v[48:51], v[32:47]
	v_mul_f32_e64 v26, v26, v0
	v_mul_f32_e64 v27, v27, v0
	v_mul_f32_e64 v24, v24, v0
	v_mul_f32_e64 v25, v25, v0
	v_mul_f32_e64 v22, v22, v0
	v_mul_f32_e64 v23, v23, v0
	v_pk_mul_f32 v[20:21], v[20:21], v[0:1] op_sel_hi:[1,0]
	v_pk_mul_f32 v[18:19], v[18:19], v[0:1] op_sel_hi:[1,0]
	v_pk_mul_f32 v[16:17], v[16:17], v[0:1] op_sel_hi:[1,0]
	v_fma_f32 v57, v57, s37, -v15
	v_exp_f32_e32 v57, v57
	v_mfma_f32_32x32x16_bf16 v[16:31], v[128:131], v[48:51], v[16:31]
	v_add_f32_e32 v48, v55, v190
	v_add_f32_e32 v64, v56, v48
	v_cvt_pk_bf16_f32 v48, v72, v73
	v_cvt_pk_bf16_f32 v49, v74, v75
	v_cvt_pk_bf16_f32 v50, v76, v77
	v_cvt_pk_bf16_f32 v51, v78, v79
	v_fma_f32 v58, v58, s37, -v15
	v_exp_f32_e32 v58, v58
	v_mfma_f32_32x32x16_bf16 v[32:47], v[124:127], v[48:51], v[32:47]
	v_fma_f32 v59, v59, s37, -v15
	v_exp_f32_e32 v59, v59
	v_add_f32_e32 v64, v57, v64
	v_add_f32_e32 v64, v58, v64
	v_add_f32_e32 v64, v59, v64
	v_mfma_f32_32x32x16_bf16 v[16:31], v[120:123], v[48:51], v[16:31]
	v_fma_f32 v48, v60, s37, -v15
	v_exp_f32_e32 v60, v48
	v_cvt_pk_bf16_f32 v48, v187, v188
	v_cvt_pk_bf16_f32 v49, v189, v186
	v_cvt_pk_bf16_f32 v50, v52, v53
	v_cvt_pk_bf16_f32 v51, v54, v55
	v_fma_f32 v53, v61, s37, -v15
	v_exp_f32_e32 v53, v53
	v_mfma_f32_32x32x16_bf16 v[32:47], v[116:119], v[48:51], v[32:47]
	v_fma_f32 v54, v62, s37, -v15
	v_exp_f32_e32 v54, v54
	v_fma_f32 v55, v63, s37, -v15
	v_exp_f32_e32 v55, v55
	v_add_f32_e32 v52, v60, v64
	v_mov_b32_e32 v186, v15
	v_mfma_f32_32x32x16_bf16 v[16:31], v[10:13], v[48:51], v[16:31]
	v_add_f32_e32 v10, v53, v52
	v_add_f32_e32 v10, v54, v10
	v_add_f32_e32 v48, v55, v10
	v_cvt_pk_bf16_f32 v10, v56, v57
	v_cvt_pk_bf16_f32 v11, v58, v59
	v_cvt_pk_bf16_f32 v12, v60, v53
	v_cvt_pk_bf16_f32 v13, v54, v55
	s_nop 1
	v_mfma_f32_32x32x16_bf16 v[32:47], v[6:9], v[10:13], v[32:47]
	v_mov_b32_e32 v6, v48
	v_mov_b32_e32 v247, v48
	s_nop 1
	v_permlane32_swap_b32_e32 v6, v247
	v_xor_b32_e32 v6, v6, v247
	v_xor_b32_e32 v6, v6, v48
	s_waitcnt lgkmcnt(0)
	v_add_f32_e32 v6, v48, v6
	v_fmac_f32_e32 v6, v165, v0
	v_mfma_f32_32x32x16_bf16 v[16:31], v[2:5], v[10:13], v[16:31]
	v_mov_b32_e32 v165, v6
.LBB0_788:
	s_andn2_saveexec_b64 s[24:25], s[24:25]
	s_cbranch_execz .LBB0_790
	v_lshl_add_u32 v14, s40, 1, v176
	ds_read_b128 v[2:5], v14
	ds_read_b128 v[6:9], v14 offset:32
	ds_read_b128 v[10:13], v14 offset:64
	ds_read_b128 v[116:119], v14 offset:96
	ds_read_b128 v[120:123], v14 offset:128
	ds_read_b128 v[124:127], v14 offset:160
	ds_read_b128 v[48:51], v14 offset:6656
	ds_read_b128 v[128:131], v14 offset:6688
	ds_read_b128 v[132:135], v14 offset:6720
	ds_read_b128 v[188:191], v14 offset:6752
	ds_read_b128 v[194:197], v14 offset:6784
	ds_read_b128 v[198:201], v14 offset:6816
	s_waitcnt lgkmcnt(11)
	v_mfma_f32_32x32x16_bf16 v[64:79], v[2:5], v[100:103], 0
	v_lshlrev_b32_e32 v2, 1, v175
	v_add3_u32 v3, s39, v172, v2
	v_add3_u32 v2, s39, v173, v2
	s_waitcnt lgkmcnt(10)
	v_mfma_f32_32x32x16_bf16 v[64:79], v[6:9], v[80:83], v[64:79]
	s_waitcnt lgkmcnt(5)
	v_mfma_f32_32x32x16_bf16 v[48:63], v[48:51], v[100:103], 0
	v_mfma_f32_32x32x16_bf16 v[64:79], v[10:13], v[84:87], v[64:79]
	s_waitcnt lgkmcnt(4)
	v_mfma_f32_32x32x16_bf16 v[48:63], v[128:131], v[80:83], v[48:63]
	v_mfma_f32_32x32x16_bf16 v[64:79], v[116:119], v[88:91], v[64:79]
	s_waitcnt lgkmcnt(3)
	v_mfma_f32_32x32x16_bf16 v[48:63], v[132:135], v[84:87], v[48:63]
	v_mfma_f32_32x32x16_bf16 v[64:79], v[120:123], v[92:95], v[64:79]
	s_waitcnt lgkmcnt(2)
	v_mfma_f32_32x32x16_bf16 v[48:63], v[188:191], v[88:91], v[48:63]
	v_mfma_f32_32x32x16_bf16 v[64:79], v[124:127], v[96:99], v[64:79]
	ds_read_b128 v[132:135], v3 offset:13312
	ds_read_b128 v[124:127], v3 offset:13344
	ds_read_b128 v[128:131], v2 offset:13312
	ds_read_b128 v[120:123], v2 offset:13344
	ds_read_b128 v[116:119], v3 offset:13376
	ds_read_b128 v[6:9], v3 offset:13408
	ds_read_b128 v[10:13], v2 offset:13376
	ds_read_b128 v[2:5], v2 offset:13408
	s_waitcnt lgkmcnt(9)
	v_mfma_f32_32x32x16_bf16 v[48:63], v[194:197], v[92:95], v[48:63]
	s_waitcnt lgkmcnt(8)
	v_mfma_f32_32x32x16_bf16 v[48:63], v[198:201], v[96:99], v[48:63]
	v_add_u32_e32 v14, s14, v175
	v_cmp_le_i32_e32 vcc, v14, v164
	s_nop 1
	v_cndmask_b32_e32 v15, v185, v64, vcc
	v_cmp_lt_i32_e32 vcc, v14, v164
	s_nop 1
	v_cndmask_b32_e32 v64, v185, v65, vcc
	v_add_u32_e32 v65, 2, v14
	v_cmp_le_i32_e32 vcc, v65, v164
	s_nop 1
	v_cndmask_b32_e32 v65, v185, v66, vcc
	v_add_u32_e32 v66, 3, v14
	v_cmp_le_i32_e32 vcc, v66, v164
	s_nop 1
	v_cndmask_b32_e32 v66, v185, v67, vcc
	v_add_u32_e32 v67, 4, v14
	v_cmp_le_i32_e32 vcc, v67, v164
	s_nop 1
	v_cndmask_b32_e32 v67, v185, v68, vcc
	v_add_u32_e32 v68, 5, v14
	v_cmp_le_i32_e32 vcc, v68, v164
	s_nop 1
	v_cndmask_b32_e32 v68, v185, v69, vcc
	v_add_u32_e32 v69, 6, v14
	v_cmp_le_i32_e32 vcc, v69, v164
	s_nop 1
	v_cndmask_b32_e32 v69, v185, v70, vcc
	v_add_u32_e32 v70, s14, v174
	v_or_b32_e32 v187, 7, v70
	v_cmp_le_i32_e32 vcc, v187, v164
	v_add_u32_e32 v187, 16, v14
	s_nop 0
	v_cndmask_b32_e32 v71, v185, v71, vcc
	v_cmp_le_i32_e32 vcc, v187, v164
	v_add_u32_e32 v187, 17, v14
	s_nop 0
	v_cndmask_b32_e32 v72, v185, v72, vcc
	v_cmp_le_i32_e32 vcc, v187, v164
	v_add_u32_e32 v187, 18, v14
	s_nop 0
	v_cndmask_b32_e32 v73, v185, v73, vcc
	v_cmp_le_i32_e32 vcc, v187, v164
	v_add_u32_e32 v187, 19, v14
	s_nop 0
	v_cndmask_b32_e32 v74, v185, v74, vcc
	v_cmp_le_i32_e32 vcc, v187, v164
	v_add_u32_e32 v187, 20, v14
	s_nop 0
	v_cndmask_b32_e32 v75, v185, v75, vcc
	v_cmp_le_i32_e32 vcc, v187, v164
	v_add_u32_e32 v187, 21, v14
	s_nop 0
	v_cndmask_b32_e32 v76, v185, v76, vcc
	v_cmp_le_i32_e32 vcc, v187, v164
; DI float fexp2(float x) { return __builtin_amdgcn_exp2f(x); }
; DI float shx(float v, int m) { return __shfl_xor(v, m, 64); }
; template <int DQK, bool MASKED, int MODE, class MF>
; DI void attn_step(const bf16_t* sK, const bf16_t* sVt, const bf16x8 (&qf)[DQK / 16], f32x16& o0, f32x16& o1, float& m, float& l,
;                   float sc, const MF& mf, int lane, f32x16 (&s)[2], float invl, bool lanevalid = true) {
;     ...
;   float mxr = -3.0e38f;
; #pragma unroll
;   for (int sub = 0; sub < 2; ++sub)
; #pragma unroll
;     for (int q = 0; q < 16; ++q) {
;       if (MASKED) { const int kk = sub * 32 + 16 * (q >> 3) + 8 * h + (q & 7); s[sub][q] = mf(kk) ? s[sub][q] : -3.0e38f; }
;       if (MODE != 2) mxr = fmaxf(mxr, s[sub][q]);
;     }
;   float alpha = 1.f;
;   if (MODE != 2) {
;     float mx = fmaxf(m, mxr * sc);
;     mx = fmaxf(mx, shx(mx, 32));
;     if (!MASKED) mx = lanevalid ? mx : m;
;     alpha = fexp2(m - mx);
;     m = mx;
;   }
;   const float moff = (!MASKED && !lanevalid) ? 1.0e30f : m;
;   float ps = 0.f;
; #pragma unroll
;   for (int sub = 0; sub < 2; ++sub)
; #pragma unroll
;     for (int q = 0; q < 16; ++q) {
;       float pv = fexp2(__builtin_fmaf(s[sub][q], sc, -moff));
;       if (MASKED && MODE != 0) pv = (s[sub][q] > -1.0e38f) ? pv : 0.f;
;       if (MODE == 2) pv *= invl;
;       s[sub][q] = pv;
;       ps += pv;
;     }
;   if (MODE != 2) {
;     ps += shx(ps, 32);
;     l = l * alpha + ps;
;   }
;   if (MODE == 1) return;
;   if (MODE == 0) {
; #pragma unroll
;     for (int q = 0; q < 16; ++q) { o0[q] *= alpha; o1[q] *= alpha; }
	v_add_u32_e32 v187, 22, v14
	s_nop 0
	v_cndmask_b32_e32 v77, v185, v77, vcc
	v_cmp_le_i32_e32 vcc, v187, v164
	v_or_b32_e32 v187, 23, v70
	s_nop 0
	v_cndmask_b32_e32 v78, v185, v78, vcc
	v_cmp_le_i32_e32 vcc, v187, v164
	v_add_u32_e32 v187, 32, v14
	s_nop 0
	v_cndmask_b32_e32 v79, v185, v79, vcc
	v_cmp_le_i32_e32 vcc, v187, v164
	v_add_u32_e32 v187, 33, v14
	s_nop 0
	v_cndmask_b32_e32 v48, v185, v48, vcc
	v_cmp_le_i32_e32 vcc, v187, v164
	v_add_u32_e32 v187, 34, v14
	s_nop 0
	v_cndmask_b32_e32 v49, v185, v49, vcc
	v_cmp_le_i32_e32 vcc, v187, v164
	v_add_u32_e32 v187, 35, v14
	s_nop 0
	v_cndmask_b32_e32 v50, v185, v50, vcc
	v_cmp_le_i32_e32 vcc, v187, v164
	v_add_u32_e32 v187, 36, v14
	s_nop 0
	v_cndmask_b32_e32 v51, v185, v51, vcc
	v_cmp_le_i32_e32 vcc, v187, v164
	v_add_u32_e32 v187, 37, v14
	s_nop 0
	v_cndmask_b32_e32 v52, v185, v52, vcc
	v_cmp_le_i32_e32 vcc, v187, v164
	v_add_u32_e32 v187, 38, v14
	s_nop 0
	v_cndmask_b32_e32 v53, v185, v53, vcc
	v_cmp_le_i32_e32 vcc, v187, v164
	v_or_b32_e32 v187, 39, v70
	s_nop 0
	v_cndmask_b32_e32 v54, v185, v54, vcc
	v_cmp_le_i32_e32 vcc, v187, v164
	v_add_u32_e32 v187, 48, v14
	s_nop 0
	v_cndmask_b32_e32 v55, v185, v55, vcc
	v_cmp_le_i32_e32 vcc, v187, v164
	v_add_u32_e32 v187, 49, v14
	s_nop 0
	v_cndmask_b32_e32 v56, v185, v56, vcc
	v_cmp_le_i32_e32 vcc, v187, v164
	v_add_u32_e32 v187, 50, v14
	s_nop 0
	v_cndmask_b32_e32 v57, v185, v57, vcc
	v_cmp_le_i32_e32 vcc, v187, v164
	v_add_u32_e32 v187, 51, v14
	s_nop 0
	v_cndmask_b32_e32 v58, v185, v58, vcc
	v_cmp_le_i32_e32 vcc, v187, v164
	v_add_u32_e32 v187, 52, v14
	s_nop 0
	v_cndmask_b32_e32 v59, v185, v59, vcc
	v_cmp_le_i32_e32 vcc, v187, v164
	v_add_u32_e32 v187, 53, v14
	v_add_u32_e32 v14, 54, v14
	v_cndmask_b32_e32 v60, v185, v60, vcc
	v_cmp_le_i32_e32 vcc, v187, v164
	s_nop 1
	v_cndmask_b32_e32 v61, v185, v61, vcc
	v_cmp_le_i32_e32 vcc, v14, v164
	s_nop 1
	v_cndmask_b32_e32 v14, v185, v62, vcc
	v_or_b32_e32 v62, 55, v70
	v_cmp_le_i32_e32 vcc, v62, v164
	s_nop 1
	v_cndmask_b32_e32 v62, v185, v63, vcc
	v_max3_f32 v63, v15, s36, v64
	v_max3_f32 v63, v63, v65, v66
	v_max3_f32 v63, v63, v67, v68
	v_max3_f32 v63, v63, v69, v71
	v_max3_f32 v63, v63, v72, v73
	v_max3_f32 v63, v63, v74, v75
	v_max3_f32 v63, v63, v76, v77
	v_max3_f32 v63, v63, v78, v79
	v_max3_f32 v63, v63, v48, v49
	v_max3_f32 v63, v63, v50, v51
	v_max3_f32 v63, v63, v52, v53
	v_max3_f32 v63, v63, v54, v55
	v_max3_f32 v63, v63, v56, v57
	v_max3_f32 v63, v63, v58, v59
	v_max3_f32 v63, v63, v60, v61
	v_max3_f32 v63, v63, v14, v62
	v_mul_f32_e32 v63, 0x3e16c740, v63
	v_cmp_lt_i32_e32 vcc, v183, v184
	v_max_f32_e32 v0, v0, v63
	s_nop 0
	v_cndmask_b32_e32 v63, v182, v183, vcc
	v_lshlrev_b32_e32 v63, 2, v63
	v_mov_b32_e32 v70, v0
	v_mov_b32_e32 v247, v0
	s_nop 1
	v_permlane32_swap_b32_e32 v70, v247
	v_xor_b32_e32 v70, v70, v247
	v_xor_b32_e32 v70, v70, v0
	v_max_f32_e32 v70, v70, v70
	v_max_f32_e32 v70, v0, v70
	v_fma_f32 v0, v15, s37, -v70
	v_exp_f32_e32 v15, v0
	v_fma_f32 v0, v64, s37, -v70
	v_exp_f32_e32 v64, v0
	v_fma_f32 v0, v65, s37, -v70
	v_exp_f32_e32 v65, v0
	v_fma_f32 v66, v66, s37, -v70
	v_exp_f32_e32 v66, v66
	v_fma_f32 v67, v67, s37, -v70
	v_sub_f32_e32 v0, v186, v70
	v_add_f32_e32 v186, 0, v15
	v_exp_f32_e32 v67, v67
	v_fma_f32 v68, v68, s37, -v70
	v_add_f32_e32 v186, v64, v186
	v_exp_f32_e32 v68, v68
	v_fma_f32 v69, v69, s37, -v70
	v_add_f32_e32 v186, v65, v186
	v_exp_f32_e32 v69, v69
	v_fma_f32 v71, v71, s37, -v70
	v_add_f32_e32 v186, v66, v186
	v_exp_f32_e32 v71, v71
	v_fma_f32 v72, v72, s37, -v70
	v_add_f32_e32 v186, v67, v186
	v_exp_f32_e32 v72, v72
	v_fma_f32 v73, v73, s37, -v70
	v_add_f32_e32 v186, v68, v186
	v_exp_f32_e32 v73, v73
	v_fma_f32 v74, v74, s37, -v70
	v_add_f32_e32 v186, v69, v186
	v_exp_f32_e32 v74, v74
	v_fma_f32 v75, v75, s37, -v70
	v_add_f32_e32 v186, v71, v186
	v_exp_f32_e32 v75, v75
	v_fma_f32 v76, v76, s37, -v70
	v_add_f32_e32 v186, v72, v186
	v_exp_f32_e32 v76, v76
	v_fma_f32 v77, v77, s37, -v70
	v_add_f32_e32 v186, v73, v186
	v_exp_f32_e32 v77, v77
	v_fma_f32 v78, v78, s37, -v70
	v_add_f32_e32 v186, v74, v186
	v_exp_f32_e32 v78, v78
	v_fma_f32 v79, v79, s37, -v70
	v_add_f32_e32 v186, v75, v186
	v_exp_f32_e32 v79, v79
	v_fma_f32 v48, v48, s37, -v70
	v_add_f32_e32 v186, v76, v186
	v_exp_f32_e32 v187, v48
	v_fma_f32 v48, v49, s37, -v70
	v_add_f32_e32 v186, v77, v186
	v_exp_f32_e32 v188, v48
	v_fma_f32 v48, v50, s37, -v70
	v_add_f32_e32 v186, v78, v186
	v_exp_f32_e32 v189, v48
	v_fma_f32 v49, v51, s37, -v70
	v_add_f32_e32 v48, v79, v186
	v_exp_f32_e32 v186, v49
	v_fma_f32 v49, v52, s37, -v70
	v_add_f32_e32 v48, v187, v48
	v_exp_f32_e32 v52, v49
	v_fma_f32 v49, v53, s37, -v70
	v_add_f32_e32 v48, v188, v48
	v_exp_f32_e32 v53, v49
	v_fma_f32 v49, v54, s37, -v70
	v_add_f32_e32 v48, v189, v48
	v_exp_f32_e32 v54, v49
	v_add_f32_e32 v48, v186, v48
	v_add_f32_e32 v48, v52, v48
	v_exp_f32_e32 v0, v0
	v_add_f32_e32 v48, v53, v48
	v_add_f32_e32 v190, v54, v48
	v_fma_f32 v48, v55, s37, -v70
	v_exp_f32_e32 v55, v48
	v_fma_f32 v48, v56, s37, -v70
	v_exp_f32_e32 v56, v48
	v_pk_mul_f32 v[46:47], v[46:47], v[0:1] op_sel_hi:[1,0]
	v_pk_mul_f32 v[44:45], v[44:45], v[0:1] op_sel_hi:[1,0]
	v_pk_mul_f32 v[42:43], v[42:43], v[0:1] op_sel_hi:[1,0]
	v_pk_mul_f32 v[40:41], v[40:41], v[0:1] op_sel_hi:[1,0]
	v_pk_mul_f32 v[38:39], v[38:39], v[0:1] op_sel_hi:[1,0]
	v_pk_mul_f32 v[36:37], v[36:37], v[0:1] op_sel_hi:[1,0]
	v_pk_mul_f32 v[34:35], v[34:35], v[0:1] op_sel_hi:[1,0]
	v_pk_mul_f32 v[32:33], v[32:33], v[0:1] op_sel_hi:[1,0]
	v_pk_mul_f32 v[30:31], v[30:31], v[0:1] op_sel_hi:[1,0]
	v_cvt_pk_bf16_f32 v48, v15, v64
	v_cvt_pk_bf16_f32 v49, v65, v66
	v_cvt_pk_bf16_f32 v50, v67, v68
	v_cvt_pk_bf16_f32 v51, v69, v71
	v_pk_mul_f32 v[28:29], v[28:29], v[0:1] op_sel_hi:[1,0]
	v_pk_mul_f32 v[26:27], v[26:27], v[0:1] op_sel_hi:[1,0]
	v_pk_mul_f32 v[24:25], v[24:25], v[0:1] op_sel_hi:[1,0]
	v_pk_mul_f32 v[22:23], v[22:23], v[0:1] op_sel_hi:[1,0]
	v_pk_mul_f32 v[20:21], v[20:21], v[0:1] op_sel_hi:[1,0]
	v_pk_mul_f32 v[18:19], v[18:19], v[0:1] op_sel_hi:[1,0]
	v_pk_mul_f32 v[16:17], v[16:17], v[0:1] op_sel_hi:[1,0]
	s_waitcnt lgkmcnt(0)
; #define MFMA(a, b, c) __builtin_amdgcn_mfma_f32_32x32x16_bf16((a), (b), (c), 0, 0, 0)
; DI unsigned pack2(float a, float b) { f32x2_t v = {a, b}; bf16x2_t r = __builtin_convertvector(v, bf16x2_t); return __builtin_bit_cast(unsigned, r); }
; DI float fexp2(float x) { return __builtin_amdgcn_exp2f(x); }
; DI float shx(float v, int m) { return __shfl_xor(v, m, 64); }
; template <int DQK, bool MASKED, int MODE, class MF>
; DI void attn_step(const bf16_t* sK, const bf16_t* sVt, const bf16x8 (&qf)[DQK / 16], f32x16& o0, f32x16& o1, float& m, float& l,
;                   float sc, const MF& mf, int lane, f32x16 (&s)[2], float invl, bool lanevalid = true) {
;     ...
;   float ps = 0.f;
; #pragma unroll
;   for (int sub = 0; sub < 2; ++sub)
; #pragma unroll
;     for (int q = 0; q < 16; ++q) {
;       float pv = fexp2(__builtin_fmaf(s[sub][q], sc, -moff));
;       if (MASKED && MODE != 0) pv = (s[sub][q] > -1.0e38f) ? pv : 0.f;
;       if (MODE == 2) pv *= invl;
;       s[sub][q] = pv;
;       ps += pv;
;     }
;   if (MODE != 2) {
;     ps += shx(ps, 32);
;     l = l * alpha + ps;
;   }
;   if (MODE == 1) return;
;   if (MODE == 0) {
; #pragma unroll
;     for (int q = 0; q < 16; ++q) { o0[q] *= alpha; o1[q] *= alpha; }
;   }
; #pragma unroll
;   for (int sub = 0; sub < 2; ++sub)
; #pragma unroll
;     for (int s2 = 0; s2 < 2; ++s2) {
;       union { bf16x8 v; unsigned u[4]; } pb;
; #pragma unroll
;       for (int e = 0; e < 4; ++e) pb.u[e] = pack2(s[sub][8 * s2 + 2 * e], s[sub][8 * s2 + 2 * e + 1]);
;       o0 = MFMA(vf[sub][s2][0], pb.v, o0);
;       o1 = MFMA(vf[sub][s2][1], pb.v, o1);
;     }
	v_mfma_f32_32x32x16_bf16 v[32:47], v[132:135], v[48:51], v[32:47]
	v_fma_f32 v57, v57, s37, -v70
	v_exp_f32_e32 v57, v57
	v_fma_f32 v58, v58, s37, -v70
	v_exp_f32_e32 v58, v58
	v_fma_f32 v59, v59, s37, -v70
	v_add_f32_e32 v15, v55, v190
	v_exp_f32_e32 v59, v59
	v_mfma_f32_32x32x16_bf16 v[16:31], v[128:131], v[48:51], v[16:31]
	v_cvt_pk_bf16_f32 v48, v72, v73
	v_cvt_pk_bf16_f32 v49, v74, v75
	v_cvt_pk_bf16_f32 v50, v76, v77
	v_cvt_pk_bf16_f32 v51, v78, v79
	v_add_f32_e32 v15, v56, v15
	v_add_f32_e32 v15, v57, v15
	v_fma_f32 v14, v14, s37, -v70
	v_mfma_f32_32x32x16_bf16 v[32:47], v[124:127], v[48:51], v[32:47]
	v_add_f32_e32 v15, v58, v15
	v_exp_f32_e32 v14, v14
	v_add_f32_e32 v15, v59, v15
	v_mfma_f32_32x32x16_bf16 v[16:31], v[120:123], v[48:51], v[16:31]
	v_fma_f32 v48, v60, s37, -v70
	v_exp_f32_e32 v60, v48
	v_cvt_pk_bf16_f32 v48, v187, v188
	v_cvt_pk_bf16_f32 v49, v189, v186
	v_cvt_pk_bf16_f32 v50, v52, v53
	v_cvt_pk_bf16_f32 v51, v54, v55
	v_fma_f32 v52, v61, s37, -v70
	v_exp_f32_e32 v52, v52
	v_mfma_f32_32x32x16_bf16 v[32:47], v[116:119], v[48:51], v[32:47]
	v_fma_f32 v53, v62, s37, -v70
	v_exp_f32_e32 v53, v53
	v_add_f32_e32 v15, v60, v15
	v_mov_b32_e32 v186, v70
	v_mfma_f32_32x32x16_bf16 v[16:31], v[10:13], v[48:51], v[16:31]
	v_add_f32_e32 v10, v52, v15
	v_add_f32_e32 v10, v14, v10
	v_add_f32_e32 v15, v53, v10
	v_cvt_pk_bf16_f32 v10, v56, v57
	v_cvt_pk_bf16_f32 v11, v58, v59
	v_cvt_pk_bf16_f32 v12, v60, v52
	v_cvt_pk_bf16_f32 v13, v14, v53
	s_nop 1
	v_mfma_f32_32x32x16_bf16 v[32:47], v[6:9], v[10:13], v[32:47]
	v_mov_b32_e32 v6, v15
	v_mov_b32_e32 v247, v15
	s_nop 1
	v_permlane32_swap_b32_e32 v6, v247
	v_xor_b32_e32 v6, v6, v247
	v_xor_b32_e32 v6, v6, v15
	s_waitcnt lgkmcnt(0)
	v_add_f32_e32 v6, v15, v6
	v_fmac_f32_e32 v6, v165, v0
	v_mfma_f32_32x32x16_bf16 v[16:31], v[2:5], v[10:13], v[16:31]
	v_mov_b32_e32 v165, v6

; DI float bf2f(bf16_t b) { return __uint_as_float(((unsigned)b) << 16); }
; DI float sigmoidf_(float x) { return __builtin_amdgcn_rcpf(1.f + __expf(-x)); }
; DI void phase_attn_nsa(const Params& P, bf16_t* og, unsigned char* smem, int L, int G) {
;     ...
;     int tid = threadIdx.x;
;     asm volatile("" : "+v"(tid));
;     tid &= 255;
;     const int lane = tid & 63, w = tid >> 6, r = lane & 31, h = lane >> 5;
;     int qt, bg; gqa_item(it, L, G, gi, qt, bg);
;     const int b = bg >> 2, g = bg & 3;
;     const int t0 = qt * 32, t = t0 + r, head = g * 4 + w;
;     const size_t tok = (size_t)b * SEQ + t;
;     bf16x8 qf[4];
; #pragma unroll
;     for (int ks = 0; ks < 4; ++ks) qf[ks] = *(const bf16x8*)(big + NS_Q + tok * 1024 + head * 64 + ks * 16 + 8 * h);
;     const bf16_t* glp = big + NS_GL + tok * 64;
;     const float g0 = sigmoidf_(bf2f(glp[head])), g1 = sigmoidf_(bf2f(glp[16 + head])), g2 = sigmoidf_(bf2f(glp[32 + head]));
;     f32x16 o0, o1, s[2];
;     {
;       const bf16_t* kb = big + NS_KC2 + (size_t)((b * 4 + g) * 128) * 64;
;       const bf16_t* vb = big + NS_VCT + (size_t)((b * 4 + g) * 64) * 128;
;       float m = NEGF, l = 0.f;
;       KVR R; kv64_fetch(R, kb, 64, vb, 128, 0, false, tid);
; #pragma unroll
;       for (int tile = 0; tile < 2; ++tile) {
;         const int key0 = tile * 64;
;         kv64_commit(R, sK, sVt, false, tid);
;         if (tile == 0) kv64_fetch(R, kb, 64, vb, 128, 64, false, tid); else kv64_fetch(R, kb, 64, vb, 128, 0, true, tid);
;         __builtin_amdgcn_sched_barrier(0);
;         auto mf = [&](int kk) { return (key0 + kk) * 16 + 31 <= t; };
;         attn_step<64, true, 1>(sK, sVt, qf, o0, o1, m, l, sc, mf, lane, s, 0.f);
.LBB0_1278:
	v_ashrrev_i32_e32 v114, 2, v2
	v_and_b32_e32 v118, 31, v120
	s_lshl_b32 s46, s44, 5
	v_ashrrev_i32_e32 v115, 31, v114
	v_or_b32_e32 v136, s46, v118
	v_lshlrev_b64 v[134:135], 11, v[114:115]
	v_mov_b32_e32 v137, v1
	v_bfe_u32 v168, v120, 6, 2
	v_and_b32_e32 v119, 3, v2
	v_lshl_add_u64 v[4:5], v[134:135], 0, v[136:137]
	v_lshl_or_b32 v121, v119, 2, v168
	v_lshlrev_b64 v[6:7], 11, v[4:5]
	v_readlane_b32 s0, v246, 38
	v_lshl_add_u64 v[6:7], s[76:77], 0, v[6:7]
	v_lshlrev_b32_e32 v0, 7, v121
	v_lshlrev_b64 v[4:5], 7, v[4:5]
	v_readlane_b32 s1, v246, 39
	v_lshl_add_u64 v[12:13], v[6:7], 0, v[0:1]
	v_lshlrev_b32_e32 v0, 1, v121
	v_lshl_add_u64 v[4:5], s[0:1], 0, v[4:5]
	v_lshl_add_u64 v[14:15], v[4:5], 0, v[0:1]
	v_lshlrev_b32_e32 v4, 7, v2
	v_ashrrev_i32_e32 v5, 31, v4
	v_readlane_b32 s0, v246, 40
	v_lshlrev_b32_e32 v0, 3, v120
	v_lshlrev_b64 v[4:5], 7, v[4:5]
	v_readlane_b32 s1, v246, 41
	v_bfe_u32 v169, v120, 3, 5
	v_and_b32_e32 v0, 56, v0
	v_lshl_add_u64 v[8:9], s[0:1], 0, v[4:5]
	v_or_b32_e32 v174, 32, v169
	v_lshlrev_b32_e32 v140, 1, v0
	v_lshlrev_b32_e32 v0, 7, v169
	v_mov_b32_e32 v141, v1
	v_lshl_add_u64 v[4:5], v[8:9], 0, v[0:1]
	v_lshlrev_b32_e32 v0, 7, v174
	v_lshl_add_u64 v[46:47], v[4:5], 0, v[140:141]
	v_lshl_add_u64 v[8:9], v[8:9], 0, v[0:1]
	global_load_dwordx4 v[4:7], v[46:47], off
	v_lshl_add_u64 v[42:43], v[8:9], 0, v[140:141]
	global_load_dwordx4 v[8:11], v[42:43], off
	v_lshrrev_b32_e32 v0, 2, v120
	v_and_b32_e32 v56, 8, v0
	v_mov_b32_e32 v139, v1
	v_lshlrev_b32_e32 v138, 1, v56
	v_lshl_add_u64 v[12:13], v[12:13], 0, v[138:139]
	global_load_dwordx4 v[74:77], v[12:13], off
	global_load_dwordx4 v[78:81], v[12:13], off offset:32
	global_load_dwordx4 v[82:85], v[12:13], off offset:64
	global_load_dwordx4 v[86:89], v[12:13], off offset:96
	global_load_ushort v124, v[14:15], off
	global_load_ushort v123, v[14:15], off offset:32
	global_load_ushort v122, v[14:15], off offset:64
	s_movk_i32 s0, 0x3000
	v_mul_u32_u24_e32 v0, 0x48, v169
	v_lshlrev_b32_e32 v0, 1, v0
	v_add_co_u32_e32 v50, vcc, s0, v46
	v_add3_u32 v170, v153, v0, v140
	s_nop 0
	v_addc_co_u32_e32 v51, vcc, 0, v47, vcc
	s_barrier
	v_lshlrev_b32_e32 v116, 6, v2
	v_ashrrev_i32_e32 v117, 31, v116
	v_readlane_b32 s0, v246, 42
	v_lshlrev_b64 v[2:3], 8, v[116:117]
	v_readlane_b32 s1, v246, 43
	v_and_b32_e32 v0, 19, v120
	v_bfe_u32 v139, v120, 2, 4
	v_cmp_lt_i32_e32 vcc, v164, v165
	v_lshl_add_u64 v[52:53], s[0:1], 0, v[2:3]
	v_and_b32_e32 v171, 8, v139
	v_lshl_add_u64 v[2:3], v[52:53], 0, v[140:141]
	v_lshl_add_u32 v57, v171, 1, v153
	s_movk_i32 s47, 0x90
	v_and_b32_e32 v137, 63, v120
	v_lshlrev_b32_e32 v54, 8, v174
	v_mov_b32_e32 v55, v1
	v_writelane_b32 v245, s2, 25
	v_lshl_add_u64 v[48:49], v[2:3], 0, v[54:55]
	s_waitcnt vmcnt(8)
	ds_write_b128 v170, v[4:7]
	s_waitcnt vmcnt(7)
	ds_write_b128 v170, v[8:11] offset:4608
	s_waitcnt lgkmcnt(0)
	s_barrier
	global_load_dwordx4 v[34:37], v[50:51], off
	global_load_dwordx4 v[38:41], v[50:51], off offset:-4096
	v_lshrrev_b32_e32 v4, 1, v120
	v_lshlrev_b32_e32 v5, 1, v120
	v_and_b32_e32 v4, 4, v4
	v_and_b32_e32 v5, 8, v5
	v_or3_b32 v125, v4, v0, v5
	v_cndmask_b32_e32 v0, v163, v164, vcc
	v_lshlrev_b32_e32 v173, 2, v0
	v_lshlrev_b32_e32 v0, 8, v169
	v_mad_u32_u24 v172, v125, s47, v57
	v_lshl_add_u64 v[44:45], v[2:3], 0, v[0:1]
	ds_read_b128 v[2:5], v172
	ds_read_b128 v[18:21], v172 offset:32
	ds_read_b128 v[22:25], v172 offset:64
	ds_read_b128 v[26:29], v172 offset:96
	ds_read_b128 v[30:33], v172 offset:4608
	ds_read_b128 v[62:65], v172 offset:4640
	ds_read_b128 v[66:69], v172 offset:4672
	ds_read_b128 v[70:73], v172 offset:4704
	s_waitcnt vmcnt(8) lgkmcnt(7)
	v_mfma_f32_32x32x16_bf16 v[2:17], v[2:5], v[74:77], 0
	v_lshlrev_b32_e32 v59, 4, v171
	v_lshlrev_b32_e32 v60, 4, v139
	v_or_b32_e32 v58, 0x11f, v59
	s_waitcnt lgkmcnt(0)
	s_barrier
	s_waitcnt vmcnt(0)
	ds_write_b128 v170, v[38:41]
	ds_write_b128 v170, v[34:37] offset:4608
	v_mfma_f32_32x32x16_bf16 v[2:17], v[18:21], v[78:81], v[2:17]
	v_or_b32_e32 v18, 31, v59
	v_cmp_gt_u32_e64 s[0:1], v18, v136
	v_or_b32_e32 v19, 47, v59
	v_or_b32_e32 v20, 63, v59
	v_writelane_b32 v245, s0, 26
	v_or_b32_e32 v21, 0x4f, v59
	s_waitcnt lgkmcnt(0)
	v_mfma_f32_32x32x16_bf16 v[2:17], v[22:25], v[82:85], v[2:17]
	v_writelane_b32 v245, s1, 27
	v_or_b32_e32 v22, 0x5f, v59
	v_or_b32_e32 v23, 0x6f, v59
	v_or_b32_e32 v24, 0x7f, v60
	v_or_b32_e32 v25, 0x70, v60
	v_add_u32_e32 v25, 31, v25
	s_barrier
; DI float fexp2(float x) { return __builtin_amdgcn_exp2f(x); }
; DI float shx(float v, int m) { return __shfl_xor(v, m, 64); }
; template <int DQK, bool MASKED, int MODE, class MF>
; DI void attn_step(const bf16_t* sK, const bf16_t* sVt, const bf16x8 (&qf)[DQK / 16], f32x16& o0, f32x16& o1, float& m, float& l,
;                   float sc, const MF& mf, int lane, f32x16 (&s)[2], float invl, bool lanevalid = true) {
;     ...
;   float mxr = -3.0e38f;
; #pragma unroll
;   for (int sub = 0; sub < 2; ++sub)
; #pragma unroll
;     for (int q = 0; q < 16; ++q) {
;       if (MASKED) { const int kk = sub * 32 + 16 * (q >> 3) + 8 * h + (q & 7); s[sub][q] = mf(kk) ? s[sub][q] : -3.0e38f; }
;       if (MODE != 2) mxr = fmaxf(mxr, s[sub][q]);
;     }
;   float alpha = 1.f;
;   if (MODE != 2) {
;     float mx = fmaxf(m, mxr * sc);
;     mx = fmaxf(mx, shx(mx, 32));
;     if (!MASKED) mx = lanevalid ? mx : m;
;     alpha = fexp2(m - mx);
;     m = mx;
;   }
;   const float moff = (!MASKED && !lanevalid) ? 1.0e30f : m;
; DI void phase_attn_nsa(const Params& P, bf16_t* og, unsigned char* smem, int L, int G) {
;     ...
;       for (int tile = 0; tile < 2; ++tile) {
;         const int key0 = tile * 64;
;         kv64_commit(R, sK, sVt, false, tid);
;         if (tile == 0) kv64_fetch(R, kb, 64, vb, 128, 64, false, tid); else kv64_fetch(R, kb, 64, vb, 128, 0, true, tid);
;         __builtin_amdgcn_sched_barrier(0);
;         auto mf = [&](int kk) { return (key0 + kk) * 16 + 31 <= t; };
;         attn_step<64, true, 1>(sK, sVt, qf, o0, o1, m, l, sc, mf, lane, s, 0.f);
	v_mfma_f32_32x32x16_bf16 v[2:17], v[26:29], v[86:89], v[2:17]
	global_load_dwordx4 v[34:37], v[48:49], off
	global_load_dwordx4 v[38:41], v[44:45], off
	s_nop 0
	global_load_dwordx4 v[42:45], v[42:43], off
	s_nop 0
	global_load_dwordx4 v[46:49], v[46:47], off
	s_nop 5
	v_cndmask_b32_e64 v2, v2, v166, s[0:1]
	v_cmp_gt_u32_e64 s[0:1], v19, v136
	v_cmp_lt_f32_e32 vcc, s48, v2
	s_nop 0
	v_writelane_b32 v245, s0, 28
	s_nop 1
	v_writelane_b32 v245, s1, 29
	v_cndmask_b32_e64 v3, v3, v166, s[0:1]
	v_cmp_gt_u32_e64 s[0:1], v20, v136
	s_nop 1
	v_writelane_b32 v245, s0, 30
	s_nop 1
	v_writelane_b32 v245, s1, 31
	v_cndmask_b32_e64 v4, v4, v166, s[0:1]
	v_cmp_gt_u32_e64 s[0:1], v21, v136
	s_nop 1
	v_writelane_b32 v245, s0, 32
	s_nop 1
	v_writelane_b32 v245, s1, 33
	v_cndmask_b32_e64 v5, v5, v166, s[0:1]
	v_cmp_gt_u32_e64 s[0:1], v22, v136
	s_nop 1
	v_writelane_b32 v245, s0, 34
	s_nop 1
	v_writelane_b32 v245, s1, 35
	v_cndmask_b32_e64 v6, v6, v166, s[0:1]
	v_cmp_gt_u32_e64 s[0:1], v23, v136
	s_nop 1
	v_writelane_b32 v245, s0, 36
	s_nop 1
	v_writelane_b32 v245, s1, 37
	v_cndmask_b32_e64 v7, v7, v166, s[0:1]
	v_cmp_gt_u32_e64 s[0:1], v24, v136
	s_nop 1
	v_writelane_b32 v245, s0, 38
	s_nop 1
	v_writelane_b32 v245, s1, 39
	v_cndmask_b32_e64 v8, v8, v166, s[0:1]
	v_cmp_gt_u32_e64 s[0:1], v25, v136
	v_mfma_f32_32x32x16_bf16 v[18:33], v[30:33], v[74:77], 0
	s_nop 0
	v_writelane_b32 v245, s0, 40
	s_nop 1
	v_writelane_b32 v245, s1, 41
	v_cndmask_b32_e64 v9, v9, v166, s[0:1]
	v_cmp_gt_u32_e64 s[0:1], v58, v136
	v_or_b32_e32 v58, 0x12f, v59
	v_mfma_f32_32x32x16_bf16 v[18:33], v[62:65], v[78:81], v[18:33]
	v_writelane_b32 v245, s0, 42
	s_nop 1
	v_writelane_b32 v245, s1, 43
	v_cndmask_b32_e64 v10, v10, v166, s[0:1]
	v_cmp_gt_u32_e64 s[0:1], v58, v136
	v_or_b32_e32 v58, 0x13f, v59
	v_mfma_f32_32x32x16_bf16 v[18:33], v[66:69], v[82:85], v[18:33]
	v_writelane_b32 v245, s0, 44
	s_nop 1
	v_writelane_b32 v245, s1, 45
	v_cndmask_b32_e64 v11, v11, v166, s[0:1]
	v_cmp_gt_u32_e64 s[0:1], v58, v136
	v_or_b32_e32 v58, 0x14f, v59
	v_mfma_f32_32x32x16_bf16 v[18:33], v[70:73], v[86:89], v[18:33]
	v_writelane_b32 v245, s0, 46
	s_nop 1
	v_writelane_b32 v245, s1, 47
	v_cndmask_b32_e64 v12, v12, v166, s[0:1]
	v_cmp_gt_u32_e64 s[0:1], v58, v136
	v_or_b32_e32 v58, 0x15f, v59
	s_nop 0
	v_writelane_b32 v245, s0, 48
	s_nop 1
	v_writelane_b32 v245, s1, 49
	v_cndmask_b32_e64 v13, v13, v166, s[0:1]
	v_cmp_gt_u32_e64 s[0:1], v58, v136
	v_or_b32_e32 v58, 0x16f, v59
	s_nop 0
	v_writelane_b32 v245, s0, 50
	s_nop 1
	v_writelane_b32 v245, s1, 51
	v_cndmask_b32_e64 v14, v14, v166, s[0:1]
	v_cmp_gt_u32_e64 s[0:1], v58, v136
	v_or_b32_e32 v58, 0x17f, v60
	v_cmp_gt_u32_e64 s[52:53], v58, v136
	v_or_b32_e32 v58, 0x170, v60
	v_add_u32_e32 v58, 31, v58
	v_cmp_gt_u32_e64 s[58:59], v58, v136
	v_or_b32_e32 v58, 0x21f, v59
	v_cmp_gt_u32_e64 s[62:63], v58, v136
	v_or_b32_e32 v58, 0x22f, v59
	v_cmp_gt_u32_e64 s[64:65], v58, v136
	v_or_b32_e32 v58, 0x23f, v59
	v_cmp_gt_u32_e64 s[66:67], v58, v136
	v_or_b32_e32 v58, 0x24f, v59
	v_cmp_gt_u32_e64 s[68:69], v58, v136
	v_or_b32_e32 v58, 0x25f, v59
	v_cmp_gt_u32_e64 s[70:71], v58, v136
	v_or_b32_e32 v58, 0x26f, v59
	v_cmp_gt_u32_e64 s[74:75], v58, v136
	v_or_b32_e32 v58, 0x27f, v60
	v_cmp_gt_u32_e64 s[76:77], v58, v136
	v_or_b32_e32 v58, 0x270, v60
	v_add_u32_e32 v58, 31, v58
	v_cmp_gt_u32_e64 s[82:83], v58, v136
	v_or_b32_e32 v58, 0x31f, v59
	v_cmp_gt_u32_e64 s[84:85], v58, v136
	v_or_b32_e32 v58, 0x32f, v59
	v_cmp_gt_u32_e64 s[86:87], v58, v136
	v_or_b32_e32 v58, 0x33f, v59
	v_cmp_gt_u32_e64 s[90:91], v58, v136
	v_or_b32_e32 v58, 0x34f, v59
	v_cmp_gt_u32_e64 s[94:95], v58, v136
	v_or_b32_e32 v58, 0x35f, v59
	v_cmp_gt_u32_e64 s[96:97], v58, v136
	v_or_b32_e32 v58, 0x36f, v59
	v_cmp_gt_u32_e64 s[40:41], v58, v136
	v_or_b32_e32 v58, 0x37f, v60
	v_cmp_gt_u32_e64 s[36:37], v58, v136
	v_or_b32_e32 v58, 0x370, v60
	v_add_u32_e32 v58, 31, v58
	v_cmp_gt_u32_e64 s[34:35], v58, v136
	v_max3_f32 v58, v2, s8, v3
	v_max3_f32 v58, v58, v4, v5
	v_max3_f32 v58, v58, v6, v7
	v_max3_f32 v58, v58, v8, v9
	v_max3_f32 v58, v58, v10, v11
	v_writelane_b32 v245, s0, 52
	v_max3_f32 v58, v58, v12, v13
	v_cndmask_b32_e64 v16, v16, v166, s[52:53]
	v_cndmask_b32_e64 v15, v15, v166, s[0:1]
	v_cndmask_b32_e64 v17, v17, v166, s[58:59]
	v_max3_f32 v58, v58, v14, v15
	v_cndmask_b32_e64 v18, v18, v166, s[62:63]
	v_cndmask_b32_e64 v19, v19, v166, s[64:65]
	v_max3_f32 v58, v58, v16, v17
	v_cndmask_b32_e64 v20, v20, v166, s[66:67]
	v_cndmask_b32_e64 v21, v21, v166, s[68:69]
	v_max3_f32 v58, v58, v18, v19
	v_cndmask_b32_e64 v22, v22, v166, s[70:71]
	v_cndmask_b32_e64 v23, v23, v166, s[74:75]
	v_max3_f32 v58, v58, v20, v21
	v_cndmask_b32_e64 v24, v24, v166, s[76:77]
	v_cndmask_b32_e64 v25, v25, v166, s[82:83]
	v_max3_f32 v58, v58, v22, v23
	v_cndmask_b32_e64 v26, v26, v166, s[84:85]
	v_cndmask_b32_e64 v27, v27, v166, s[86:87]
	v_max3_f32 v58, v58, v24, v25
	v_cndmask_b32_e64 v28, v28, v166, s[90:91]
	v_cndmask_b32_e64 v29, v29, v166, s[94:95]
	v_max3_f32 v58, v58, v26, v27
	v_cndmask_b32_e64 v30, v30, v166, s[96:97]
	v_cndmask_b32_e64 v31, v31, v166, s[40:41]
	v_max3_f32 v58, v58, v28, v29
	v_cndmask_b32_e64 v32, v32, v166, s[36:37]
	v_cndmask_b32_e64 v33, v33, v166, s[34:35]
	v_max3_f32 v58, v58, v30, v31
	v_max3_f32 v58, v58, v32, v33
	v_mul_f32_e32 v58, 0x3e38aa3b, v58
	v_max_f32_e32 v58, 0xf149f2ca, v58
	v_mov_b32_e32 v61, v58
	v_mov_b32_e32 v247, v58
	s_nop 1
	v_permlane32_swap_b32_e32 v61, v247
	v_xor_b32_e32 v61, v61, v247
	v_xor_b32_e32 v61, v61, v58
	v_writelane_b32 v245, s1, 53
	s_waitcnt lgkmcnt(0)
; DI float fexp2(float x) { return __builtin_amdgcn_exp2f(x); }
; DI float shx(float v, int m) { return __shfl_xor(v, m, 64); }
; template <int DQK, bool MASKED, int MODE, class MF>
; DI void attn_step(const bf16_t* sK, const bf16_t* sVt, const bf16x8 (&qf)[DQK / 16], f32x16& o0, f32x16& o1, float& m, float& l,
;                   float sc, const MF& mf, int lane, f32x16 (&s)[2], float invl, bool lanevalid = true) {
;     ...
;   float ps = 0.f;
; #pragma unroll
;   for (int sub = 0; sub < 2; ++sub)
; #pragma unroll
;     for (int q = 0; q < 16; ++q) {
;       float pv = fexp2(__builtin_fmaf(s[sub][q], sc, -moff));
;       if (MASKED && MODE != 0) pv = (s[sub][q] > -1.0e38f) ? pv : 0.f;
;       if (MODE == 2) pv *= invl;
;       s[sub][q] = pv;
;       ps += pv;
;     }
;   if (MODE != 2) {
;     ps += shx(ps, 32);
;     l = l * alpha + ps;
;   }
; DI void phase_attn_nsa(const Params& P, bf16_t* og, unsigned char* smem, int L, int G) {
;     ...
;       for (int tile = 0; tile < 2; ++tile) {
;         const int key0 = tile * 64;
;         kv64_commit(R, sK, sVt, false, tid);
;         if (tile == 0) kv64_fetch(R, kb, 64, vb, 128, 64, false, tid); else kv64_fetch(R, kb, 64, vb, 128, 0, true, tid);
;         __builtin_amdgcn_sched_barrier(0);
;         auto mf = [&](int kk) { return (key0 + kk) * 16 + 31 <= t; };
;         attn_step<64, true, 1>(sK, sVt, qf, o0, o1, m, l, sc, mf, lane, s, 0.f);
	v_max_f32_e32 v61, v61, v61
	v_max_f32_e32 v58, v58, v61
	v_fma_f32 v61, v2, s33, -v58
	v_exp_f32_e32 v61, v61
	v_fma_f32 v62, v4, s33, -v58
	v_exp_f32_e32 v62, v62
	v_add_f32_e32 v61, 0, v61
	v_cndmask_b32_e32 v2, 0, v61, vcc
	v_fma_f32 v61, v3, s33, -v58
	v_exp_f32_e32 v61, v61
	v_cmp_lt_f32_e32 vcc, s48, v3
	s_nop 1
	v_cndmask_b32_e32 v3, 0, v61, vcc
	v_cmp_lt_f32_e32 vcc, s48, v4
	v_add_f32_e32 v2, v3, v2
	v_fma_f32 v4, v6, s33, -v58
	v_cndmask_b32_e32 v3, 0, v62, vcc
	v_add_f32_e32 v2, v3, v2
	v_fma_f32 v3, v5, s33, -v58
	v_exp_f32_e32 v3, v3
	v_exp_f32_e32 v4, v4
	v_cmp_lt_f32_e32 vcc, s48, v5
	s_nop 1
	v_cndmask_b32_e32 v3, 0, v3, vcc
	v_cmp_lt_f32_e32 vcc, s48, v6
	v_add_f32_e32 v2, v3, v2
	s_nop 0
	v_cndmask_b32_e32 v3, 0, v4, vcc
	v_add_f32_e32 v2, v3, v2
	v_fma_f32 v3, v7, s33, -v58
	v_exp_f32_e32 v3, v3
	v_fma_f32 v4, v8, s33, -v58
	v_exp_f32_e32 v4, v4
	v_cmp_lt_f32_e32 vcc, s48, v7
	s_nop 1
	v_cndmask_b32_e32 v3, 0, v3, vcc
	v_cmp_lt_f32_e32 vcc, s48, v8
	v_add_f32_e32 v2, v3, v2
	s_nop 0
	v_cndmask_b32_e32 v3, 0, v4, vcc
	v_add_f32_e32 v2, v3, v2
	v_fma_f32 v3, v9, s33, -v58
	v_exp_f32_e32 v3, v3
	v_fma_f32 v4, v10, s33, -v58
	v_exp_f32_e32 v4, v4
	v_cmp_lt_f32_e32 vcc, s48, v9
	s_nop 1
	v_cndmask_b32_e32 v3, 0, v3, vcc
	v_cmp_lt_f32_e32 vcc, s48, v10
	v_add_f32_e32 v2, v3, v2
	s_nop 0
	v_cndmask_b32_e32 v3, 0, v4, vcc
	v_add_f32_e32 v2, v3, v2
	v_fma_f32 v3, v11, s33, -v58
	v_exp_f32_e32 v3, v3
	v_fma_f32 v4, v12, s33, -v58
	v_exp_f32_e32 v4, v4
	v_cmp_lt_f32_e32 vcc, s48, v11
	s_nop 1
	v_cndmask_b32_e32 v3, 0, v3, vcc
	v_cmp_lt_f32_e32 vcc, s48, v12
	v_add_f32_e32 v2, v3, v2
	s_nop 0
	v_cndmask_b32_e32 v3, 0, v4, vcc
	v_add_f32_e32 v2, v3, v2
	v_fma_f32 v3, v13, s33, -v58
	v_exp_f32_e32 v3, v3
	v_fma_f32 v4, v14, s33, -v58
	v_exp_f32_e32 v4, v4
	v_cmp_lt_f32_e32 vcc, s48, v13
	s_nop 1
	v_cndmask_b32_e32 v3, 0, v3, vcc
	v_cmp_lt_f32_e32 vcc, s48, v14
	v_add_f32_e32 v2, v3, v2
	s_nop 0
	v_cndmask_b32_e32 v3, 0, v4, vcc
	v_add_f32_e32 v2, v3, v2
	v_fma_f32 v3, v15, s33, -v58
	v_exp_f32_e32 v3, v3
	v_fma_f32 v4, v16, s33, -v58
	v_exp_f32_e32 v4, v4
	v_cmp_lt_f32_e32 vcc, s48, v15
	s_nop 1
	v_cndmask_b32_e32 v3, 0, v3, vcc
	v_cmp_lt_f32_e32 vcc, s48, v16
	v_add_f32_e32 v2, v3, v2
	s_nop 0
	v_cndmask_b32_e32 v3, 0, v4, vcc
	v_add_f32_e32 v2, v3, v2
	v_fma_f32 v3, v17, s33, -v58
	v_exp_f32_e32 v3, v3
	v_fma_f32 v4, v18, s33, -v58
	v_exp_f32_e32 v4, v4
	v_cmp_lt_f32_e32 vcc, s48, v17
	s_nop 1
	v_cndmask_b32_e32 v3, 0, v3, vcc
	v_cmp_lt_f32_e32 vcc, s48, v18
	v_add_f32_e32 v2, v3, v2
	s_nop 0
	v_cndmask_b32_e32 v3, 0, v4, vcc
	v_add_f32_e32 v2, v3, v2
	v_fma_f32 v3, v19, s33, -v58
	v_exp_f32_e32 v3, v3
	v_cmp_lt_f32_e32 vcc, s48, v19
	v_fma_f32 v4, v21, s33, -v58
	v_exp_f32_e32 v4, v4
	v_cndmask_b32_e32 v3, 0, v3, vcc
	v_add_f32_e32 v2, v3, v2
	v_fma_f32 v3, v20, s33, -v58
	v_exp_f32_e32 v3, v3
	v_cmp_lt_f32_e32 vcc, s48, v20
	s_nop 1
	v_cndmask_b32_e32 v3, 0, v3, vcc
	v_cmp_lt_f32_e32 vcc, s48, v21
	v_add_f32_e32 v2, v3, v2
	s_nop 0
	v_cndmask_b32_e32 v3, 0, v4, vcc
	v_add_f32_e32 v2, v3, v2
	v_fma_f32 v3, v22, s33, -v58
	v_exp_f32_e32 v3, v3
	v_fma_f32 v4, v23, s33, -v58
	v_exp_f32_e32 v4, v4
	v_cmp_lt_f32_e32 vcc, s48, v22
	s_nop 1
	v_cndmask_b32_e32 v3, 0, v3, vcc
	v_cmp_lt_f32_e32 vcc, s48, v23
	v_add_f32_e32 v2, v3, v2
	s_nop 0
	v_cndmask_b32_e32 v3, 0, v4, vcc
	v_add_f32_e32 v2, v3, v2
	v_fma_f32 v3, v24, s33, -v58
	v_exp_f32_e32 v3, v3
	v_fma_f32 v4, v25, s33, -v58
	v_exp_f32_e32 v4, v4
	v_cmp_lt_f32_e32 vcc, s48, v24
	s_nop 1
	v_cndmask_b32_e32 v3, 0, v3, vcc
	v_cmp_lt_f32_e32 vcc, s48, v25
	v_add_f32_e32 v2, v3, v2
	s_nop 0
	v_cndmask_b32_e32 v3, 0, v4, vcc
	v_add_f32_e32 v2, v3, v2
	v_fma_f32 v3, v26, s33, -v58
	v_exp_f32_e32 v3, v3
	v_fma_f32 v4, v27, s33, -v58
	v_exp_f32_e32 v4, v4
	v_cmp_lt_f32_e32 vcc, s48, v26
	s_nop 1
	v_cndmask_b32_e32 v3, 0, v3, vcc
	v_cmp_lt_f32_e32 vcc, s48, v27
	v_add_f32_e32 v2, v3, v2
	s_nop 0
	v_cndmask_b32_e32 v3, 0, v4, vcc
	v_add_f32_e32 v2, v3, v2
	v_fma_f32 v3, v28, s33, -v58
	v_exp_f32_e32 v3, v3
	v_fma_f32 v4, v29, s33, -v58
	v_exp_f32_e32 v4, v4
	v_cmp_lt_f32_e32 vcc, s48, v28
	s_nop 1
	v_cndmask_b32_e32 v3, 0, v3, vcc
	v_cmp_lt_f32_e32 vcc, s48, v29
	v_add_f32_e32 v2, v3, v2
	s_nop 0
	v_cndmask_b32_e32 v3, 0, v4, vcc
	v_add_f32_e32 v2, v3, v2
	v_fma_f32 v3, v30, s33, -v58
	v_exp_f32_e32 v3, v3
	v_fma_f32 v4, v31, s33, -v58
	v_exp_f32_e32 v4, v4
	v_cmp_lt_f32_e32 vcc, s48, v30
	s_nop 1
	v_cndmask_b32_e32 v3, 0, v3, vcc
	v_cmp_lt_f32_e32 vcc, s48, v31
	v_add_f32_e32 v2, v3, v2
	s_nop 0
	v_cndmask_b32_e32 v3, 0, v4, vcc
	v_add_f32_e32 v2, v3, v2
	v_fma_f32 v3, v32, s33, -v58
	v_exp_f32_e32 v3, v3
	v_fma_f32 v4, v33, s33, -v58
	v_exp_f32_e32 v4, v4
	v_cmp_lt_f32_e32 vcc, s48, v32
	s_nop 1
	v_cndmask_b32_e32 v3, 0, v3, vcc
	v_cmp_lt_f32_e32 vcc, s48, v33
	v_add_f32_e32 v2, v3, v2
	s_nop 0
	v_cndmask_b32_e32 v3, 0, v4, vcc
	v_add_f32_e32 v2, v3, v2
	v_mov_b32_e32 v3, v2
	v_mov_b32_e32 v247, v2
	s_nop 1
	v_permlane32_swap_b32_e32 v3, v247
	v_xor_b32_e32 v3, v3, v247
	v_xor_b32_e32 v3, v3, v2
	v_sub_f32_e32 v4, 0xf149f2ca, v58
	v_exp_f32_e32 v4, v4
	s_waitcnt lgkmcnt(0)
	v_add_f32_e32 v61, v2, v3
	v_fmac_f32_e32 v61, 0, v4
	ds_read_b128 v[2:5], v172
	ds_read_b128 v[18:21], v172 offset:32
	ds_read_b128 v[22:25], v172 offset:64
	ds_read_b128 v[26:29], v172 offset:96
	ds_read_b128 v[30:33], v172 offset:4608
	ds_read_b128 v[62:65], v172 offset:4640
	ds_read_b128 v[66:69], v172 offset:4672
	ds_read_b128 v[70:73], v172 offset:4704
	s_waitcnt lgkmcnt(7)
	v_mfma_f32_32x32x16_bf16 v[2:17], v[2:5], v[74:77], 0
	v_or_b32_e32 v90, 0x51f, v59
	v_cmp_gt_u32_e64 s[60:61], v90, v136
	v_or_b32_e32 v90, 0x53f, v59
	v_or_b32_e32 v91, 0x52f, v59
	v_cmp_gt_u32_e64 s[78:79], v90, v136
	v_or_b32_e32 v90, 0x54f, v59
	v_cmp_gt_u32_e64 s[72:73], v91, v136
	s_waitcnt lgkmcnt(6)
	v_mfma_f32_32x32x16_bf16 v[2:17], v[18:21], v[78:81], v[2:17]
	v_or_b32_e32 v18, 0x41f, v59
	v_cmp_gt_u32_e64 s[0:1], v18, v136
	v_or_b32_e32 v19, 0x42f, v59
	v_or_b32_e32 v20, 0x43f, v59
	v_writelane_b32 v245, s0, 54
	v_or_b32_e32 v21, 0x44f, v59
	v_cmp_gt_u32_e64 s[80:81], v90, v136
	s_waitcnt lgkmcnt(5)
	v_mfma_f32_32x32x16_bf16 v[2:17], v[22:25], v[82:85], v[2:17]
	v_writelane_b32 v245, s1, 55
	v_or_b32_e32 v22, 0x45f, v59
	v_or_b32_e32 v25, 0x470, v60
	v_or_b32_e32 v23, 0x46f, v59
	v_or_b32_e32 v24, 0x47f, v60
	v_add_u32_e32 v25, 31, v25
	v_cmp_gt_u32_e64 s[54:55], v24, v136
	s_waitcnt lgkmcnt(4)
	v_mfma_f32_32x32x16_bf16 v[2:17], v[26:29], v[86:89], v[2:17]
	v_cmp_gt_u32_e64 s[56:57], v25, v136
	s_waitcnt lgkmcnt(0)
	s_barrier
; DI float fexp2(float x) { return __builtin_amdgcn_exp2f(x); }
; DI float shx(float v, int m) { return __shfl_xor(v, m, 64); }
; template <int DQK, bool MASKED, int MODE, class MF>
; DI void attn_step(const bf16_t* sK, const bf16_t* sVt, const bf16x8 (&qf)[DQK / 16], f32x16& o0, f32x16& o1, float& m, float& l,
;                   float sc, const MF& mf, int lane, f32x16 (&s)[2], float invl, bool lanevalid = true) {
;     ...
;   float mxr = -3.0e38f;
; #pragma unroll
;   for (int sub = 0; sub < 2; ++sub)
; #pragma unroll
;     for (int q = 0; q < 16; ++q) {
;       if (MASKED) { const int kk = sub * 32 + 16 * (q >> 3) + 8 * h + (q & 7); s[sub][q] = mf(kk) ? s[sub][q] : -3.0e38f; }
;       if (MODE != 2) mxr = fmaxf(mxr, s[sub][q]);
;     }
;   float alpha = 1.f;
;   if (MODE != 2) {
;     float mx = fmaxf(m, mxr * sc);
;     mx = fmaxf(mx, shx(mx, 32));
;     if (!MASKED) mx = lanevalid ? mx : m;
;     alpha = fexp2(m - mx);
;     m = mx;
;   }
;   const float moff = (!MASKED && !lanevalid) ? 1.0e30f : m;
; DI void phase_attn_nsa(const Params& P, bf16_t* og, unsigned char* smem, int L, int G) {
;     ...
;       for (int tile = 0; tile < 2; ++tile) {
;         const int key0 = tile * 64;
;         kv64_commit(R, sK, sVt, true, tid);
	s_waitcnt vmcnt(0)
	ds_write_b128 v170, v[46:49]
	ds_write_b128 v170, v[42:45] offset:4608
	ds_write_b128 v170, v[38:41] offset:9216
	ds_write_b128 v170, v[34:37] offset:13824
	s_waitcnt lgkmcnt(0)
	s_barrier
	s_nop 1
	v_cndmask_b32_e64 v2, v2, v166, s[0:1]
	v_cmp_gt_u32_e64 s[0:1], v19, v136
	v_cndmask_b32_e64 v8, v8, v166, s[54:55]
	v_cndmask_b32_e64 v9, v9, v166, s[56:57]
	v_writelane_b32 v245, s0, 56
	v_cndmask_b32_e64 v10, v10, v166, s[60:61]
	v_cndmask_b32_e64 v11, v11, v166, s[72:73]
	v_writelane_b32 v245, s1, 57
	v_cndmask_b32_e64 v3, v3, v166, s[0:1]
	v_cmp_gt_u32_e64 s[0:1], v20, v136
	v_cndmask_b32_e64 v12, v12, v166, s[78:79]
	v_cndmask_b32_e64 v13, v13, v166, s[80:81]
	v_writelane_b32 v245, s0, 58
	v_cmp_lt_f32_e32 vcc, s48, v2
	s_nop 0
	v_writelane_b32 v245, s1, 59
	v_cndmask_b32_e64 v4, v4, v166, s[0:1]
	v_cmp_gt_u32_e64 s[0:1], v21, v136
	v_or_b32_e32 v126, 32, v137
	v_mad_u32_u24 v98, v118, s47, v57
	v_writelane_b32 v245, s0, 60
	v_mad_u32_u24 v129, v126, s47, v57
	s_nop 0
	v_writelane_b32 v245, s1, 61
	v_cndmask_b32_e64 v5, v5, v166, s[0:1]
	v_cmp_gt_u32_e64 s[0:1], v22, v136
	s_nop 1
	v_writelane_b32 v245, s0, 62
	s_nop 1
	v_writelane_b32 v245, s1, 63
	v_cndmask_b32_e64 v6, v6, v166, s[0:1]
	v_cmp_gt_u32_e64 s[0:1], v23, v136
	v_mfma_f32_32x32x16_bf16 v[18:33], v[30:33], v[74:77], 0
	s_nop 0
	v_writelane_b32 v244, s0, 0
	s_nop 1
	v_writelane_b32 v244, s1, 1
	v_cndmask_b32_e64 v7, v7, v166, s[0:1]
	v_mfma_f32_32x32x16_bf16 v[18:33], v[62:65], v[78:81], v[18:33]
	v_or_b32_e32 v62, 0x55f, v59
	v_cmp_gt_u32_e64 s[88:89], v62, v136
	v_or_b32_e32 v62, 0x56f, v59
	v_cmp_gt_u32_e64 s[92:93], v62, v136
	v_or_b32_e32 v62, 0x57f, v60
	v_cmp_gt_u32_e64 s[42:43], v62, v136
	v_or_b32_e32 v62, 0x570, v60
	v_add_u32_e32 v62, 31, v62
	v_cmp_gt_u32_e64 s[38:39], v62, v136
	v_or_b32_e32 v62, 0x61f, v59
	v_cmp_gt_u32_e64 s[30:31], v62, v136
	v_or_b32_e32 v62, 0x62f, v59
	v_cmp_gt_u32_e64 s[28:29], v62, v136
	v_or_b32_e32 v62, 0x63f, v59
	v_cmp_gt_u32_e64 s[26:27], v62, v136
	v_or_b32_e32 v62, 0x64f, v59
	v_cmp_gt_u32_e64 s[16:17], v62, v136
	v_or_b32_e32 v62, 0x65f, v59
	v_cmp_gt_u32_e64 s[18:19], v62, v136
	v_or_b32_e32 v62, 0x66f, v59
	v_cmp_gt_u32_e64 s[20:21], v62, v136
	v_or_b32_e32 v62, 0x67f, v60
	v_cmp_gt_u32_e64 s[22:23], v62, v136
	v_or_b32_e32 v62, 0x670, v60
	v_mfma_f32_32x32x16_bf16 v[18:33], v[66:69], v[82:85], v[18:33]
	v_add_u32_e32 v62, 31, v62
	v_cmp_gt_u32_e64 s[24:25], v62, v136
	v_or_b32_e32 v62, 0x71f, v59
	v_cmp_gt_u32_e64 s[14:15], v62, v136
	v_or_b32_e32 v62, 0x72f, v59
	v_cmp_gt_u32_e64 s[12:13], v62, v136
	v_or_b32_e32 v62, 0x73f, v59
	v_cmp_gt_u32_e64 s[10:11], v62, v136
	v_or_b32_e32 v62, 0x74f, v59
	v_cmp_gt_u32_e64 s[8:9], v62, v136
	v_or_b32_e32 v62, 0x75f, v59
	v_or_b32_e32 v59, 0x76f, v59
	v_cmp_gt_u32_e64 s[4:5], v59, v136
	v_or_b32_e32 v59, 0x77f, v60
	v_cmp_gt_u32_e64 s[2:3], v59, v136
	v_or_b32_e32 v59, 0x770, v60
	v_mfma_f32_32x32x16_bf16 v[18:33], v[70:73], v[86:89], v[18:33]
	v_add_u32_e32 v59, 31, v59
	v_cmp_gt_u32_e64 s[0:1], v59, v136
	v_max3_f32 v59, v2, s49, v3
	v_max3_f32 v59, v59, v4, v5
	v_max3_f32 v59, v59, v6, v7
	v_max3_f32 v59, v59, v8, v9
	v_max3_f32 v59, v59, v10, v11
	v_cndmask_b32_e64 v14, v14, v166, s[88:89]
	v_cndmask_b32_e64 v15, v15, v166, s[92:93]
	v_max3_f32 v59, v59, v12, v13
	v_cndmask_b32_e64 v16, v16, v166, s[42:43]
	v_cndmask_b32_e64 v17, v17, v166, s[38:39]
	v_max3_f32 v59, v59, v14, v15
	v_cndmask_b32_e64 v18, v18, v166, s[30:31]
	v_cndmask_b32_e64 v19, v19, v166, s[28:29]
	v_max3_f32 v59, v59, v16, v17
	v_cndmask_b32_e64 v20, v20, v166, s[26:27]
	v_cndmask_b32_e64 v21, v21, v166, s[16:17]
	v_max3_f32 v59, v59, v18, v19
	v_cndmask_b32_e64 v22, v22, v166, s[18:19]
	v_cndmask_b32_e64 v23, v23, v166, s[20:21]
	v_max3_f32 v59, v59, v20, v21
	v_cndmask_b32_e64 v24, v24, v166, s[22:23]
	v_cndmask_b32_e64 v25, v25, v166, s[24:25]
	v_max3_f32 v59, v59, v22, v23
	v_cndmask_b32_e64 v26, v26, v166, s[14:15]
	v_cndmask_b32_e64 v27, v27, v166, s[12:13]
	v_max3_f32 v59, v59, v24, v25
	v_cndmask_b32_e64 v28, v28, v166, s[10:11]
	v_cndmask_b32_e64 v29, v29, v166, s[8:9]
	v_cmp_gt_u32_e64 s[6:7], v62, v136
	v_max3_f32 v59, v59, v26, v27
	v_cndmask_b32_e64 v31, v31, v166, s[4:5]
	v_cndmask_b32_e64 v30, v30, v166, s[6:7]
	v_max3_f32 v59, v59, v28, v29
	v_cndmask_b32_e64 v32, v32, v166, s[2:3]
	v_cndmask_b32_e64 v33, v33, v166, s[0:1]
	v_max3_f32 v59, v59, v30, v31
	v_max3_f32 v59, v59, v32, v33
	v_mul_f32_e32 v59, 0x3e38aa3b, v59
	v_max_f32_e32 v59, v58, v59
	v_mov_b32_e32 v60, v59
	v_mov_b32_e32 v247, v59
	s_nop 1
	v_permlane32_swap_b32_e32 v60, v247
	v_xor_b32_e32 v60, v60, v247
	v_xor_b32_e32 v60, v60, v59
	s_waitcnt lgkmcnt(0)
; DI float fexp2(float x) { return __builtin_amdgcn_exp2f(x); }
; DI float shx(float v, int m) { return __shfl_xor(v, m, 64); }
; template <int DQK, bool MASKED, int MODE, class MF>
; DI void attn_step(const bf16_t* sK, const bf16_t* sVt, const bf16x8 (&qf)[DQK / 16], f32x16& o0, f32x16& o1, float& m, float& l,
;                   float sc, const MF& mf, int lane, f32x16 (&s)[2], float invl, bool lanevalid = true) {
;     ...
;   float ps = 0.f;
; #pragma unroll
;   for (int sub = 0; sub < 2; ++sub)
; #pragma unroll
;     for (int q = 0; q < 16; ++q) {
;       float pv = fexp2(__builtin_fmaf(s[sub][q], sc, -moff));
;       if (MASKED && MODE != 0) pv = (s[sub][q] > -1.0e38f) ? pv : 0.f;
;       if (MODE == 2) pv *= invl;
;       s[sub][q] = pv;
;       ps += pv;
;     }
;   if (MODE != 2) {
;     ps += shx(ps, 32);
;     l = l * alpha + ps;
;   }
	v_max_f32_e32 v60, v60, v60
	v_max_f32_e32 v127, v59, v60
	v_fma_f32 v59, v2, s33, -v127
	v_exp_f32_e32 v59, v59
	v_fma_f32 v60, v3, s33, -v127
	v_exp_f32_e32 v60, v60
	v_add_f32_e32 v59, 0, v59
	v_cndmask_b32_e32 v2, 0, v59, vcc
	v_cmp_lt_f32_e32 vcc, s48, v3
	v_fma_f32 v59, v5, s33, -v127
	v_exp_f32_e32 v59, v59
	v_cndmask_b32_e32 v3, 0, v60, vcc
	v_add_f32_e32 v2, v3, v2
	v_fma_f32 v3, v4, s33, -v127
	v_exp_f32_e32 v3, v3
	v_cmp_lt_f32_e32 vcc, s48, v4
	v_fma_f32 v4, v7, s33, -v127
	v_exp_f32_e32 v4, v4
	v_cndmask_b32_e32 v3, 0, v3, vcc
	v_cmp_lt_f32_e32 vcc, s48, v5
	v_add_f32_e32 v2, v3, v2
	s_nop 0
	v_cndmask_b32_e32 v3, 0, v59, vcc
	v_add_f32_e32 v2, v3, v2
	v_fma_f32 v3, v6, s33, -v127
	v_exp_f32_e32 v3, v3
	v_cmp_lt_f32_e32 vcc, s48, v6
	s_nop 1
	v_cndmask_b32_e32 v3, 0, v3, vcc
	v_cmp_lt_f32_e32 vcc, s48, v7
	v_add_f32_e32 v2, v3, v2
	s_nop 0
	v_cndmask_b32_e32 v3, 0, v4, vcc
	v_add_f32_e32 v2, v3, v2
	v_fma_f32 v3, v8, s33, -v127
	v_exp_f32_e32 v3, v3
	v_fma_f32 v4, v9, s33, -v127
	v_exp_f32_e32 v4, v4
	v_cmp_lt_f32_e32 vcc, s48, v8
	s_nop 1
	v_cndmask_b32_e32 v3, 0, v3, vcc
	v_cmp_lt_f32_e32 vcc, s48, v9
	v_add_f32_e32 v2, v3, v2
	s_nop 0
	v_cndmask_b32_e32 v3, 0, v4, vcc
	v_add_f32_e32 v2, v3, v2
	v_fma_f32 v3, v10, s33, -v127
	v_exp_f32_e32 v3, v3
	v_fma_f32 v4, v11, s33, -v127
	v_exp_f32_e32 v4, v4
	v_cmp_lt_f32_e32 vcc, s48, v10
	s_nop 1
	v_cndmask_b32_e32 v3, 0, v3, vcc
	v_cmp_lt_f32_e32 vcc, s48, v11
	v_add_f32_e32 v2, v3, v2
	s_nop 0
	v_cndmask_b32_e32 v3, 0, v4, vcc
	v_add_f32_e32 v2, v3, v2
	v_fma_f32 v3, v12, s33, -v127
	v_exp_f32_e32 v3, v3
	v_fma_f32 v4, v13, s33, -v127
	v_exp_f32_e32 v4, v4
	v_cmp_lt_f32_e32 vcc, s48, v12
	s_nop 1
	v_cndmask_b32_e32 v3, 0, v3, vcc
	v_cmp_lt_f32_e32 vcc, s48, v13
	v_add_f32_e32 v2, v3, v2
	s_nop 0
	v_cndmask_b32_e32 v3, 0, v4, vcc
	v_add_f32_e32 v2, v3, v2
	v_fma_f32 v3, v14, s33, -v127
	v_exp_f32_e32 v3, v3
	v_fma_f32 v4, v15, s33, -v127
	v_exp_f32_e32 v4, v4
	v_cmp_lt_f32_e32 vcc, s48, v14
	s_nop 1
	v_cndmask_b32_e32 v3, 0, v3, vcc
	v_cmp_lt_f32_e32 vcc, s48, v15
	v_add_f32_e32 v2, v3, v2
	s_nop 0
	v_cndmask_b32_e32 v3, 0, v4, vcc
	v_add_f32_e32 v2, v3, v2
	v_fma_f32 v3, v16, s33, -v127
	v_exp_f32_e32 v3, v3
	v_fma_f32 v4, v17, s33, -v127
	v_exp_f32_e32 v4, v4
	v_cmp_lt_f32_e32 vcc, s48, v16
	s_nop 1
	v_cndmask_b32_e32 v3, 0, v3, vcc
	v_cmp_lt_f32_e32 vcc, s48, v17
	v_add_f32_e32 v2, v3, v2
	s_nop 0
	v_cndmask_b32_e32 v3, 0, v4, vcc
	v_add_f32_e32 v2, v3, v2
	v_fma_f32 v3, v18, s33, -v127
	v_exp_f32_e32 v3, v3
	v_fma_f32 v4, v19, s33, -v127
	v_exp_f32_e32 v4, v4
	v_cmp_lt_f32_e32 vcc, s48, v18
	s_nop 1
	v_cndmask_b32_e32 v3, 0, v3, vcc
	v_cmp_lt_f32_e32 vcc, s48, v19
	v_add_f32_e32 v2, v3, v2
	s_nop 0
	v_cndmask_b32_e32 v3, 0, v4, vcc
	v_add_f32_e32 v2, v3, v2
	v_fma_f32 v3, v20, s33, -v127
	v_exp_f32_e32 v3, v3
	v_fma_f32 v4, v21, s33, -v127
	v_exp_f32_e32 v4, v4
	v_cmp_lt_f32_e32 vcc, s48, v20
	s_nop 1
	v_cndmask_b32_e32 v3, 0, v3, vcc
	v_cmp_lt_f32_e32 vcc, s48, v21
	v_add_f32_e32 v2, v3, v2
	s_nop 0
	v_cndmask_b32_e32 v3, 0, v4, vcc
	v_add_f32_e32 v2, v3, v2
	v_fma_f32 v3, v22, s33, -v127
	v_exp_f32_e32 v3, v3
	v_fma_f32 v4, v23, s33, -v127
	v_exp_f32_e32 v4, v4
	v_cmp_lt_f32_e32 vcc, s48, v22
	s_nop 1
	v_cndmask_b32_e32 v3, 0, v3, vcc
	v_cmp_lt_f32_e32 vcc, s48, v23
	v_add_f32_e32 v2, v3, v2
	s_nop 0
	v_cndmask_b32_e32 v3, 0, v4, vcc
	v_add_f32_e32 v6, v3, v2
	v_fma_f32 v2, v24, s33, -v127
	v_exp_f32_e32 v7, v2
	v_fma_f32 v2, v25, s33, -v127
	v_exp_f32_e32 v8, v2
	v_lshl_add_u64 v[2:3], v[52:53], 0, v[54:55]
	v_lshl_add_u64 v[2:3], v[2:3], 0, v[140:141]
	v_lshl_add_u64 v[4:5], v[52:53], 0, v[0:1]
	v_lshl_add_u64 v[4:5], v[4:5], 0, v[140:141]
	global_load_dwordx4 v[34:37], v[2:3], off offset:128
	global_load_dwordx4 v[38:41], v[4:5], off offset:128
	global_load_dwordx4 v[42:45], v[50:51], off
	global_load_dwordx4 v[46:49], v[50:51], off offset:-4096
	v_cmp_lt_f32_e32 vcc, s48, v24
	v_fma_f32 v3, v27, s33, -v127
	v_exp_f32_e32 v3, v3
	v_cndmask_b32_e32 v0, 0, v7, vcc
	v_cmp_lt_f32_e32 vcc, s48, v25
	v_add_f32_e32 v0, v0, v6
	s_nop 0
	v_cndmask_b32_e32 v2, 0, v8, vcc
	v_add_f32_e32 v0, v2, v0
	v_fma_f32 v2, v26, s33, -v127
	v_exp_f32_e32 v2, v2
	v_cmp_lt_f32_e32 vcc, s48, v26
	s_nop 1
	v_cndmask_b32_e32 v2, 0, v2, vcc
	v_cmp_lt_f32_e32 vcc, s48, v27
	v_add_f32_e32 v0, v2, v0
	s_nop 0
	v_cndmask_b32_e32 v2, 0, v3, vcc
	v_add_f32_e32 v0, v2, v0
	v_fma_f32 v2, v28, s33, -v127
	v_exp_f32_e32 v2, v2
	v_fma_f32 v3, v29, s33, -v127
	v_exp_f32_e32 v3, v3
	v_cmp_lt_f32_e32 vcc, s48, v28
	s_nop 1
	v_cndmask_b32_e32 v2, 0, v2, vcc
	v_cmp_lt_f32_e32 vcc, s48, v29
	v_add_f32_e32 v0, v2, v0
	s_nop 0
	v_cndmask_b32_e32 v2, 0, v3, vcc
	v_add_f32_e32 v0, v2, v0
	v_fma_f32 v2, v30, s33, -v127
	v_exp_f32_e32 v2, v2
	v_fma_f32 v3, v31, s33, -v127
	v_exp_f32_e32 v3, v3
	v_cmp_lt_f32_e32 vcc, s48, v30
	s_nop 1
	v_cndmask_b32_e32 v2, 0, v2, vcc
	v_cmp_lt_f32_e32 vcc, s48, v31
	v_add_f32_e32 v0, v2, v0
	s_nop 0
	v_cndmask_b32_e32 v2, 0, v3, vcc
	v_add_f32_e32 v0, v2, v0
	v_fma_f32 v2, v32, s33, -v127
	v_exp_f32_e32 v2, v2
	v_fma_f32 v3, v33, s33, -v127
	v_exp_f32_e32 v3, v3
	v_cmp_lt_f32_e32 vcc, s48, v32
	s_nop 1
	v_cndmask_b32_e32 v2, 0, v2, vcc
	v_cmp_lt_f32_e32 vcc, s48, v33
	v_add_f32_e32 v0, v2, v0
	s_nop 0
	v_cndmask_b32_e32 v2, 0, v3, vcc
	v_add_f32_e32 v0, v2, v0
	v_mov_b32_e32 v2, v0
	v_mov_b32_e32 v247, v0
	s_nop 1
	v_permlane32_swap_b32_e32 v2, v247
	v_xor_b32_e32 v2, v2, v247
	v_xor_b32_e32 v2, v2, v0
	v_sub_f32_e32 v3, v58, v127
	v_exp_f32_e32 v3, v3
	s_waitcnt lgkmcnt(0)
; DI void phase_attn_nsa(const Params& P, bf16_t* og, unsigned char* smem, int L, int G) {
;     ...
;       const float invl = l > 0.f ? 1.f / l : 0.f;
;       o_zero(o0, o1);
;       float cprev = 0.f;
; #pragma unroll
;       for (int tile = 0; tile < 2; ++tile) {
;         const int key0 = tile * 64;
;         kv64_commit(R, sK, sVt, true, tid);
;         if (tile == 0) kv64_fetch(R, kb, 64, vb, 128, 64, true, tid);
;         __builtin_amdgcn_sched_barrier(0);
;         auto mf = [&](int kk) { return (key0 + kk) * 16 + 31 <= t; };
;         float l2 = 0.f;
;         attn_step<64, true, 2>(sK, sVt, qf, o0, o1, m, l2, sc, mf, lane, s, invl);
	v_add_f32_e32 v0, v0, v2
	v_fmac_f32_e32 v0, v3, v61
	v_div_scale_f32 v2, vcc, v0, v0, 1.0
	v_rcp_f32_e32 v3, v2
	s_nop 0
	v_fma_f32 v4, -v2, v3, 1.0
	v_fmac_f32_e32 v3, v4, v3
	v_div_scale_f32 v4, vcc, 1.0, v0, 1.0
	v_mul_f32_e32 v5, v4, v3
	v_fma_f32 v6, -v2, v5, v4
	v_fmac_f32_e32 v5, v6, v3
	v_fma_f32 v2, -v2, v5, v4
	v_div_fmas_f32 v2, v2, v3, v5
	v_div_fixup_f32 v2, v2, v0, 1.0
	v_cmp_lt_f32_e32 vcc, 0, v0
	s_nop 1
	v_cndmask_b32_e32 v0, 0, v2, vcc
	v_lshl_or_b32 v2, v168, 5, v118
	v_mul_u32_u24_e32 v2, 0x84, v2
	v_add3_u32 v128, v153, v2, v56
	v_cmp_gt_u32_e32 vcc, 32, v137
	v_add_u32_e32 v99, 0x9200, v128
	ds_read_b128 v[2:5], v172
	ds_read_b128 v[50:53], v172 offset:32
	ds_read_b128 v[54:57], v172 offset:64
	ds_read_b128 v[58:61], v172 offset:96
	ds_read_b128 v[6:9], v172 offset:4608
	ds_read_b128 v[62:65], v172 offset:4640
	ds_read_b128 v[66:69], v172 offset:4672
	ds_read_b128 v[70:73], v172 offset:4704
	s_waitcnt lgkmcnt(7)
	v_mfma_f32_32x32x16_bf16 v[18:33], v[2:5], v[74:77], 0
	s_waitcnt lgkmcnt(3)
	v_mfma_f32_32x32x16_bf16 v[2:17], v[6:9], v[74:77], 0
	v_mfma_f32_32x32x16_bf16 v[18:33], v[50:53], v[78:81], v[18:33]
	s_waitcnt lgkmcnt(2)
	v_mfma_f32_32x32x16_bf16 v[2:17], v[62:65], v[78:81], v[2:17]
	v_mfma_f32_32x32x16_bf16 v[18:33], v[54:57], v[82:85], v[18:33]
	s_waitcnt lgkmcnt(1)
	v_mfma_f32_32x32x16_bf16 v[2:17], v[66:69], v[82:85], v[2:17]
	v_mfma_f32_32x32x16_bf16 v[18:33], v[58:61], v[86:89], v[18:33]
	s_waitcnt lgkmcnt(0)
	v_mfma_f32_32x32x16_bf16 v[2:17], v[70:73], v[86:89], v[2:17]
	ds_read_b128 v[94:97], v98 offset:9216
	ds_read_b128 v[90:93], v98 offset:9248
	ds_read_b128 v[62:65], v129 offset:9216
	ds_read_b128 v[58:61], v129 offset:9248
	ds_read_b128 v[70:73], v98 offset:9280
	ds_read_b128 v[54:57], v129 offset:9280
	ds_read_b128 v[66:69], v98 offset:9312
	ds_read_b128 v[50:53], v129 offset:9312
	v_readlane_b32 s50, v245, 26
	v_readlane_b32 s51, v245, 27
	s_nop 1
	v_cndmask_b32_e64 v100, v16, v166, s[36:37]
	v_cndmask_b32_e64 v101, v17, v166, s[34:35]
	v_cndmask_b32_e64 v18, v18, v166, s[50:51]
	v_readlane_b32 s50, v245, 28
	v_readlane_b32 s51, v245, 29
	v_fma_f32 v16, v18, s33, -v127
	v_exp_f32_e32 v16, v16
	v_cndmask_b32_e64 v19, v19, v166, s[50:51]
	v_fma_f32 v17, v19, s33, -v127
	v_exp_f32_e32 v17, v17
	v_readlane_b32 s50, v245, 30
	v_readlane_b32 s51, v245, 31
	v_cmp_lt_f32_e64 s[34:35], s48, v18
	v_cndmask_b32_e64 v32, v32, v166, s[52:53]
	v_cndmask_b32_e64 v20, v20, v166, s[50:51]
	v_readlane_b32 s50, v245, 32
	v_cndmask_b32_e64 v102, 0, v16, s[34:35]
	v_cmp_lt_f32_e64 s[34:35], s48, v19
	v_readlane_b32 s51, v245, 33
	v_cndmask_b32_e64 v33, v33, v166, s[58:59]
	v_cndmask_b32_e64 v17, 0, v17, s[34:35]
	v_cndmask_b32_e64 v21, v21, v166, s[50:51]
	v_mul_f32_e32 v103, v17, v0
	v_fma_f32 v17, v20, s33, -v127
	v_exp_f32_e32 v17, v17
	v_fma_f32 v18, v21, s33, -v127
	v_readlane_b32 s50, v245, 34
	v_exp_f32_e32 v18, v18
	v_readlane_b32 s51, v245, 35
	v_cmp_lt_f32_e64 s[34:35], s48, v20
	v_cndmask_b32_e64 v2, v2, v166, s[62:63]
	v_cndmask_b32_e64 v22, v22, v166, s[50:51]
	v_readlane_b32 s50, v245, 36
	v_readlane_b32 s51, v245, 37
	v_cndmask_b32_e64 v104, 0, v17, s[34:35]
	v_cmp_lt_f32_e64 s[34:35], s48, v21
	v_cndmask_b32_e64 v23, v23, v166, s[50:51]
	v_fma_f32 v20, v23, s33, -v127
	v_cndmask_b32_e64 v105, 0, v18, s[34:35]
	v_fma_f32 v18, v22, s33, -v127
	v_exp_f32_e32 v18, v18
	v_exp_f32_e32 v20, v20
	v_readlane_b32 s50, v245, 38
	v_readlane_b32 s51, v245, 39
	v_cmp_lt_f32_e64 s[34:35], s48, v22
	v_cndmask_b32_e64 v3, v3, v166, s[64:65]
	v_cndmask_b32_e64 v24, v24, v166, s[50:51]
	v_readlane_b32 s50, v245, 40
	v_cndmask_b32_e64 v22, 0, v18, s[34:35]
	v_cmp_lt_f32_e64 s[34:35], s48, v23
	v_readlane_b32 s51, v245, 41
	v_cndmask_b32_e64 v4, v4, v166, s[66:67]
	v_cndmask_b32_e64 v18, 0, v20, s[34:35]
	v_cndmask_b32_e64 v25, v25, v166, s[50:51]
	v_mul_f32_e32 v23, v18, v0
	v_fma_f32 v18, v24, s33, -v127
	v_readlane_b32 s50, v245, 42
	v_exp_f32_e32 v18, v18
	v_fma_f32 v20, v25, s33, -v127
	v_readlane_b32 s51, v245, 43
	v_exp_f32_e32 v20, v20
	v_cmp_lt_f32_e64 s[34:35], s48, v24
	v_cndmask_b32_e64 v26, v26, v166, s[50:51]
	v_readlane_b32 s50, v245, 44
	v_readlane_b32 s51, v245, 45
	v_cndmask_b32_e64 v24, 0, v18, s[34:35]
	v_cmp_lt_f32_e64 s[34:35], s48, v25
	v_cndmask_b32_e64 v27, v27, v166, s[50:51]
	v_fma_f32 v18, v26, s33, -v127
	v_cndmask_b32_e64 v25, 0, v20, s[34:35]
	v_exp_f32_e32 v18, v18
	v_fma_f32 v20, v27, s33, -v127
	v_exp_f32_e32 v20, v20
	v_readlane_b32 s50, v245, 46
	v_readlane_b32 s51, v245, 47
	v_cmp_lt_f32_e64 s[34:35], s48, v26
	v_cndmask_b32_e64 v5, v5, v166, s[68:69]
	v_cndmask_b32_e64 v28, v28, v166, s[50:51]
	v_readlane_b32 s50, v245, 48
	v_cndmask_b32_e64 v26, 0, v18, s[34:35]
	v_cmp_lt_f32_e64 s[34:35], s48, v27
	v_readlane_b32 s51, v245, 49
	v_cndmask_b32_e64 v6, v6, v166, s[70:71]
	v_cndmask_b32_e64 v18, 0, v20, s[34:35]
	v_cndmask_b32_e64 v29, v29, v166, s[50:51]
	v_mul_f32_e32 v27, v18, v0
	v_fma_f32 v18, v28, s33, -v127
	v_readlane_b32 s50, v245, 50
	v_exp_f32_e32 v18, v18
	v_fma_f32 v20, v29, s33, -v127
	v_readlane_b32 s51, v245, 51
	v_exp_f32_e32 v20, v20
	v_cmp_lt_f32_e64 s[34:35], s48, v28
	v_cndmask_b32_e64 v30, v30, v166, s[50:51]
	v_readlane_b32 s50, v245, 52
	v_readlane_b32 s51, v245, 53
	v_cndmask_b32_e64 v28, 0, v18, s[34:35]
	v_cmp_lt_f32_e64 s[34:35], s48, v29
	v_cndmask_b32_e64 v31, v31, v166, s[50:51]
	v_fma_f32 v18, v30, s33, -v127
	v_cndmask_b32_e64 v29, 0, v20, s[34:35]
	v_exp_f32_e32 v18, v18
	v_fma_f32 v20, v31, s33, -v127
	v_exp_f32_e32 v20, v20
	v_cmp_lt_f32_e64 s[34:35], s48, v30
	v_cndmask_b32_e64 v7, v7, v166, s[74:75]
	v_cndmask_b32_e64 v8, v8, v166, s[76:77]
; DI float shx(float v, int m) { return __shfl_xor(v, m, 64); }
; DI void phase_attn_nsa(const Params& P, bf16_t* og, unsigned char* smem, int L, int G) {
;     ...
; #pragma unroll
;         for (int sub = 0; sub < 2; ++sub)
; #pragma unroll
;           for (int s2 = 0; s2 < 2; ++s2) {
;             const int Gi = tile * 4 + sub * 2 + s2;
;             const int q0 = 8 * s2;
;             const float Aj = s[sub][q0] + s[sub][q0 + 1] + s[sub][q0 + 2] + s[sub][q0 + 3];
;             const float Bj = s[sub][q0 + 4] + s[sub][q0 + 5] + s[sub][q0 + 6] + s[sub][q0 + 7] + s[sub][q0 + 3];
;             const float cx = shx(s[sub][q0 + 7], 32);
;             const float add = h ? cx : cprev;
;             cprev = cx;
;             impL[(w * 32 + r) * 33 + 4 * Gi + 2 * h] = Aj + add;
;             impL[(w * 32 + r) * 33 + 4 * Gi + 2 * h + 1] = Bj;
;           }
	v_cndmask_b32_e64 v30, 0, v18, s[34:35]
	v_cmp_lt_f32_e64 s[34:35], s48, v31
	v_cndmask_b32_e64 v9, v9, v166, s[82:83]
	v_cndmask_b32_e64 v10, v10, v166, s[84:85]
	v_cndmask_b32_e64 v18, 0, v20, s[34:35]
	v_mul_f32_e32 v31, v18, v0
	v_fma_f32 v18, v32, s33, -v127
	v_exp_f32_e32 v18, v18
	v_fma_f32 v20, v33, s33, -v127
	v_exp_f32_e32 v20, v20
	v_cmp_lt_f32_e64 s[34:35], s48, v32
	v_cndmask_b32_e64 v11, v11, v166, s[86:87]
	v_cndmask_b32_e64 v12, v12, v166, s[90:91]
	v_cndmask_b32_e64 v32, 0, v18, s[34:35]
	v_cmp_lt_f32_e64 s[34:35], s48, v33
	v_fma_f32 v18, v2, s33, -v127
	v_exp_f32_e32 v18, v18
	v_cndmask_b32_e64 v33, 0, v20, s[34:35]
	v_fma_f32 v20, v3, s33, -v127
	v_exp_f32_e32 v20, v20
	v_cmp_lt_f32_e64 s[34:35], s48, v2
	v_cndmask_b32_e64 v13, v13, v166, s[94:95]
	v_cndmask_b32_e64 v14, v14, v166, s[96:97]
	v_cndmask_b32_e64 v130, 0, v18, s[34:35]
	v_cmp_lt_f32_e64 s[34:35], s48, v3
	v_fma_f32 v3, v5, s33, -v127
	v_exp_f32_e32 v3, v3
	v_cndmask_b32_e64 v2, 0, v20, s[34:35]
	v_mul_f32_e32 v132, v2, v0
	v_fma_f32 v2, v4, s33, -v127
	v_exp_f32_e32 v2, v2
	v_cmp_lt_f32_e64 s[34:35], s48, v4
	v_cndmask_b32_e64 v15, v15, v166, s[40:41]
	v_mul_f32_e32 v16, v102, v0
	v_cndmask_b32_e64 v133, 0, v2, s[34:35]
	v_cmp_lt_f32_e64 s[34:35], s48, v5
	v_fma_f32 v2, v6, s33, -v127
	v_exp_f32_e32 v2, v2
	v_cndmask_b32_e64 v142, 0, v3, s[34:35]
	v_fma_f32 v3, v7, s33, -v127
	v_exp_f32_e32 v3, v3
	v_cmp_lt_f32_e64 s[34:35], s48, v6
	v_mul_f32_e32 v17, v104, v0
	v_mul_f32_e32 v19, v105, v0
	v_cndmask_b32_e64 v144, 0, v2, s[34:35]
	v_cmp_lt_f32_e64 s[34:35], s48, v7
	v_mul_f32_e32 v21, v22, v0
	v_mul_f32_e32 v106, v24, v0
	v_cndmask_b32_e64 v2, 0, v3, s[34:35]
	v_mul_f32_e32 v146, v2, v0
	v_fma_f32 v2, v8, s33, -v127
	v_exp_f32_e32 v2, v2
	v_fma_f32 v3, v9, s33, -v127
	v_exp_f32_e32 v3, v3
	v_cmp_lt_f32_e64 s[34:35], s48, v8
	v_mul_f32_e32 v107, v25, v0
	v_cvt_pk_bf16_f32 v18, v16, v103
	v_cndmask_b32_e64 v147, 0, v2, s[34:35]
	v_cmp_lt_f32_e64 s[34:35], s48, v9
	v_fma_f32 v2, v10, s33, -v127
	v_exp_f32_e32 v2, v2
	v_cndmask_b32_e64 v149, 0, v3, s[34:35]
	v_fma_f32 v3, v11, s33, -v127
	v_exp_f32_e32 v3, v3
	v_cmp_lt_f32_e64 s[34:35], s48, v10
	v_cvt_pk_bf16_f32 v19, v17, v19
	v_cvt_pk_bf16_f32 v20, v21, v23
	v_cndmask_b32_e64 v151, 0, v2, s[34:35]
	v_cmp_lt_f32_e64 s[34:35], s48, v11
	v_cvt_pk_bf16_f32 v21, v106, v107
	v_mul_f32_e32 v108, v26, v0
	v_cndmask_b32_e64 v2, 0, v3, s[34:35]
	v_mul_f32_e32 v176, v2, v0
	v_fma_f32 v2, v12, s33, -v127
	v_exp_f32_e32 v2, v2
	v_fma_f32 v3, v13, s33, -v127
	v_exp_f32_e32 v3, v3
	v_cmp_lt_f32_e64 s[34:35], s48, v12
	v_mul_f32_e32 v109, v28, v0
	v_mul_f32_e32 v110, v29, v0
	v_cndmask_b32_e64 v177, 0, v2, s[34:35]
	v_cmp_lt_f32_e64 s[34:35], s48, v13
	v_fma_f32 v2, v14, s33, -v127
	v_exp_f32_e32 v2, v2
	v_cndmask_b32_e64 v179, 0, v3, s[34:35]
	v_fma_f32 v3, v15, s33, -v127
	v_exp_f32_e32 v3, v3
	v_cmp_lt_f32_e64 s[34:35], s48, v14
	v_mul_f32_e32 v111, v30, v0
	v_mul_f32_e32 v112, v32, v0
	v_cndmask_b32_e64 v181, 0, v2, s[34:35]
	v_cmp_lt_f32_e64 s[34:35], s48, v15
	v_fma_f32 v2, v100, s33, -v127
	v_exp_f32_e32 v184, v2
	v_cndmask_b32_e64 v183, 0, v3, s[34:35]
	s_waitcnt lgkmcnt(7)
	v_mfma_f32_32x32x16_bf16 v[2:17], v[94:97], v[18:21], 0
	v_mul_f32_e32 v113, v33, v0
	v_cvt_pk_bf16_f32 v94, v108, v27
	v_cvt_pk_bf16_f32 v95, v109, v110
	v_cvt_pk_bf16_f32 v96, v111, v31
	v_cvt_pk_bf16_f32 v97, v112, v113
	v_mul_f32_e32 v131, v130, v0
	v_mul_f32_e32 v141, v133, v0
	s_waitcnt lgkmcnt(6)
	v_mfma_f32_32x32x16_bf16 v[2:17], v[90:93], v[94:97], v[2:17]
	v_mul_f32_e32 v143, v142, v0
	v_mul_f32_e32 v145, v144, v0
	v_mul_f32_e32 v148, v147, v0
	v_mul_f32_e32 v150, v149, v0
	v_fma_f32 v90, v101, s33, -v127
	v_exp_f32_e32 v109, v90
	v_cvt_pk_bf16_f32 v90, v131, v132
	v_cvt_pk_bf16_f32 v91, v141, v143
	v_cvt_pk_bf16_f32 v92, v145, v146
	v_cvt_pk_bf16_f32 v93, v148, v150
	v_cmp_lt_f32_e64 s[34:35], s48, v100
	v_mul_f32_e32 v175, v151, v0
	s_waitcnt lgkmcnt(3)
	v_mfma_f32_32x32x16_bf16 v[2:17], v[70:73], v[90:93], v[2:17]
	v_cndmask_b32_e64 v100, 0, v184, s[34:35]
	v_cmp_lt_f32_e64 s[34:35], s48, v101
	v_mul_f32_e32 v178, v177, v0
	v_mul_f32_e32 v180, v179, v0
	v_cndmask_b32_e64 v101, 0, v109, s[34:35]
	v_mul_f32_e32 v182, v181, v0
	v_mul_f32_e32 v106, v183, v0
	v_mul_f32_e32 v108, v100, v0
	v_mul_f32_e32 v109, v101, v0
	v_cvt_pk_bf16_f32 v70, v175, v176
	v_cvt_pk_bf16_f32 v71, v178, v180
	v_cvt_pk_bf16_f32 v72, v182, v106
	v_cvt_pk_bf16_f32 v73, v108, v109
	v_fmac_f32_e32 v103, v102, v0
	v_fmac_f32_e32 v23, v22, v0
	s_waitcnt lgkmcnt(1)
	v_mfma_f32_32x32x16_bf16 v[2:17], v[66:69], v[70:73], v[2:17]
	v_mov_b32_e32 v66, v107
	v_mov_b32_e32 v247, v107
	s_nop 1
	v_permlane32_swap_b32_e32 v66, v247
	v_xor_b32_e32 v66, v66, v247
	v_xor_b32_e32 v66, v66, v107
	v_mov_b32_e32 v67, v113
	v_mov_b32_e32 v247, v113
	s_nop 1
	v_permlane32_swap_b32_e32 v67, v247
	v_xor_b32_e32 v67, v67, v247
	v_xor_b32_e32 v67, v67, v113
	v_fmac_f32_e32 v103, v104, v0
	v_fmac_f32_e32 v23, v24, v0
	v_fmac_f32_e32 v103, v105, v0
	v_fmac_f32_e32 v23, v25, v0
	s_waitcnt lgkmcnt(1)
	v_cndmask_b32_e64 v22, v66, 0, vcc
	v_fmac_f32_e32 v27, v26, v0
	v_fmac_f32_e32 v31, v30, v0
	v_fmac_f32_e32 v23, v105, v0
	v_add_f32_e32 v22, v22, v103
	v_fmac_f32_e32 v27, v28, v0
	v_fmac_f32_e32 v31, v32, v0
	ds_write2_b32 v99, v22, v23 offset1:1
	v_fmac_f32_e32 v27, v29, v0
	v_fmac_f32_e32 v31, v33, v0
	s_waitcnt lgkmcnt(1)
	v_cndmask_b32_e32 v22, v67, v66, vcc
	v_fmac_f32_e32 v31, v29, v0
	v_add_f32_e32 v22, v22, v27
	v_add_u32_e32 v23, 0x9210, v128
	ds_write2_b32 v23, v22, v31 offset1:1
	v_mfma_f32_32x32x16_bf16 v[18:33], v[62:65], v[18:21], 0
	v_fmac_f32_e32 v132, v130, v0
	v_mov_b32_e32 v62, v150
	v_mov_b32_e32 v247, v150
	s_nop 1
	v_permlane32_swap_b32_e32 v62, v247
	v_xor_b32_e32 v62, v62, v247
	v_xor_b32_e32 v62, v62, v150
	v_mov_b32_e32 v130, v109
	v_mov_b32_e32 v247, v109
	s_nop 1
	v_permlane32_swap_b32_e32 v130, v247
	v_xor_b32_e32 v130, v130, v247
	v_xor_b32_e32 v130, v130, v109
	v_fmac_f32_e32 v146, v144, v0
	v_fmac_f32_e32 v176, v151, v0
	v_fmac_f32_e32 v106, v181, v0
	v_fmac_f32_e32 v132, v133, v0
	v_mfma_f32_32x32x16_bf16 v[18:33], v[58:61], v[94:97], v[18:33]
	v_fmac_f32_e32 v146, v147, v0
	v_fmac_f32_e32 v176, v177, v0
	v_fmac_f32_e32 v106, v100, v0
	v_fmac_f32_e32 v132, v142, v0
	v_fmac_f32_e32 v146, v149, v0
	s_waitcnt lgkmcnt(1)
	v_cndmask_b32_e32 v63, v62, v67, vcc
	v_fmac_f32_e32 v176, v179, v0
	v_mfma_f32_32x32x16_bf16 v[18:33], v[54:57], v[90:93], v[18:33]
	v_fmac_f32_e32 v106, v101, v0
	s_waitcnt lgkmcnt(0)
	v_cndmask_b32_e32 v54, v130, v62, vcc
	v_fmac_f32_e32 v146, v142, v0
	v_add_f32_e32 v63, v63, v132
	v_add_u32_e32 v58, 0x9220, v128
	v_fmac_f32_e32 v106, v179, v0
	v_add_f32_e32 v54, v54, v176
	v_mfma_f32_32x32x16_bf16 v[18:33], v[50:53], v[70:73], v[18:33]
	v_add_u32_e32 v55, 0x9230, v128
	ds_write2_b32 v58, v63, v146 offset1:1
	ds_write2_b32 v55, v54, v106 offset1:1
	s_waitcnt lgkmcnt(0)
	s_barrier
; DI float fexp2(float x) { return __builtin_amdgcn_exp2f(x); }
; DI float shx(float v, int m) { return __shfl_xor(v, m, 64); }
; template <int DQK, bool MASKED, int MODE, class MF>
; DI void attn_step(const bf16_t* sK, const bf16_t* sVt, const bf16x8 (&qf)[DQK / 16], f32x16& o0, f32x16& o1, float& m, float& l,
;                   float sc, const MF& mf, int lane, f32x16 (&s)[2], float invl, bool lanevalid = true) {
;     ...
;       if (MASKED) { const int kk = sub * 32 + 16 * (q >> 3) + 8 * h + (q & 7); s[sub][q] = mf(kk) ? s[sub][q] : -3.0e38f; }
;       if (MODE != 2) mxr = fmaxf(mxr, s[sub][q]);
;     }
;   float alpha = 1.f;
;   if (MODE != 2) {
;     float mx = fmaxf(m, mxr * sc);
;     mx = fmaxf(mx, shx(mx, 32));
;     if (!MASKED) mx = lanevalid ? mx : m;
;     alpha = fexp2(m - mx);
;     m = mx;
;   }
;   const float moff = (!MASKED && !lanevalid) ? 1.0e30f : m;
;   float ps = 0.f;
; #pragma unroll
;   for (int sub = 0; sub < 2; ++sub)
; #pragma unroll
;     for (int q = 0; q < 16; ++q) {
;       float pv = fexp2(__builtin_fmaf(s[sub][q], sc, -moff));
;       if (MASKED && MODE != 0) pv = (s[sub][q] > -1.0e38f) ? pv : 0.f;
;       if (MODE == 2) pv *= invl;
;       s[sub][q] = pv;
; DI void phase_attn_nsa(const Params& P, bf16_t* og, unsigned char* smem, int L, int G) {
;     ...
;       for (int tile = 0; tile < 2; ++tile) {
;         const int key0 = tile * 64;
;         kv64_commit(R, sK, sVt, true, tid);
;         if (tile == 0) kv64_fetch(R, kb, 64, vb, 128, 64, true, tid);
;         __builtin_amdgcn_sched_barrier(0);
;         auto mf = [&](int kk) { return (key0 + kk) * 16 + 31 <= t; };
;         float l2 = 0.f;
;         attn_step<64, true, 2>(sK, sVt, qf, o0, o1, m, l2, sc, mf, lane, s, invl);
	s_waitcnt vmcnt(0)
	ds_write_b128 v170, v[46:49]
	ds_write_b128 v170, v[42:45] offset:4608
	ds_write_b128 v170, v[38:41] offset:9216
	ds_write_b128 v170, v[34:37] offset:13824
	s_waitcnt lgkmcnt(0)
	s_barrier
	ds_read_b128 v[34:37], v172
	ds_read_b128 v[66:69], v172 offset:32
	ds_read_b128 v[70:73], v172 offset:64
	ds_read_b128 v[90:93], v172 offset:96
	ds_read_b128 v[38:41], v172 offset:4608
	ds_read_b128 v[94:97], v172 offset:4640
	ds_read_b128 v[100:103], v172 offset:4672
	ds_read_b128 v[104:107], v172 offset:4704
	s_waitcnt lgkmcnt(7)
	v_mfma_f32_32x32x16_bf16 v[50:65], v[34:37], v[74:77], 0
	s_waitcnt lgkmcnt(3)
	v_mfma_f32_32x32x16_bf16 v[34:49], v[38:41], v[74:77], 0
	v_mfma_f32_32x32x16_bf16 v[50:65], v[66:69], v[78:81], v[50:65]
	s_waitcnt lgkmcnt(2)
	v_mfma_f32_32x32x16_bf16 v[34:49], v[94:97], v[78:81], v[34:49]
	v_mfma_f32_32x32x16_bf16 v[50:65], v[70:73], v[82:85], v[50:65]
	s_waitcnt lgkmcnt(1)
	v_mfma_f32_32x32x16_bf16 v[34:49], v[100:103], v[82:85], v[34:49]
	v_mfma_f32_32x32x16_bf16 v[50:65], v[90:93], v[86:89], v[50:65]
	s_waitcnt lgkmcnt(0)
	v_mfma_f32_32x32x16_bf16 v[34:49], v[104:107], v[86:89], v[34:49]
	ds_read_b128 v[110:113], v98 offset:9216
	ds_read_b128 v[106:109], v98 offset:9248
	ds_read_b128 v[94:97], v129 offset:9216
	ds_read_b128 v[90:93], v129 offset:9248
	ds_read_b128 v[102:105], v98 offset:9280
	ds_read_b128 v[70:73], v129 offset:9280
	ds_read_b128 v[98:101], v98 offset:9312
	ds_read_b128 v[66:69], v129 offset:9312
	v_readlane_b32 s34, v245, 54
	v_readlane_b32 s35, v245, 55
	s_nop 1
	v_cndmask_b32_e64 v129, v49, v166, s[0:1]
	v_cndmask_b32_e64 v56, v56, v166, s[54:55]
	v_cndmask_b32_e64 v50, v50, v166, s[34:35]
	v_readlane_b32 s34, v245, 56
	v_readlane_b32 s35, v245, 57
	v_fma_f32 v49, v50, s33, -v127
	v_exp_f32_e32 v49, v49
	v_cndmask_b32_e64 v51, v51, v166, s[34:35]
	v_fma_f32 v131, v51, s33, -v127
	v_exp_f32_e32 v131, v131
	v_readlane_b32 s34, v245, 58
	v_readlane_b32 s35, v245, 59
	v_cmp_lt_f32_e64 s[0:1], s48, v50
	v_cndmask_b32_e64 v57, v57, v166, s[56:57]
	v_cndmask_b32_e64 v52, v52, v166, s[34:35]
	v_readlane_b32 s34, v245, 60
	v_cndmask_b32_e64 v132, 0, v49, s[0:1]
	v_cmp_lt_f32_e64 s[0:1], s48, v51
	v_readlane_b32 s35, v245, 61
	v_cndmask_b32_e64 v58, v58, v166, s[60:61]
	v_cndmask_b32_e64 v50, 0, v131, s[0:1]
	v_cndmask_b32_e64 v53, v53, v166, s[34:35]
	v_readlane_b32 s34, v245, 62
	v_mul_f32_e32 v131, v0, v50
	v_fma_f32 v50, v52, s33, -v127
	v_readlane_b32 s35, v245, 63
	v_exp_f32_e32 v50, v50
	v_fma_f32 v51, v53, s33, -v127
	v_cndmask_b32_e64 v54, v54, v166, s[34:35]
	v_readlane_b32 s34, v244, 0
	v_readlane_b32 s35, v244, 1
	v_exp_f32_e32 v51, v51
	v_cmp_lt_f32_e64 s[0:1], s48, v52
	v_cndmask_b32_e64 v55, v55, v166, s[34:35]
	v_fma_f32 v52, v54, s33, -v127
	v_cndmask_b32_e64 v133, 0, v50, s[0:1]
	v_cmp_lt_f32_e64 s[0:1], s48, v53
	v_exp_f32_e32 v52, v52
	v_fma_f32 v53, v55, s33, -v127
	v_exp_f32_e32 v53, v53
	v_cndmask_b32_e64 v141, 0, v51, s[0:1]
	v_cmp_lt_f32_e64 s[0:1], s48, v54
	v_fma_f32 v54, v57, s33, -v127
	v_exp_f32_e32 v54, v54
	v_cndmask_b32_e64 v142, 0, v52, s[0:1]
	v_cmp_lt_f32_e64 s[0:1], s48, v55
	v_cndmask_b32_e64 v59, v59, v166, s[72:73]
	v_fma_f32 v55, v59, s33, -v127
	v_cndmask_b32_e64 v53, 0, v53, s[0:1]
	v_mul_f32_e32 v143, v0, v53
	v_fma_f32 v53, v56, s33, -v127
	v_exp_f32_e32 v53, v53
	v_cmp_lt_f32_e64 s[0:1], s48, v56
	v_exp_f32_e32 v55, v55
	v_cndmask_b32_e64 v60, v60, v166, s[78:79]
	v_cndmask_b32_e64 v56, 0, v53, s[0:1]
	v_cmp_lt_f32_e64 s[0:1], s48, v57
	v_cndmask_b32_e64 v61, v61, v166, s[80:81]
	v_cndmask_b32_e64 v62, v62, v166, s[88:89]
	v_cndmask_b32_e64 v57, 0, v54, s[0:1]
	v_fma_f32 v54, v58, s33, -v127
	v_exp_f32_e32 v54, v54
	v_cmp_lt_f32_e64 s[0:1], s48, v58
	v_fma_f32 v145, v61, s33, -v127
	v_cndmask_b32_e64 v63, v63, v166, s[92:93]
	v_cndmask_b32_e64 v58, 0, v54, s[0:1]
	v_cmp_lt_f32_e64 s[0:1], s48, v59
	v_exp_f32_e32 v145, v145
	v_fma_f32 v146, v62, s33, -v127
	v_cndmask_b32_e64 v55, 0, v55, s[0:1]
	v_mul_f32_e32 v59, v0, v55
	v_fma_f32 v55, v60, s33, -v127
	v_exp_f32_e32 v55, v55
	v_exp_f32_e32 v146, v146
	v_fma_f32 v147, v63, s33, -v127
	v_cmp_lt_f32_e64 s[0:1], s48, v60
	v_exp_f32_e32 v147, v147
	v_cndmask_b32_e64 v64, v64, v166, s[42:43]
	v_cndmask_b32_e64 v60, 0, v55, s[0:1]
	v_cmp_lt_f32_e64 s[0:1], s48, v61
	v_cndmask_b32_e64 v65, v65, v166, s[38:39]
	v_cndmask_b32_e64 v34, v34, v166, s[30:31]
	v_cndmask_b32_e64 v61, 0, v145, s[0:1]
	v_cmp_lt_f32_e64 s[0:1], s48, v62
	v_fma_f32 v148, v65, s33, -v127
	v_cndmask_b32_e64 v35, v35, v166, s[28:29]
	v_cndmask_b32_e64 v62, 0, v146, s[0:1]
	v_cmp_lt_f32_e64 s[0:1], s48, v63
	v_exp_f32_e32 v148, v148
	v_fma_f32 v149, v34, s33, -v127
	v_cndmask_b32_e64 v63, 0, v147, s[0:1]
	v_fma_f32 v147, v64, s33, -v127
	v_exp_f32_e32 v147, v147
	v_exp_f32_e32 v149, v149
	v_fma_f32 v150, v35, s33, -v127
	v_cmp_lt_f32_e64 s[0:1], s48, v64
	v_exp_f32_e32 v150, v150
	v_cndmask_b32_e64 v36, v36, v166, s[26:27]
	v_cndmask_b32_e64 v64, 0, v147, s[0:1]
	v_cmp_lt_f32_e64 s[0:1], s48, v65
	v_cndmask_b32_e64 v37, v37, v166, s[16:17]
	v_cndmask_b32_e64 v38, v38, v166, s[18:19]
	v_cndmask_b32_e64 v65, 0, v148, s[0:1]
	v_cmp_lt_f32_e64 s[0:1], s48, v34
	v_cndmask_b32_e64 v39, v39, v166, s[20:21]
	v_cndmask_b32_e64 v40, v40, v166, s[22:23]
	v_cndmask_b32_e64 v149, 0, v149, s[0:1]
	v_cmp_lt_f32_e64 s[0:1], s48, v35
	v_fma_f32 v35, v37, s33, -v127
	v_exp_f32_e32 v35, v35
	v_cndmask_b32_e64 v34, 0, v150, s[0:1]
	v_mul_f32_e32 v150, v0, v34
	v_fma_f32 v34, v36, s33, -v127
	v_exp_f32_e32 v34, v34
	v_cmp_lt_f32_e64 s[0:1], s48, v36
	v_cndmask_b32_e64 v41, v41, v166, s[24:25]
	v_cndmask_b32_e64 v42, v42, v166, s[14:15]
; DI float shx(float v, int m) { return __shfl_xor(v, m, 64); }
; DI void phase_attn_nsa(const Params& P, bf16_t* og, unsigned char* smem, int L, int G) {
;     ...
; #pragma unroll
;         for (int sub = 0; sub < 2; ++sub)
; #pragma unroll
;           for (int s2 = 0; s2 < 2; ++s2) {
;             const int Gi = tile * 4 + sub * 2 + s2;
;             const int q0 = 8 * s2;
;             const float Aj = s[sub][q0] + s[sub][q0 + 1] + s[sub][q0 + 2] + s[sub][q0 + 3];
;             const float Bj = s[sub][q0 + 4] + s[sub][q0 + 5] + s[sub][q0 + 6] + s[sub][q0 + 7] + s[sub][q0 + 3];
;             const float cx = shx(s[sub][q0 + 7], 32);
;             const float add = h ? cx : cprev;
;             cprev = cx;
;             impL[(w * 32 + r) * 33 + 4 * Gi + 2 * h] = Aj + add;
;             impL[(w * 32 + r) * 33 + 4 * Gi + 2 * h + 1] = Bj;
;           }
;       }
;     }
;     __syncthreads();
	v_cndmask_b32_e64 v175, 0, v34, s[0:1]
	v_cmp_lt_f32_e64 s[0:1], s48, v37
	v_fma_f32 v34, v38, s33, -v127
	v_exp_f32_e32 v34, v34
	v_cndmask_b32_e64 v177, 0, v35, s[0:1]
	v_fma_f32 v35, v39, s33, -v127
	v_exp_f32_e32 v35, v35
	v_cmp_lt_f32_e64 s[0:1], s48, v38
	v_cndmask_b32_e64 v43, v43, v166, s[12:13]
	v_cndmask_b32_e64 v44, v44, v166, s[10:11]
	v_cndmask_b32_e64 v179, 0, v34, s[0:1]
	v_cmp_lt_f32_e64 s[0:1], s48, v39
	v_cndmask_b32_e64 v45, v45, v166, s[8:9]
	v_cndmask_b32_e64 v46, v46, v166, s[6:7]
	v_cndmask_b32_e64 v34, 0, v35, s[0:1]
	v_mul_f32_e32 v181, v0, v34
	v_fma_f32 v34, v40, s33, -v127
	v_exp_f32_e32 v34, v34
	v_fma_f32 v35, v41, s33, -v127
	v_exp_f32_e32 v35, v35
	v_cmp_lt_f32_e64 s[0:1], s48, v40
	v_cndmask_b32_e64 v47, v47, v166, s[4:5]
	v_cndmask_b32_e64 v48, v48, v166, s[2:3]
	v_cndmask_b32_e64 v182, 0, v34, s[0:1]
	v_cmp_lt_f32_e64 s[0:1], s48, v41
	v_fma_f32 v34, v42, s33, -v127
	v_exp_f32_e32 v34, v34
	v_cndmask_b32_e64 v184, 0, v35, s[0:1]
	v_fma_f32 v35, v43, s33, -v127
	v_exp_f32_e32 v35, v35
	v_cmp_lt_f32_e64 s[0:1], s48, v42
	v_mul_f32_e32 v49, v0, v132
	v_mul_f32_e32 v50, v0, v133
	v_cndmask_b32_e64 v42, 0, v34, s[0:1]
	v_cmp_lt_f32_e64 s[0:1], s48, v43
	v_mul_f32_e32 v51, v0, v141
	v_mul_f32_e32 v52, v0, v142
	v_cndmask_b32_e64 v34, 0, v35, s[0:1]
	v_mul_f32_e32 v43, v0, v34
	v_fma_f32 v34, v44, s33, -v127
	v_exp_f32_e32 v34, v34
	v_fma_f32 v35, v45, s33, -v127
	v_exp_f32_e32 v35, v35
	v_cmp_lt_f32_e64 s[0:1], s48, v44
	v_mul_f32_e32 v53, v0, v56
	v_mul_f32_e32 v144, v0, v57
	v_cndmask_b32_e64 v44, 0, v34, s[0:1]
	v_cmp_lt_f32_e64 s[0:1], s48, v45
	v_fma_f32 v34, v46, s33, -v127
	v_exp_f32_e32 v34, v34
	v_cndmask_b32_e64 v45, 0, v35, s[0:1]
	v_fma_f32 v35, v47, s33, -v127
	v_exp_f32_e32 v35, v35
	v_cmp_lt_f32_e64 s[0:1], s48, v46
	v_cvt_pk_bf16_f32 v36, v52, v143
	v_cvt_pk_bf16_f32 v37, v53, v144
	v_cndmask_b32_e64 v46, 0, v34, s[0:1]
	v_cmp_lt_f32_e64 s[0:1], s48, v47
	v_fma_f32 v34, v48, s33, -v127
	v_exp_f32_e32 v39, v34
	v_cndmask_b32_e64 v38, 0, v35, s[0:1]
	v_cvt_pk_bf16_f32 v34, v49, v131
	v_cvt_pk_bf16_f32 v35, v50, v51
	v_mul_f32_e32 v54, v0, v58
	v_mul_f32_e32 v55, v0, v60
	s_waitcnt lgkmcnt(7)
	v_mfma_f32_32x32x16_bf16 v[2:17], v[110:113], v[34:37], v[2:17]
	v_mul_f32_e32 v145, v0, v61
	v_mul_f32_e32 v146, v0, v62
	v_mul_f32_e32 v63, v0, v63
	v_mul_f32_e32 v147, v0, v64
	v_mul_f32_e32 v148, v0, v65
	v_cmp_lt_f32_e64 s[0:1], s48, v48
	v_mul_f32_e32 v47, v0, v38
	v_cvt_pk_bf16_f32 v38, v54, v59
	v_cndmask_b32_e64 v110, 0, v39, s[0:1]
	v_cvt_pk_bf16_f32 v39, v55, v145
	v_cvt_pk_bf16_f32 v40, v146, v63
	v_cvt_pk_bf16_f32 v41, v147, v148
	v_mul_f32_e32 v151, v0, v149
	v_mul_f32_e32 v176, v0, v175
	s_waitcnt lgkmcnt(6)
	v_mfma_f32_32x32x16_bf16 v[2:17], v[106:109], v[38:41], v[2:17]
	v_mul_f32_e32 v178, v0, v177
	v_mul_f32_e32 v180, v0, v179
	v_mul_f32_e32 v183, v0, v182
	v_mul_f32_e32 v185, v0, v184
	v_fma_f32 v48, v129, s33, -v127
	v_exp_f32_e32 v52, v48
	v_cvt_pk_bf16_f32 v48, v151, v150
	v_cvt_pk_bf16_f32 v49, v176, v178
	v_cvt_pk_bf16_f32 v50, v180, v181
	v_cvt_pk_bf16_f32 v51, v183, v185
	v_cmp_lt_f32_e64 s[0:1], s48, v129
	v_mul_f32_e32 v186, v0, v42
	s_waitcnt lgkmcnt(3)
	v_mfma_f32_32x32x16_bf16 v[2:17], v[102:105], v[48:51], v[2:17]
	v_cndmask_b32_e64 v102, 0, v52, s[0:1]
	v_mul_f32_e32 v187, v0, v44
	v_mul_f32_e32 v188, v0, v45
	v_mul_f32_e32 v189, v0, v46
	v_mul_f32_e32 v55, v0, v110
	v_mul_f32_e32 v103, v0, v102
	v_cvt_pk_bf16_f32 v52, v186, v43
	v_cvt_pk_bf16_f32 v53, v187, v188
	v_cvt_pk_bf16_f32 v54, v189, v47
	v_cvt_pk_bf16_f32 v55, v55, v103
	v_fmac_f32_e32 v131, v0, v132
	v_fmac_f32_e32 v143, v0, v142
	s_waitcnt lgkmcnt(1)
	v_mfma_f32_32x32x16_bf16 v[2:17], v[98:101], v[52:55], v[2:17]
	v_mov_b32_e32 v98, v144
	v_mov_b32_e32 v247, v144
	s_nop 1
	v_permlane32_swap_b32_e32 v98, v247
	v_xor_b32_e32 v98, v98, v247
	v_xor_b32_e32 v98, v98, v144
	v_fmac_f32_e32 v131, v0, v133
	v_fmac_f32_e32 v143, v0, v56
	v_fmac_f32_e32 v131, v0, v141
	v_fmac_f32_e32 v143, v0, v57
	s_waitcnt lgkmcnt(0)
	v_cndmask_b32_e32 v56, v98, v130, vcc
	v_fmac_f32_e32 v143, v0, v141
	v_add_f32_e32 v56, v131, v56
	v_add_u32_e32 v57, 0x9240, v128
	ds_write2_b32 v57, v56, v143 offset1:1
	v_mov_b32_e32 v56, v148
	v_mov_b32_e32 v247, v148
	s_nop 1
	v_permlane32_swap_b32_e32 v56, v247
	v_xor_b32_e32 v56, v56, v247
	v_xor_b32_e32 v56, v56, v148
	v_fmac_f32_e32 v59, v0, v58
	v_fmac_f32_e32 v63, v0, v62
	v_fmac_f32_e32 v59, v0, v60
	v_fmac_f32_e32 v63, v0, v64
	v_mfma_f32_32x32x16_bf16 v[18:33], v[94:97], v[34:37], v[18:33]
	v_fmac_f32_e32 v59, v0, v61
	v_fmac_f32_e32 v63, v0, v65
	s_waitcnt lgkmcnt(0)
	v_cndmask_b32_e32 v57, v56, v98, vcc
	v_fmac_f32_e32 v63, v0, v61
	v_add_f32_e32 v57, v59, v57
	v_add_u32_e32 v58, 0x9250, v128
	ds_write2_b32 v58, v57, v63 offset1:1
	v_mov_b32_e32 v57, v185
	v_mov_b32_e32 v247, v185
	s_nop 1
	v_permlane32_swap_b32_e32 v57, v247
	v_xor_b32_e32 v57, v57, v247
	v_xor_b32_e32 v57, v57, v185
	v_fmac_f32_e32 v43, v0, v42
	v_mov_b32_e32 v42, v103
	v_mov_b32_e32 v247, v103
	s_nop 1
	v_permlane32_swap_b32_e32 v42, v247
	v_xor_b32_e32 v42, v42, v247
	v_xor_b32_e32 v42, v42, v103
	v_fmac_f32_e32 v181, v0, v179
	v_fmac_f32_e32 v47, v0, v46
	v_fmac_f32_e32 v150, v0, v149
	v_fmac_f32_e32 v181, v0, v182
	v_fmac_f32_e32 v47, v0, v110
	v_fmac_f32_e32 v150, v0, v175
	v_fmac_f32_e32 v181, v0, v184
	v_fmac_f32_e32 v43, v0, v44
	v_fmac_f32_e32 v47, v0, v102
	v_fmac_f32_e32 v150, v0, v177
	v_fmac_f32_e32 v181, v0, v177
	v_fmac_f32_e32 v43, v0, v45
	v_fmac_f32_e32 v47, v0, v45
	s_waitcnt lgkmcnt(0)
	v_cndmask_b32_e32 v0, v42, v57, vcc
	v_mfma_f32_32x32x16_bf16 v[18:33], v[90:93], v[38:41], v[18:33]
	v_add_f32_e32 v0, v43, v0
	v_add_u32_e32 v34, 0x9270, v128
	v_bfe_u32 v46, v120, 5, 3
	v_cndmask_b32_e32 v56, v57, v56, vcc
	ds_write2_b32 v34, v0, v47 offset1:1
	v_mul_u32_u24_e32 v43, 33, v46
	v_mad_u32_u24 v0, v46, 33, v118
	v_add_f32_e32 v56, v150, v56
	v_add_u32_e32 v58, 0x9260, v128
	v_lshl_add_u32 v0, v0, 2, v153
	v_lshlrev_b32_e32 v38, 2, v43
	v_lshlrev_b32_e32 v34, 2, v118
	ds_write2_b32 v58, v56, v181 offset1:1
	s_waitcnt lgkmcnt(0)
	s_barrier
; DI void phase_attn_nsa(const Params& P, bf16_t* og, unsigned char* smem, int L, int G) {
;     ...
; #pragma unroll
;     for (int pss = 0; pss < 4; ++pss) {
;       const int pair = pss * 256 + tid, q = pair >> 5, j = pair & 31;
;       scoreL[q * 33 + j] = impL[(0 * 32 + q) * 33 + j] + impL[(1 * 32 + q) * 33 + j] + impL[(2 * 32 + q) * 33 + j] + impL[(3 * 32 + q) * 33 + j];
;     }
;     __syncthreads();
; #pragma unroll
;     for (int pss = 0; pss < 4; ++pss) {
;       const int pair = pss * 256 + tid, q = pair >> 5, j = pair & 31;
;       const int tq = t0 + q, cur = tq >> 6;
;       const bool forced = (j == 0) || (j == cur) || (j == cur - 1);
;       const int nf = cur >= 2 ? 3 : cur + 1;
;       const int need = 8 - nf;
;       const bool cand = (j >= 1) && (j <= cur - 2);
;       const float sj = scoreL[q * 33 + j];
;       int rank = 0;
;       for (int j2 = 1; j2 <= cur - 2; ++j2) {
;         const float s2v = scoreL[q * 33 + j2];
;         rank += (s2v > sj || (s2v == sj && j2 < j)) ? 1 : 0;
;       }
;       const bool selected = forced || (cand && rank < need);
	v_add3_u32 v35, v153, v38, v34
	ds_read_b32 v36, v0 offset:37376
	ds_read_b32 v37, v35 offset:41600
	ds_read_b32 v39, v35 offset:45824
	ds_read_b32 v40, v35 offset:50048
	v_mfma_f32_32x32x16_bf16 v[18:33], v[70:73], v[48:51], v[18:33]
	s_lshr_b32 s20, s44, 1
	s_waitcnt lgkmcnt(2)
	v_add_f32_e32 v36, v36, v37
	s_waitcnt lgkmcnt(1)
	v_add_f32_e32 v36, v36, v39
	s_waitcnt lgkmcnt(0)
	v_add_f32_e32 v36, v36, v40
	ds_write_b32 v0, v36 offset:54272
	ds_read_b32 v0, v35 offset:38432
	ds_read_b32 v36, v35 offset:42656
	ds_read_b32 v37, v35 offset:46880
	ds_read_b32 v39, v35 offset:39488
	ds_read_b32 v40, v35 offset:43712
	ds_read_b32 v41, v35 offset:47936
	ds_read_b32 v42, v35 offset:44768
	ds_read_b32 v44, v35 offset:40544
	s_waitcnt lgkmcnt(6)
	v_add_f32_e32 v0, v0, v36
	ds_read_b32 v36, v35 offset:51104
	s_waitcnt lgkmcnt(6)
	v_add_f32_e32 v0, v0, v37
	v_mfma_f32_32x32x16_bf16 v[18:33], v[66:69], v[52:55], v[18:33]
	ds_read_b32 v37, v35 offset:52160
	ds_read_b32 v45, v35 offset:53216
	ds_read_b32 v47, v35 offset:48992
	s_min_u32 s0, s20, 2
	s_waitcnt lgkmcnt(3)
	v_add_f32_e32 v0, v0, v36
	ds_write_b32 v35, v0 offset:55328
	v_add_f32_e32 v0, v39, v40
	v_add_f32_e32 v0, v0, v41
	s_waitcnt lgkmcnt(3)
	v_add_f32_e32 v0, v0, v37
	ds_write_b32 v35, v0 offset:56384
	v_add_f32_e32 v0, v44, v42
	s_add_i32 s22, s20, -1
	s_xor_b32 s21, s0, 7
	s_add_i32 s23, s20, -2
	s_waitcnt lgkmcnt(2)
	v_add_f32_e32 v0, v0, v47
	v_add_u32_e32 v39, v153, v34
	s_cmp_gt_u32 s44, 5
	v_add_f32_e32 v0, v0, v45
	s_cselect_b64 s[10:11], -1, 0
	s_cmp_lt_u32 s44, 6
	v_add_u32_e32 v44, v39, v38
	s_mov_b64 s[2:3], -1
	ds_write_b32 v35, v0 offset:57440
	s_waitcnt lgkmcnt(0)
	s_barrier
	s_cbranch_scc1 .LBB0_1292
	ds_read_b32 v34, v44 offset:54272
	s_cmp_lt_u32 s23, 2
	s_cbranch_scc1 .LBB0_1284
	s_add_i32 s0, s20, -4
	s_lshr_b32 s14, s0, 1
	s_add_i32 s14, s14, 1
	s_cmp_lt_u32 s0, 6
	v_mov_b32_e32 v35, v118
	s_cbranch_scc1 .LBB0_1285
	s_and_b32 s16, s14, -4
	s_mov_b32 s13, 2
	v_lshl_add_u32 v0, v43, 2, v155
	s_mov_b32 s12, 1
	s_mov_b32 s15, 0
	v_mov_b32_e32 v36, 0
	v_mov_b32_e32 v37, 0

; DI float fexp2(float x) { return __builtin_amdgcn_exp2f(x); }
; DI float shx(float v, int m) { return __shfl_xor(v, m, 64); }
; template <int DQK, bool MASKED, int MODE, class MF>
; DI void attn_step(const bf16_t* sK, const bf16_t* sVt, const bf16x8 (&qf)[DQK / 16], f32x16& o0, f32x16& o1, float& m, float& l,
;                   float sc, const MF& mf, int lane, f32x16 (&s)[2], float invl, bool lanevalid = true) {
;     ...
;   float alpha = 1.f;
;   if (MODE != 2) {
;     float mx = fmaxf(m, mxr * sc);
;     mx = fmaxf(mx, shx(mx, 32));
;     if (!MASKED) mx = lanevalid ? mx : m;
;     alpha = fexp2(m - mx);
;     m = mx;
;   }
;   const float moff = (!MASKED && !lanevalid) ? 1.0e30f : m;
;   float ps = 0.f;
; #pragma unroll
;   for (int sub = 0; sub < 2; ++sub)
; #pragma unroll
;     for (int q = 0; q < 16; ++q) {
;       float pv = fexp2(__builtin_fmaf(s[sub][q], sc, -moff));
;       if (MASKED && MODE != 0) pv = (s[sub][q] > -1.0e38f) ? pv : 0.f;
;       if (MODE == 2) pv *= invl;
;       s[sub][q] = pv;
;       ps += pv;
;     }
;   if (MODE != 2) {
;     ps += shx(ps, 32);
;     l = l * alpha + ps;
;   }
;   if (MODE == 1) return;
;   if (MODE == 0) {
; #pragma unroll
;     for (int q = 0; q < 16; ++q) { o0[q] *= alpha; o1[q] *= alpha; }
; DI void phase_attn_nsa(const Params& P, bf16_t* og, unsigned char* smem, int L, int G) {
;     ...
;         if ((selU >> j) & 1u) {
;           const bool lsel = (sel >> j) & 1u;
;           auto mf = [&](int kk) { return lsel && (key0 + kk <= t); };
;           if (key0 + 63 > t0) attn_step<64, true, 0>(sK + cb * KVB64, sVt + cb * KVB64, qf, o0, o1, m, l, sc, mf, lane, s, 0.f);
;           else attn_step<64, false, 0>(sK + cb * KVB64, sVt + cb * KVB64, qf, o0, o1, m, l, sc, mf, lane, s, 0.f, lsel);
.LBB0_1349:
	s_lshr_b32 s1, s2, s0
	s_bitcmp0_b32 s1, 0
	s_cbranch_scc1 .LBB0_1355
	v_lshrrev_b32_e32 v0, s0, v183
	s_add_i32 s6, s44, 63
	s_mulk_i32 s5, 0x4800
	v_and_b32_e32 v190, 1, v0
	s_mov_b64 s[0:1], -1
	s_cmp_le_u32 s6, s46
	v_max_f32_e32 v188, v141, v141
	v_add_u32_e32 v189, s5, v153
	v_cmp_eq_u32_e32 vcc, 1, v190
	s_cbranch_scc0 .LBB0_1352
	v_add_u32_e32 v0, s5, v182
	ds_read_b128 v[34:37], v0
	ds_read_b128 v[38:41], v0 offset:32
	ds_read_b128 v[106:109], v0 offset:64
	ds_read_b128 v[110:113], v0 offset:96
	ds_read_b128 v[42:45], v0 offset:4608
	ds_read_b128 v[114:117], v0 offset:4640
	ds_read_b128 v[118:121], v0 offset:4672
	ds_read_b128 v[194:197], v0 offset:4704
	s_waitcnt lgkmcnt(7)
	v_mfma_f32_32x32x16_bf16 v[58:73], v[34:37], v[74:77], 0
	v_add3_u32 v0, v189, v175, v138
	v_add3_u32 v34, v189, v177, v138
	s_waitcnt lgkmcnt(3)
	v_mfma_f32_32x32x16_bf16 v[42:57], v[42:45], v[74:77], 0
	v_mfma_f32_32x32x16_bf16 v[58:73], v[38:41], v[78:81], v[58:73]
	s_waitcnt lgkmcnt(2)
	v_mfma_f32_32x32x16_bf16 v[42:57], v[114:117], v[78:81], v[42:57]
	v_mfma_f32_32x32x16_bf16 v[58:73], v[106:109], v[82:85], v[58:73]
	s_waitcnt lgkmcnt(1)
	v_mfma_f32_32x32x16_bf16 v[42:57], v[118:121], v[82:85], v[42:57]
	v_mfma_f32_32x32x16_bf16 v[58:73], v[110:113], v[86:89], v[58:73]
	ds_read_b128 v[198:201], v0 offset:9216
	ds_read_b128 v[126:129], v0 offset:9248
	ds_read_b128 v[130:133], v34 offset:9216
	ds_read_b128 v[122:125], v34 offset:9248
	ds_read_b128 v[118:121], v0 offset:9280
	ds_read_b128 v[110:113], v0 offset:9312
	ds_read_b128 v[114:117], v34 offset:9280
	ds_read_b128 v[106:109], v34 offset:9312
	s_waitcnt lgkmcnt(8)
	v_mfma_f32_32x32x16_bf16 v[42:57], v[194:197], v[86:89], v[42:57]
	s_nop 1
	v_max3_f32 v0, v58, s8, v59
	v_max3_f32 v0, v0, v60, v61
	v_max3_f32 v0, v0, v62, v63
	v_max3_f32 v0, v0, v64, v65
	v_max3_f32 v0, v0, v66, v67
	v_max3_f32 v0, v0, v68, v69
	v_max3_f32 v0, v0, v70, v71
	v_max3_f32 v0, v0, v72, v73
	s_nop 1
	v_max3_f32 v0, v0, v42, v43
	v_max3_f32 v0, v0, v44, v45
	v_max3_f32 v0, v0, v46, v47
	v_max3_f32 v0, v0, v48, v49
	v_max3_f32 v0, v0, v50, v51
	v_max3_f32 v0, v0, v52, v53
	v_max3_f32 v0, v0, v54, v55
	v_max3_f32 v0, v0, v56, v57
	v_mul_f32_e32 v0, 0x3e38aa3b, v0
	v_max_f32_e32 v0, v188, v0
	v_mov_b32_e32 v34, v0
	v_mov_b32_e32 v247, v0
	s_nop 1
	v_permlane32_swap_b32_e32 v34, v247
	v_xor_b32_e32 v34, v34, v247
	v_xor_b32_e32 v34, v34, v0
	s_mov_b64 s[0:1], 0
	v_max_f32_e32 v34, v34, v34
	v_max_f32_e32 v34, v0, v34
	v_cndmask_b32_e64 v191, v167, -v34, vcc
	v_fmamk_f32 v35, v58, 0x3e38aa3b, v191
	v_fmamk_f32 v36, v59, 0x3e38aa3b, v191
	v_exp_f32_e32 v58, v35
	v_fmamk_f32 v37, v60, 0x3e38aa3b, v191
	v_exp_f32_e32 v59, v36
	v_exp_f32_e32 v60, v37
	v_fmamk_f32 v35, v61, 0x3e38aa3b, v191
	v_exp_f32_e32 v61, v35
	v_add_f32_e32 v36, 0, v58
	v_fmamk_f32 v35, v62, 0x3e38aa3b, v191
	v_add_f32_e32 v36, v59, v36
	v_exp_f32_e32 v62, v35
	v_fmamk_f32 v35, v63, 0x3e38aa3b, v191
	v_add_f32_e32 v36, v60, v36
	v_exp_f32_e32 v63, v35
	v_fmamk_f32 v35, v64, 0x3e38aa3b, v191
	v_exp_f32_e32 v64, v35
	v_add_f32_e32 v35, v61, v36
	v_fmamk_f32 v36, v65, 0x3e38aa3b, v191
	v_exp_f32_e32 v65, v36
	v_fmamk_f32 v36, v66, 0x3e38aa3b, v191
	v_add_f32_e32 v35, v62, v35
	v_exp_f32_e32 v203, v36
	v_fmamk_f32 v36, v67, 0x3e38aa3b, v191
	v_add_f32_e32 v35, v63, v35
	v_exp_f32_e32 v204, v36
	v_fmamk_f32 v36, v68, 0x3e38aa3b, v191
	v_add_f32_e32 v35, v64, v35
	v_exp_f32_e32 v205, v36
	v_fmamk_f32 v36, v69, 0x3e38aa3b, v191
	v_add_f32_e32 v35, v65, v35
	v_exp_f32_e32 v206, v36
	v_fmamk_f32 v36, v70, 0x3e38aa3b, v191
	v_add_f32_e32 v35, v203, v35
	v_exp_f32_e32 v207, v36
	v_fmamk_f32 v36, v71, 0x3e38aa3b, v191
	v_add_f32_e32 v35, v204, v35
	v_exp_f32_e32 v208, v36
	v_fmamk_f32 v36, v72, 0x3e38aa3b, v191
	v_add_f32_e32 v35, v205, v35
	v_exp_f32_e32 v209, v36
	v_fmamk_f32 v36, v73, 0x3e38aa3b, v191
	v_add_f32_e32 v35, v206, v35
	v_exp_f32_e32 v210, v36
	v_fmamk_f32 v36, v42, 0x3e38aa3b, v191
	v_add_f32_e32 v35, v207, v35
	v_exp_f32_e32 v211, v36
	v_fmamk_f32 v36, v43, 0x3e38aa3b, v191
	v_add_f32_e32 v35, v208, v35
	v_exp_f32_e32 v212, v36
	v_fmamk_f32 v36, v44, 0x3e38aa3b, v191
	v_add_f32_e32 v35, v209, v35
	v_exp_f32_e32 v213, v36
	v_fmamk_f32 v36, v45, 0x3e38aa3b, v191
	v_add_f32_e32 v35, v210, v35
	v_exp_f32_e32 v214, v36
	v_fmamk_f32 v36, v46, 0x3e38aa3b, v191
	v_add_f32_e32 v35, v211, v35
	v_exp_f32_e32 v215, v36
	v_fmamk_f32 v36, v47, 0x3e38aa3b, v191
	v_cndmask_b32_e32 v0, v141, v34, vcc
	v_add_f32_e32 v35, v212, v35
	v_exp_f32_e32 v216, v36
	v_fmamk_f32 v36, v48, 0x3e38aa3b, v191
	v_sub_f32_e32 v34, v141, v0
	v_add_f32_e32 v35, v213, v35
	v_exp_f32_e32 v217, v36
	v_add_f32_e32 v35, v214, v35
	v_exp_f32_e32 v202, v34
	v_add_f32_e32 v35, v215, v35
	v_add_f32_e32 v35, v216, v35
	v_add_f32_e32 v218, v217, v35
	v_fmamk_f32 v35, v49, 0x3e38aa3b, v191
	v_fmamk_f32 v34, v50, 0x3e38aa3b, v191
	v_exp_f32_e32 v219, v35
	v_exp_f32_e32 v220, v34
	v_pk_mul_f32 v[48:49], v[32:33], v[202:203] op_sel_hi:[1,0]
	v_pk_mul_f32 v[46:47], v[30:31], v[202:203] op_sel_hi:[1,0]
	v_pk_mul_f32 v[44:45], v[28:29], v[202:203] op_sel_hi:[1,0]
	v_pk_mul_f32 v[42:43], v[26:27], v[202:203] op_sel_hi:[1,0]
	v_pk_mul_f32 v[40:41], v[24:25], v[202:203] op_sel_hi:[1,0]
	v_pk_mul_f32 v[38:39], v[22:23], v[202:203] op_sel_hi:[1,0]
	v_pk_mul_f32 v[36:37], v[20:21], v[202:203] op_sel_hi:[1,0]
	v_pk_mul_f32 v[34:35], v[18:19], v[202:203] op_sel_hi:[1,0]
	v_cvt_pk_bf16_f32 v194, v58, v59
	v_cvt_pk_bf16_f32 v195, v60, v61
	v_cvt_pk_bf16_f32 v196, v62, v63
	v_cvt_pk_bf16_f32 v197, v64, v65
	v_pk_mul_f32 v[72:73], v[16:17], v[202:203] op_sel_hi:[1,0]
	v_pk_mul_f32 v[70:71], v[14:15], v[202:203] op_sel_hi:[1,0]
	s_waitcnt lgkmcnt(0)
; template <int DQK, bool MASKED, int MODE, class MF>
; DI void attn_step(const bf16_t* sK, const bf16_t* sVt, const bf16x8 (&qf)[DQK / 16], f32x16& o0, f32x16& o1, float& m, float& l,
;                   float sc, const MF& mf, int lane, f32x16 (&s)[2], float invl, bool lanevalid = true) {
;     ...
;   for (int sub = 0; sub < 2; ++sub)
; #pragma unroll
;     for (int ks = 0; ks < DQK / 16; ++ks) kf[sub][ks] = *(const bf16x8*)(sK + (sub * 32 + pr) * KST + ks * 16 + 8 * h);
;   __builtin_amdgcn_sched_barrier(0);
; #pragma unroll
;   for (int q = 0; q < 16; ++q) { s[0][q] = 0.f; s[1][q] = 0.f; }
; #pragma unroll
;   for (int ks = 0; ks < DQK / 16; ++ks) {
;     s[0] = MFMA(kf[0][ks], qf[ks], s[0]);
;     s[1] = MFMA(kf[1][ks], qf[ks], s[1]);
;   }
;   bf16x8 vf[2][2][2];
;   if (MODE != 1) {
; #pragma unroll
;     for (int sub = 0; sub < 2; ++sub)
; #pragma unroll
;       for (int s2 = 0; s2 < 2; ++s2) {
;         vf[sub][s2][0] = *(const bf16x8*)(sVt + r * 72 + sub * 32 + s2 * 16 + 8 * h);
;         vf[sub][s2][1] = *(const bf16x8*)(sVt + (32 + r) * 72 + sub * 32 + s2 * 16 + 8 * h);
;       }
;     __builtin_amdgcn_sched_barrier(0);
;   }
;   float mxr = -3.0e38f;
; #pragma unroll
;   for (int sub = 0; sub < 2; ++sub)
; #pragma unroll
;     for (int q = 0; q < 16; ++q) {
;       if (MASKED) { const int kk = sub * 32 + 16 * (q >> 3) + 8 * h + (q & 7); s[sub][q] = mf(kk) ? s[sub][q] : -3.0e38f; }
;     ...
; #pragma unroll
;   for (int sub = 0; sub < 2; ++sub)
; #pragma unroll
;     for (int q = 0; q < 16; ++q) {
;       float pv = fexp2(__builtin_fmaf(s[sub][q], sc, -moff));
;       if (MASKED && MODE != 0) pv = (s[sub][q] > -1.0e38f) ? pv : 0.f;
;       if (MODE == 2) pv *= invl;
;       s[sub][q] = pv;
;       ps += pv;
;     }
;   if (MODE != 2) {
;     ps += shx(ps, 32);
;     l = l * alpha + ps;
;   }
;   if (MODE == 1) return;
;   if (MODE == 0) {
; #pragma unroll
;     for (int q = 0; q < 16; ++q) { o0[q] *= alpha; o1[q] *= alpha; }
;   }
; #pragma unroll
;   for (int sub = 0; sub < 2; ++sub)
; #pragma unroll
;     for (int s2 = 0; s2 < 2; ++s2) {
;       union { bf16x8 v; unsigned u[4]; } pb;
; #pragma unroll
;       for (int e = 0; e < 4; ++e) pb.u[e] = pack2(s[sub][8 * s2 + 2 * e], s[sub][8 * s2 + 2 * e + 1]);
;       o0 = MFMA(vf[sub][s2][0], pb.v, o0);
;       o1 = MFMA(vf[sub][s2][1], pb.v, o1);
;     }
	v_mfma_f32_32x32x16_bf16 v[34:49], v[198:201], v[194:197], v[34:49]
	v_mul_f32_e64 v68, v12, v202
	v_mul_f32_e64 v69, v13, v202
	v_mul_f32_e64 v66, v10, v202
	v_mul_f32_e64 v67, v11, v202
	v_mul_f32_e64 v64, v8, v202
	v_mul_f32_e64 v65, v9, v202
	v_pk_mul_f32 v[62:63], v[6:7], v[202:203] op_sel_hi:[1,0]
	v_pk_mul_f32 v[60:61], v[4:5], v[202:203] op_sel_hi:[1,0]
	v_pk_mul_f32 v[58:59], v[2:3], v[202:203] op_sel_hi:[1,0]
	v_fmamk_f32 v51, v51, 0x3e38aa3b, v191
	v_add_f32_e32 v50, v219, v218
	v_mfma_f32_32x32x16_bf16 v[58:73], v[130:133], v[194:197], v[58:73]
	v_cvt_pk_bf16_f32 v130, v203, v204
	v_cvt_pk_bf16_f32 v131, v205, v206
	v_cvt_pk_bf16_f32 v132, v207, v208
	v_cvt_pk_bf16_f32 v133, v209, v210
	v_add_f32_e32 v50, v220, v50
	v_fmamk_f32 v55, v55, 0x3e38aa3b, v191
	v_exp_f32_e32 v55, v55
	v_mfma_f32_32x32x16_bf16 v[34:49], v[126:129], v[130:133], v[34:49]
	v_exp_f32_e32 v126, v51
	v_fmamk_f32 v51, v52, 0x3e38aa3b, v191
	v_exp_f32_e32 v127, v51
	v_fmamk_f32 v51, v53, 0x3e38aa3b, v191
	v_exp_f32_e32 v128, v51
	v_add_f32_e32 v50, v126, v50
	v_add_f32_e32 v50, v127, v50
	v_mfma_f32_32x32x16_bf16 v[58:73], v[122:125], v[130:133], v[58:73]
	v_add_f32_e32 v122, v128, v50
	v_fmamk_f32 v50, v54, 0x3e38aa3b, v191
	v_exp_f32_e32 v54, v50
	v_fmamk_f32 v56, v56, 0x3e38aa3b, v191
	v_exp_f32_e32 v56, v56
	v_fmac_f32_e32 v191, 0x3e38aa3b, v57
	v_cvt_pk_bf16_f32 v50, v211, v212
	v_cvt_pk_bf16_f32 v51, v213, v214
	v_cvt_pk_bf16_f32 v52, v215, v216
	v_cvt_pk_bf16_f32 v53, v217, v219
	v_exp_f32_e32 v57, v191
	s_nop 0
	v_mfma_f32_32x32x16_bf16 v[34:49], v[118:121], v[50:53], v[34:49]
	v_add_f32_e32 v118, v54, v122
	v_cvt_pk_bf16_f32 v54, v54, v55
	v_mfma_f32_32x32x16_bf16 v[58:73], v[114:117], v[50:53], v[58:73]
	v_add_f32_e32 v50, v55, v118
	v_add_f32_e32 v50, v56, v50
	v_add_f32_e32 v50, v57, v50
	v_mov_b32_e32 v51, v50
	v_mov_b32_e32 v247, v50
	s_nop 1
	v_permlane32_swap_b32_e32 v51, v247
	v_xor_b32_e32 v51, v51, v247
	v_xor_b32_e32 v51, v51, v50
	v_cvt_pk_bf16_f32 v52, v220, v126
	v_cvt_pk_bf16_f32 v53, v127, v128
	v_cvt_pk_bf16_f32 v55, v56, v57
	s_waitcnt lgkmcnt(0)
	v_add_f32_e32 v50, v50, v51
	v_mfma_f32_32x32x16_bf16 v[34:49], v[110:113], v[52:55], v[34:49]
	v_fmac_f32_e32 v50, v185, v202
	v_mfma_f32_32x32x16_bf16 v[58:73], v[106:109], v[52:55], v[58:73]
.LBB0_1352:
	s_andn2_b64 vcc, exec, s[0:1]
	s_cbranch_vccnz .LBB0_1354
	v_add_u32_e32 v0, s5, v172
	s_nop 6
	ds_read_b128 v[34:37], v0
	s_nop 0
	ds_read_b128 v[66:69], v0 offset:32
	ds_read_b128 v[70:73], v0 offset:64
	ds_read_b128 v[106:109], v0 offset:96
	ds_read_b128 v[38:41], v0 offset:4608
	ds_read_b128 v[110:113], v0 offset:4640
	ds_read_b128 v[114:117], v0 offset:4672
	ds_read_b128 v[194:197], v0 offset:4704
	v_cmp_eq_u32_e32 vcc, 1, v190
	s_waitcnt lgkmcnt(7)
	v_mfma_f32_32x32x16_bf16 v[50:65], v[34:37], v[74:77], 0
	v_lshlrev_b32_e32 v0, 1, v171
	s_waitcnt lgkmcnt(3)
	v_mfma_f32_32x32x16_bf16 v[34:49], v[38:41], v[74:77], 0
	v_mfma_f32_32x32x16_bf16 v[50:65], v[66:69], v[78:81], v[50:65]
	s_waitcnt lgkmcnt(2)
	v_mfma_f32_32x32x16_bf16 v[34:49], v[110:113], v[78:81], v[34:49]
	v_mfma_f32_32x32x16_bf16 v[50:65], v[70:73], v[82:85], v[50:65]
	v_add3_u32 v70, v189, v175, v0
	v_add3_u32 v0, v189, v177, v0
	s_waitcnt lgkmcnt(1)
	v_mfma_f32_32x32x16_bf16 v[34:49], v[114:117], v[82:85], v[34:49]
	v_mfma_f32_32x32x16_bf16 v[50:65], v[106:109], v[86:89], v[50:65]
	ds_read_b128 v[66:69], v70 offset:9216
	ds_read_b128 v[126:129], v70 offset:9248
	ds_read_b128 v[130:133], v0 offset:9216
	ds_read_b128 v[122:125], v0 offset:9248
	ds_read_b128 v[118:121], v70 offset:9280
	ds_read_b128 v[110:113], v70 offset:9312
	ds_read_b128 v[114:117], v0 offset:9280
	ds_read_b128 v[106:109], v0 offset:9312
	s_waitcnt lgkmcnt(8)
	v_mfma_f32_32x32x16_bf16 v[34:49], v[194:197], v[86:89], v[34:49]
	v_add_u32_e32 v0, s44, v171
	v_cmp_le_u32_e64 s[0:1], v0, v136
	s_and_b64 s[0:1], vcc, s[0:1]
	v_add_u32_e32 v70, 2, v0
	v_cndmask_b32_e64 v50, v166, v50, s[0:1]
	v_cmp_lt_u32_e64 s[0:1], v0, v136
	s_and_b64 s[0:1], vcc, s[0:1]
	s_nop 0
	v_cndmask_b32_e64 v51, v166, v51, s[0:1]
	v_cmp_le_u32_e64 s[0:1], v70, v136
	s_and_b64 s[0:1], vcc, s[0:1]
	v_add_u32_e32 v70, 3, v0
	v_cndmask_b32_e64 v52, v166, v52, s[0:1]
	v_cmp_le_u32_e64 s[0:1], v70, v136
	s_and_b64 s[0:1], vcc, s[0:1]
	v_add_u32_e32 v70, 4, v0
	v_cndmask_b32_e64 v53, v166, v53, s[0:1]
	v_cmp_le_u32_e64 s[0:1], v70, v136
	s_and_b64 s[0:1], vcc, s[0:1]
	v_add_u32_e32 v70, 5, v0
	v_cndmask_b32_e64 v54, v166, v54, s[0:1]
	v_cmp_le_u32_e64 s[0:1], v70, v136
	s_and_b64 s[0:1], vcc, s[0:1]
	v_add_u32_e32 v70, 6, v0
	v_cndmask_b32_e64 v55, v166, v55, s[0:1]
	v_cmp_le_u32_e64 s[0:1], v70, v136
	v_add_u32_e32 v70, s44, v139
	s_and_b64 s[0:1], vcc, s[0:1]
	v_or_b32_e32 v71, 7, v70
	v_cndmask_b32_e64 v56, v166, v56, s[0:1]
	v_cmp_le_u32_e64 s[0:1], v71, v136
	s_and_b64 s[0:1], vcc, s[0:1]
	v_add_u32_e32 v71, 16, v0
	v_cndmask_b32_e64 v57, v166, v57, s[0:1]
	v_cmp_le_u32_e64 s[0:1], v71, v136
	s_and_b64 s[0:1], vcc, s[0:1]
	v_add_u32_e32 v71, 17, v0
	v_cndmask_b32_e64 v58, v166, v58, s[0:1]
	v_cmp_le_u32_e64 s[0:1], v71, v136
	s_and_b64 s[0:1], vcc, s[0:1]
	v_add_u32_e32 v71, 18, v0
	v_cndmask_b32_e64 v59, v166, v59, s[0:1]
	v_cmp_le_u32_e64 s[0:1], v71, v136
	s_and_b64 s[0:1], vcc, s[0:1]
	v_add_u32_e32 v71, 19, v0
	v_cndmask_b32_e64 v60, v166, v60, s[0:1]
	v_cmp_le_u32_e64 s[0:1], v71, v136
	s_and_b64 s[0:1], vcc, s[0:1]
	v_add_u32_e32 v71, 20, v0
	v_cndmask_b32_e64 v61, v166, v61, s[0:1]
	v_cmp_le_u32_e64 s[0:1], v71, v136
	s_and_b64 s[0:1], vcc, s[0:1]
	v_add_u32_e32 v71, 21, v0
	v_cndmask_b32_e64 v62, v166, v62, s[0:1]
	v_cmp_le_u32_e64 s[0:1], v71, v136
	s_and_b64 s[0:1], vcc, s[0:1]
; DI unsigned pack2(float a, float b) { f32x2_t v = {a, b}; bf16x2_t r = __builtin_convertvector(v, bf16x2_t); return __builtin_bit_cast(unsigned, r); }
; DI float fexp2(float x) { return __builtin_amdgcn_exp2f(x); }
; DI float shx(float v, int m) { return __shfl_xor(v, m, 64); }
; template <int DQK, bool MASKED, int MODE, class MF>
; DI void attn_step(const bf16_t* sK, const bf16_t* sVt, const bf16x8 (&qf)[DQK / 16], f32x16& o0, f32x16& o1, float& m, float& l,
;                   float sc, const MF& mf, int lane, f32x16 (&s)[2], float invl, bool lanevalid = true) {
;     ...
;   float mxr = -3.0e38f;
; #pragma unroll
;   for (int sub = 0; sub < 2; ++sub)
; #pragma unroll
;     for (int q = 0; q < 16; ++q) {
;       if (MASKED) { const int kk = sub * 32 + 16 * (q >> 3) + 8 * h + (q & 7); s[sub][q] = mf(kk) ? s[sub][q] : -3.0e38f; }
;       if (MODE != 2) mxr = fmaxf(mxr, s[sub][q]);
;     }
;   float alpha = 1.f;
;   if (MODE != 2) {
;     float mx = fmaxf(m, mxr * sc);
;     mx = fmaxf(mx, shx(mx, 32));
;     if (!MASKED) mx = lanevalid ? mx : m;
;     alpha = fexp2(m - mx);
;     m = mx;
;   }
;   const float moff = (!MASKED && !lanevalid) ? 1.0e30f : m;
;   float ps = 0.f;
; #pragma unroll
;   for (int sub = 0; sub < 2; ++sub)
; #pragma unroll
;     for (int q = 0; q < 16; ++q) {
;       float pv = fexp2(__builtin_fmaf(s[sub][q], sc, -moff));
;       if (MASKED && MODE != 0) pv = (s[sub][q] > -1.0e38f) ? pv : 0.f;
;       if (MODE == 2) pv *= invl;
;       s[sub][q] = pv;
;       ps += pv;
;     }
;   if (MODE != 2) {
;     ps += shx(ps, 32);
;     l = l * alpha + ps;
;   }
;   if (MODE == 1) return;
;   if (MODE == 0) {
; #pragma unroll
;     for (int q = 0; q < 16; ++q) { o0[q] *= alpha; o1[q] *= alpha; }
;   }
; #pragma unroll
;   for (int sub = 0; sub < 2; ++sub)
; #pragma unroll
;     for (int s2 = 0; s2 < 2; ++s2) {
;       union { bf16x8 v; unsigned u[4]; } pb;
; #pragma unroll
;       for (int e = 0; e < 4; ++e) pb.u[e] = pack2(s[sub][8 * s2 + 2 * e], s[sub][8 * s2 + 2 * e + 1]);
	v_add_u32_e32 v71, 22, v0
	v_cndmask_b32_e64 v63, v166, v63, s[0:1]
	v_cmp_le_u32_e64 s[0:1], v71, v136
	s_and_b64 s[0:1], vcc, s[0:1]
	v_or_b32_e32 v71, 23, v70
	v_cndmask_b32_e64 v64, v166, v64, s[0:1]
	v_cmp_le_u32_e64 s[0:1], v71, v136
	s_and_b64 s[0:1], vcc, s[0:1]
	v_add_u32_e32 v71, 32, v0
	v_cndmask_b32_e64 v65, v166, v65, s[0:1]
	v_cmp_le_u32_e64 s[0:1], v71, v136
	s_and_b64 s[0:1], vcc, s[0:1]
	v_add_u32_e32 v71, 33, v0
	v_cndmask_b32_e64 v34, v166, v34, s[0:1]
	v_cmp_le_u32_e64 s[0:1], v71, v136
	s_and_b64 s[0:1], vcc, s[0:1]
	v_add_u32_e32 v71, 34, v0
	v_cndmask_b32_e64 v35, v166, v35, s[0:1]
	v_cmp_le_u32_e64 s[0:1], v71, v136
	s_and_b64 s[0:1], vcc, s[0:1]
	v_add_u32_e32 v71, 35, v0
	v_cndmask_b32_e64 v36, v166, v36, s[0:1]
	v_cmp_le_u32_e64 s[0:1], v71, v136
	s_and_b64 s[0:1], vcc, s[0:1]
	v_add_u32_e32 v71, 36, v0
	v_cndmask_b32_e64 v37, v166, v37, s[0:1]
	v_cmp_le_u32_e64 s[0:1], v71, v136
	s_and_b64 s[0:1], vcc, s[0:1]
	v_add_u32_e32 v71, 37, v0
	v_cndmask_b32_e64 v38, v166, v38, s[0:1]
	v_cmp_le_u32_e64 s[0:1], v71, v136
	s_and_b64 s[0:1], vcc, s[0:1]
	v_add_u32_e32 v71, 38, v0
	v_cndmask_b32_e64 v39, v166, v39, s[0:1]
	v_cmp_le_u32_e64 s[0:1], v71, v136
	s_and_b64 s[0:1], vcc, s[0:1]
	v_or_b32_e32 v71, 39, v70
	v_cndmask_b32_e64 v40, v166, v40, s[0:1]
	v_cmp_le_u32_e64 s[0:1], v71, v136
	s_and_b64 s[0:1], vcc, s[0:1]
	v_add_u32_e32 v71, 48, v0
	v_cndmask_b32_e64 v41, v166, v41, s[0:1]
	v_cmp_le_u32_e64 s[0:1], v71, v136
	s_and_b64 s[0:1], vcc, s[0:1]
	v_add_u32_e32 v71, 49, v0
	v_cndmask_b32_e64 v42, v166, v42, s[0:1]
	v_cmp_le_u32_e64 s[0:1], v71, v136
	s_and_b64 s[0:1], vcc, s[0:1]
	s_nop 0
	v_cndmask_b32_e64 v189, v166, v43, s[0:1]
	v_add_u32_e32 v43, 50, v0
	v_cmp_le_u32_e64 s[0:1], v43, v136
	s_and_b64 s[0:1], vcc, s[0:1]
	v_add_u32_e32 v43, 51, v0
	v_cndmask_b32_e64 v190, v166, v44, s[0:1]
	v_cmp_le_u32_e64 s[0:1], v43, v136
	s_and_b64 s[0:1], vcc, s[0:1]
	v_add_u32_e32 v43, 52, v0
	v_cndmask_b32_e64 v191, v166, v45, s[0:1]
	v_cmp_le_u32_e64 s[0:1], v43, v136
	s_and_b64 s[0:1], vcc, s[0:1]
	v_add_u32_e32 v43, 53, v0
	v_cndmask_b32_e64 v194, v166, v46, s[0:1]
	v_cmp_le_u32_e64 s[0:1], v43, v136
	s_and_b64 s[0:1], vcc, s[0:1]
	v_add_u32_e32 v0, 54, v0
	v_cndmask_b32_e64 v195, v166, v47, s[0:1]
	v_cmp_le_u32_e64 s[0:1], v0, v136
	s_and_b64 s[0:1], vcc, s[0:1]
	v_or_b32_e32 v0, 55, v70
	v_cndmask_b32_e64 v196, v166, v48, s[0:1]
	v_cmp_le_u32_e64 s[0:1], v0, v136
	v_max3_f32 v0, v50, s8, v51
	v_max3_f32 v0, v0, v52, v53
	v_max3_f32 v0, v0, v54, v55
	v_max3_f32 v0, v0, v56, v57
	v_max3_f32 v0, v0, v58, v59
	v_max3_f32 v0, v0, v60, v61
	v_max3_f32 v0, v0, v62, v63
	v_max3_f32 v0, v0, v64, v65
	v_max3_f32 v0, v0, v34, v35
	v_max3_f32 v0, v0, v36, v37
	v_max3_f32 v0, v0, v38, v39
	v_max3_f32 v0, v0, v40, v41
	v_max3_f32 v0, v0, v42, v189
	s_and_b64 vcc, vcc, s[0:1]
	v_max3_f32 v0, v0, v190, v191
	v_cndmask_b32_e32 v197, v166, v49, vcc
	v_max3_f32 v0, v0, v194, v195
	v_max3_f32 v0, v0, v196, v197
	v_mul_f32_e32 v0, 0x3e38aa3b, v0
	v_max_f32_e32 v0, v188, v0
	v_mov_b32_e32 v43, v0
	v_mov_b32_e32 v247, v0
	s_nop 1
	v_permlane32_swap_b32_e32 v43, v247
	v_xor_b32_e32 v43, v43, v247
	v_xor_b32_e32 v43, v43, v0
	v_max_f32_e32 v43, v43, v43
	v_max_f32_e32 v0, v0, v43
	v_fma_f32 v43, v50, s33, -v0
	v_exp_f32_e32 v50, v43
	v_fma_f32 v43, v51, s33, -v0
	v_exp_f32_e32 v51, v43
	v_fma_f32 v43, v52, s33, -v0
	v_exp_f32_e32 v70, v43
	v_fma_f32 v45, v53, s33, -v0
	v_exp_f32_e32 v53, v45
	v_fma_f32 v45, v54, s33, -v0
	v_add_f32_e32 v44, 0, v50
	v_exp_f32_e32 v54, v45
	v_fma_f32 v45, v55, s33, -v0
	v_add_f32_e32 v44, v51, v44
	v_exp_f32_e32 v55, v45
	v_fma_f32 v45, v56, s33, -v0
	v_add_f32_e32 v44, v70, v44
	v_exp_f32_e32 v56, v45
	v_fma_f32 v45, v57, s33, -v0
	v_add_f32_e32 v44, v53, v44
	v_exp_f32_e32 v57, v45
	v_fma_f32 v45, v58, s33, -v0
	v_sub_f32_e32 v43, v141, v0
	v_add_f32_e32 v44, v54, v44
	v_exp_f32_e32 v141, v45
	v_fma_f32 v45, v59, s33, -v0
	v_add_f32_e32 v44, v55, v44
	v_exp_f32_e32 v188, v45
	v_fma_f32 v45, v60, s33, -v0
	v_add_f32_e32 v44, v56, v44
	v_exp_f32_e32 v198, v45
	v_fma_f32 v45, v61, s33, -v0
	v_add_f32_e32 v44, v57, v44
	v_exp_f32_e32 v199, v45
	v_fma_f32 v45, v62, s33, -v0
	v_add_f32_e32 v44, v141, v44
	v_exp_f32_e32 v200, v45
	v_fma_f32 v45, v63, s33, -v0
	v_add_f32_e32 v44, v188, v44
	v_exp_f32_e32 v201, v45
	v_fma_f32 v45, v64, s33, -v0
	v_add_f32_e32 v44, v198, v44
	v_exp_f32_e32 v202, v45
	v_fma_f32 v45, v65, s33, -v0
	v_add_f32_e32 v44, v199, v44
	v_exp_f32_e32 v203, v45
	v_fma_f32 v34, v34, s33, -v0
	v_add_f32_e32 v44, v200, v44
	v_exp_f32_e32 v204, v34
	v_fma_f32 v34, v35, s33, -v0
	v_add_f32_e32 v44, v201, v44
	v_exp_f32_e32 v205, v34
	v_fma_f32 v34, v36, s33, -v0
	v_add_f32_e32 v44, v202, v44
	v_exp_f32_e32 v206, v34
	v_fma_f32 v35, v37, s33, -v0
	v_add_f32_e32 v34, v203, v44
	v_exp_f32_e32 v207, v35
	v_fma_f32 v35, v38, s33, -v0
	v_add_f32_e32 v34, v204, v34
	v_exp_f32_e32 v208, v35
	v_fma_f32 v35, v39, s33, -v0
	v_add_f32_e32 v34, v205, v34
	v_exp_f32_e32 v209, v35
	v_fma_f32 v35, v40, s33, -v0
	v_add_f32_e32 v34, v206, v34
	v_exp_f32_e32 v210, v35
	v_add_f32_e32 v34, v207, v34
	v_add_f32_e32 v34, v208, v34
	v_exp_f32_e32 v52, v43
	v_add_f32_e32 v34, v209, v34
	v_add_f32_e32 v211, v210, v34
	v_fma_f32 v34, v41, s33, -v0
	v_exp_f32_e32 v212, v34
	v_fma_f32 v34, v42, s33, -v0
	v_exp_f32_e32 v213, v34
	v_pk_mul_f32 v[48:49], v[32:33], v[52:53] op_sel_hi:[1,0]
	v_pk_mul_f32 v[46:47], v[30:31], v[52:53] op_sel_hi:[1,0]
	v_pk_mul_f32 v[44:45], v[28:29], v[52:53] op_sel_hi:[1,0]
	v_pk_mul_f32 v[42:43], v[26:27], v[52:53] op_sel_hi:[1,0]
	v_pk_mul_f32 v[40:41], v[24:25], v[52:53] op_sel_hi:[1,0]
	v_pk_mul_f32 v[38:39], v[22:23], v[52:53] op_sel_hi:[1,0]
	v_pk_mul_f32 v[36:37], v[20:21], v[52:53] op_sel_hi:[1,0]
	v_pk_mul_f32 v[34:35], v[18:19], v[52:53] op_sel_hi:[1,0]
	v_pk_mul_f32 v[72:73], v[16:17], v[52:53] op_sel_hi:[1,0]
	v_cvt_pk_bf16_f32 v16, v50, v51
	v_cvt_pk_bf16_f32 v17, v70, v53
	v_cvt_pk_bf16_f32 v18, v54, v55
	v_cvt_pk_bf16_f32 v19, v56, v57
	v_pk_mul_f32 v[70:71], v[14:15], v[52:53] op_sel_hi:[1,0]
	v_pk_mul_f32 v[64:65], v[8:9], v[52:53] op_sel_hi:[1,0]
	s_waitcnt lgkmcnt(0)
; #define MFMA(a, b, c) __builtin_amdgcn_mfma_f32_32x32x16_bf16((a), (b), (c), 0, 0, 0)
; DI unsigned pack2(float a, float b) { f32x2_t v = {a, b}; bf16x2_t r = __builtin_convertvector(v, bf16x2_t); return __builtin_bit_cast(unsigned, r); }
; DI float fexp2(float x) { return __builtin_amdgcn_exp2f(x); }
; DI float shx(float v, int m) { return __shfl_xor(v, m, 64); }
; template <int DQK, bool MASKED, int MODE, class MF>
; DI void attn_step(const bf16_t* sK, const bf16_t* sVt, const bf16x8 (&qf)[DQK / 16], f32x16& o0, f32x16& o1, float& m, float& l,
;                   float sc, const MF& mf, int lane, f32x16 (&s)[2], float invl, bool lanevalid = true) {
;     ...
; #pragma unroll
;   for (int sub = 0; sub < 2; ++sub)
; #pragma unroll
;     for (int q = 0; q < 16; ++q) {
;       float pv = fexp2(__builtin_fmaf(s[sub][q], sc, -moff));
;       if (MASKED && MODE != 0) pv = (s[sub][q] > -1.0e38f) ? pv : 0.f;
;       if (MODE == 2) pv *= invl;
;       s[sub][q] = pv;
;       ps += pv;
;     }
;   if (MODE != 2) {
;     ps += shx(ps, 32);
;     l = l * alpha + ps;
;   }
;   if (MODE == 1) return;
;   if (MODE == 0) {
; #pragma unroll
;     for (int q = 0; q < 16; ++q) { o0[q] *= alpha; o1[q] *= alpha; }
;   }
; #pragma unroll
;   for (int sub = 0; sub < 2; ++sub)
; #pragma unroll
;     for (int s2 = 0; s2 < 2; ++s2) {
;       union { bf16x8 v; unsigned u[4]; } pb;
; #pragma unroll
;       for (int e = 0; e < 4; ++e) pb.u[e] = pack2(s[sub][8 * s2 + 2 * e], s[sub][8 * s2 + 2 * e + 1]);
;       o0 = MFMA(vf[sub][s2][0], pb.v, o0);
;       o1 = MFMA(vf[sub][s2][1], pb.v, o1);
;     }
	v_mfma_f32_32x32x16_bf16 v[34:49], v[66:69], v[16:19], v[34:49]
	v_mul_f32_e64 v68, v12, v52
	v_mul_f32_e64 v69, v13, v52
	v_mul_f32_e64 v66, v10, v52
	v_mul_f32_e64 v67, v11, v52
	v_mul_f32_e64 v62, v6, v52
	v_mul_f32_e64 v63, v7, v52
	v_pk_mul_f32 v[60:61], v[4:5], v[52:53] op_sel_hi:[1,0]
	v_pk_mul_f32 v[58:59], v[2:3], v[52:53] op_sel_hi:[1,0]
	v_add_f32_e32 v2, v212, v211
	v_add_f32_e32 v6, v213, v2
	v_mfma_f32_32x32x16_bf16 v[58:73], v[130:133], v[16:19], v[58:73]
	v_cvt_pk_bf16_f32 v2, v141, v188
	v_cvt_pk_bf16_f32 v3, v198, v199
	v_cvt_pk_bf16_f32 v4, v200, v201
	v_cvt_pk_bf16_f32 v5, v202, v203
	v_fma_f32 v7, v189, s33, -v0
	v_exp_f32_e32 v7, v7
	v_fma_f32 v8, v190, s33, -v0
	v_mfma_f32_32x32x16_bf16 v[34:49], v[126:129], v[2:5], v[34:49]
	v_exp_f32_e32 v8, v8
	v_fma_f32 v9, v191, s33, -v0
	v_exp_f32_e32 v9, v9
	v_fma_f32 v11, v195, s33, -v0
	v_add_f32_e32 v6, v7, v6
	v_exp_f32_e32 v11, v11
	v_fma_f32 v12, v196, s33, -v0
	v_mfma_f32_32x32x16_bf16 v[58:73], v[122:125], v[2:5], v[58:73]
	v_fma_f32 v2, v194, s33, -v0
	v_exp_f32_e32 v10, v2
	v_cvt_pk_bf16_f32 v2, v204, v205
	v_cvt_pk_bf16_f32 v3, v206, v207
	v_cvt_pk_bf16_f32 v4, v208, v209
	v_cvt_pk_bf16_f32 v5, v210, v212
	v_add_f32_e32 v6, v8, v6
	v_exp_f32_e32 v12, v12
	v_mfma_f32_32x32x16_bf16 v[34:49], v[118:121], v[2:5], v[34:49]
	v_fma_f32 v13, v197, s33, -v0
	v_add_f32_e32 v6, v9, v6
	v_exp_f32_e32 v13, v13
	v_add_f32_e32 v6, v10, v6
	v_mfma_f32_32x32x16_bf16 v[58:73], v[114:117], v[2:5], v[58:73]
	v_add_f32_e32 v2, v11, v6
	v_add_f32_e32 v2, v12, v2
	v_add_f32_e32 v6, v13, v2
	v_cvt_pk_bf16_f32 v2, v213, v7
	v_cvt_pk_bf16_f32 v3, v8, v9
	v_cvt_pk_bf16_f32 v4, v10, v11
	v_cvt_pk_bf16_f32 v5, v12, v13
	v_mov_b32_e32 v7, v6
	v_mov_b32_e32 v247, v6
	s_nop 1
	v_permlane32_swap_b32_e32 v7, v247
	v_xor_b32_e32 v7, v7, v247
	v_xor_b32_e32 v7, v7, v6
	s_waitcnt lgkmcnt(0)
	v_add_f32_e32 v50, v6, v7
	v_mfma_f32_32x32x16_bf16 v[34:49], v[110:113], v[2:5], v[34:49]
	v_fmac_f32_e32 v50, v185, v52
	v_mfma_f32_32x32x16_bf16 v[58:73], v[106:109], v[2:5], v[58:73]

; #define MFMA(a, b, c) __builtin_amdgcn_mfma_f32_32x32x16_bf16((a), (b), (c), 0, 0, 0)
; template <int DQK, bool MASKED, int MODE, class MF>
; DI void attn_step(const bf16_t* sK, const bf16_t* sVt, const bf16x8 (&qf)[DQK / 16], f32x16& o0, f32x16& o1, float& m, float& l,
;                   float sc, const MF& mf, int lane, f32x16 (&s)[2], float invl, bool lanevalid = true) {
;     ...
;   bf16x8 kf[2][DQK / 16];
; #pragma unroll
;   for (int sub = 0; sub < 2; ++sub)
; #pragma unroll
;     for (int ks = 0; ks < DQK / 16; ++ks) kf[sub][ks] = *(const bf16x8*)(sK + (sub * 32 + pr) * KST + ks * 16 + 8 * h);
;   __builtin_amdgcn_sched_barrier(0);
; #pragma unroll
;   for (int q = 0; q < 16; ++q) { s[0][q] = 0.f; s[1][q] = 0.f; }
; #pragma unroll
;   for (int ks = 0; ks < DQK / 16; ++ks) {
;     s[0] = MFMA(kf[0][ks], qf[ks], s[0]);
;     s[1] = MFMA(kf[1][ks], qf[ks], s[1]);
;   }
;   bf16x8 vf[2][2][2];
;   if (MODE != 1) {
; #pragma unroll
;     for (int sub = 0; sub < 2; ++sub)
; #pragma unroll
;       for (int s2 = 0; s2 < 2; ++s2) {
;         vf[sub][s2][0] = *(const bf16x8*)(sVt + r * 72 + sub * 32 + s2 * 16 + 8 * h);
;         vf[sub][s2][1] = *(const bf16x8*)(sVt + (32 + r) * 72 + sub * 32 + s2 * 16 + 8 * h);
;       }
;     __builtin_amdgcn_sched_barrier(0);
;   }
;   float mxr = -3.0e38f;
; #pragma unroll
;   for (int sub = 0; sub < 2; ++sub)
; #pragma unroll
;     for (int q = 0; q < 16; ++q) {
;       if (MASKED) { const int kk = sub * 32 + 16 * (q >> 3) + 8 * h + (q & 7); s[sub][q] = mf(kk) ? s[sub][q] : -3.0e38f; }
; DI void phase_attn_nsa(const Params& P, bf16_t* og, unsigned char* smem, int L, int G) {
;     ...
;         auto mf = [&](int kk) { const int key = key0 + kk; return key <= t && key > t - 512; };
;         if (key0 + 63 > t0 || key0 <= t0 + 31 - 512) attn_step<64, true, 0>(sK + cb * KVB64, sVt + cb * KVB64, qf, o0, o1, m, l, sc, mf, lane, s, 0.f);
;         else attn_step<64, false, 0>(sK + cb * KVB64, sVt + cb * KVB64, qf, o0, o1, m, l, sc, mf, lane, s, 0.f);
.LBB0_1365:
	s_add_i32 s0, s44, 63
	s_cmp_le_u32 s0, s46
	s_cselect_b64 s[0:1], -1, 0
	s_cmp_gt_i32 s44, s3
	s_cselect_b64 s[6:7], -1, 0
	s_and_b64 s[6:7], s[0:1], s[6:7]
	s_mulk_i32 s5, 0x2400
	v_lshl_add_u32 v98, s5, 1, v153
	s_mov_b64 s[0:1], -1
	s_and_b64 vcc, exec, s[6:7]
	v_max_f32_e32 v149, v148, v148
	s_cbranch_vccnz .LBB0_1367
	v_lshl_add_u32 v0, s5, 1, v172
	ds_read_b128 v[2:5], v0
	ds_read_b128 v[34:37], v0 offset:32
	ds_read_b128 v[38:41], v0 offset:64
	ds_read_b128 v[58:61], v0 offset:96
	ds_read_b128 v[6:9], v0 offset:4608
	ds_read_b128 v[62:65], v0 offset:4640
	ds_read_b128 v[66:69], v0 offset:4672
	ds_read_b128 v[184:187], v0 offset:4704
	s_waitcnt lgkmcnt(7)
	v_mfma_f32_32x32x16_bf16 v[18:33], v[2:5], v[74:77], 0
	v_lshlrev_b32_e32 v0, 1, v171
	s_waitcnt lgkmcnt(3)
	v_mfma_f32_32x32x16_bf16 v[2:17], v[6:9], v[74:77], 0
	v_mfma_f32_32x32x16_bf16 v[18:33], v[34:37], v[78:81], v[18:33]
	v_add3_u32 v34, v98, v175, v0
	v_add3_u32 v0, v98, v177, v0
	s_waitcnt lgkmcnt(2)
	v_mfma_f32_32x32x16_bf16 v[2:17], v[62:65], v[78:81], v[2:17]
	v_mfma_f32_32x32x16_bf16 v[18:33], v[38:41], v[82:85], v[18:33]
	s_waitcnt lgkmcnt(1)
	v_mfma_f32_32x32x16_bf16 v[2:17], v[66:69], v[82:85], v[2:17]
	v_mfma_f32_32x32x16_bf16 v[18:33], v[58:61], v[86:89], v[18:33]
	ds_read_b128 v[94:97], v34 offset:9216
	ds_read_b128 v[70:73], v34 offset:9248
	ds_read_b128 v[90:93], v0 offset:9216
	ds_read_b128 v[66:69], v0 offset:9248
	ds_read_b128 v[62:65], v34 offset:9280
	ds_read_b128 v[38:41], v34 offset:9312
	ds_read_b128 v[58:61], v0 offset:9280
	ds_read_b128 v[34:37], v0 offset:9312
	s_waitcnt lgkmcnt(8)
	v_mfma_f32_32x32x16_bf16 v[2:17], v[184:187], v[86:89], v[2:17]
	v_add_u32_e32 v0, s44, v171
	v_cmp_le_u32_e32 vcc, v0, v136
	v_cmp_gt_i32_e64 s[0:1], v0, v146
	s_and_b64 vcc, vcc, s[0:1]
	v_cndmask_b32_e32 v18, v166, v18, vcc
	v_cmp_lt_u32_e32 vcc, v0, v136
	v_cmp_ge_i32_e64 s[0:1], v0, v146
	s_and_b64 vcc, vcc, s[0:1]
	v_add_u32_e32 v99, 2, v0
	v_cndmask_b32_e32 v19, v166, v19, vcc
	v_cmp_le_u32_e32 vcc, v99, v136
	v_cmp_gt_i32_e64 s[0:1], v99, v146
	s_and_b64 vcc, vcc, s[0:1]
	v_add_u32_e32 v99, 3, v0
	v_cndmask_b32_e32 v20, v166, v20, vcc
	v_cmp_le_u32_e32 vcc, v99, v136
	v_cmp_gt_i32_e64 s[0:1], v99, v146
	s_and_b64 vcc, vcc, s[0:1]
	v_add_u32_e32 v99, 4, v0
	v_cndmask_b32_e32 v21, v166, v21, vcc
	v_cmp_le_u32_e32 vcc, v99, v136
	v_cmp_gt_i32_e64 s[0:1], v99, v146
	s_and_b64 vcc, vcc, s[0:1]
	v_add_u32_e32 v99, 5, v0
	v_cndmask_b32_e32 v22, v166, v22, vcc
	v_cmp_le_u32_e32 vcc, v99, v136
	v_cmp_gt_i32_e64 s[0:1], v99, v146
	s_and_b64 vcc, vcc, s[0:1]
	v_add_u32_e32 v99, 6, v0
	v_cndmask_b32_e32 v23, v166, v23, vcc
	v_cmp_le_u32_e32 vcc, v99, v136
	v_cmp_gt_i32_e64 s[0:1], v99, v146
	v_add_u32_e32 v99, s44, v139
	s_and_b64 vcc, vcc, s[0:1]
	v_or_b32_e32 v100, 7, v99
	v_cndmask_b32_e32 v24, v166, v24, vcc
	v_cmp_le_u32_e32 vcc, v100, v136
	v_cmp_gt_i32_e64 s[0:1], v100, v146
	s_and_b64 vcc, vcc, s[0:1]
	v_add_u32_e32 v100, 16, v0
	v_cndmask_b32_e32 v25, v166, v25, vcc
	v_cmp_le_u32_e32 vcc, v100, v136
	v_cmp_gt_i32_e64 s[0:1], v100, v146
	s_and_b64 vcc, vcc, s[0:1]
	v_add_u32_e32 v100, 17, v0
	v_cndmask_b32_e32 v26, v166, v26, vcc
	v_cmp_le_u32_e32 vcc, v100, v136
	v_cmp_gt_i32_e64 s[0:1], v100, v146
	s_and_b64 vcc, vcc, s[0:1]
	v_add_u32_e32 v100, 18, v0
	v_cndmask_b32_e32 v27, v166, v27, vcc
	v_cmp_le_u32_e32 vcc, v100, v136
	v_cmp_gt_i32_e64 s[0:1], v100, v146
	s_and_b64 vcc, vcc, s[0:1]
	v_add_u32_e32 v100, 19, v0
	v_cndmask_b32_e32 v28, v166, v28, vcc
	v_cmp_le_u32_e32 vcc, v100, v136
	v_cmp_gt_i32_e64 s[0:1], v100, v146
	s_and_b64 vcc, vcc, s[0:1]
	v_add_u32_e32 v100, 20, v0
	v_cndmask_b32_e32 v29, v166, v29, vcc
	v_cmp_le_u32_e32 vcc, v100, v136
	v_cmp_gt_i32_e64 s[0:1], v100, v146
	s_and_b64 vcc, vcc, s[0:1]
	v_add_u32_e32 v100, 21, v0
	v_cndmask_b32_e32 v30, v166, v30, vcc
	v_cmp_le_u32_e32 vcc, v100, v136
	v_cmp_gt_i32_e64 s[0:1], v100, v146
	s_and_b64 vcc, vcc, s[0:1]
	v_add_u32_e32 v100, 22, v0
	v_cndmask_b32_e32 v31, v166, v31, vcc
	v_cmp_le_u32_e32 vcc, v100, v136
	v_cmp_gt_i32_e64 s[0:1], v100, v146
	s_and_b64 vcc, vcc, s[0:1]
	v_or_b32_e32 v100, 23, v99
	v_cndmask_b32_e32 v32, v166, v32, vcc
	v_cmp_le_u32_e32 vcc, v100, v136
	v_cmp_gt_i32_e64 s[0:1], v100, v146
	s_and_b64 vcc, vcc, s[0:1]
	v_add_u32_e32 v100, 32, v0
	v_cndmask_b32_e32 v33, v166, v33, vcc
	v_cmp_le_u32_e32 vcc, v100, v136
	v_cmp_gt_i32_e64 s[0:1], v100, v146
	s_and_b64 vcc, vcc, s[0:1]
	v_add_u32_e32 v100, 33, v0
	v_cndmask_b32_e32 v2, v166, v2, vcc
	v_cmp_le_u32_e32 vcc, v100, v136
	v_cmp_gt_i32_e64 s[0:1], v100, v146
	s_and_b64 vcc, vcc, s[0:1]
	v_add_u32_e32 v100, 34, v0
	v_cndmask_b32_e32 v3, v166, v3, vcc
	v_cmp_le_u32_e32 vcc, v100, v136
	v_cmp_gt_i32_e64 s[0:1], v100, v146
	s_and_b64 vcc, vcc, s[0:1]
	v_add_u32_e32 v100, 35, v0
	v_cndmask_b32_e32 v4, v166, v4, vcc
	v_cmp_le_u32_e32 vcc, v100, v136
	v_cmp_gt_i32_e64 s[0:1], v100, v146
	s_and_b64 vcc, vcc, s[0:1]
	v_add_u32_e32 v100, 36, v0
	v_cndmask_b32_e32 v5, v166, v5, vcc
	v_cmp_le_u32_e32 vcc, v100, v136
	v_cmp_gt_i32_e64 s[0:1], v100, v146
	s_and_b64 vcc, vcc, s[0:1]
	v_add_u32_e32 v100, 37, v0
	v_cndmask_b32_e32 v6, v166, v6, vcc
	v_cmp_le_u32_e32 vcc, v100, v136
	v_cmp_gt_i32_e64 s[0:1], v100, v146
	s_and_b64 vcc, vcc, s[0:1]
	v_add_u32_e32 v100, 38, v0
	v_cndmask_b32_e32 v7, v166, v7, vcc
	v_cmp_le_u32_e32 vcc, v100, v136
	v_cmp_gt_i32_e64 s[0:1], v100, v146
	s_and_b64 vcc, vcc, s[0:1]
	v_or_b32_e32 v100, 39, v99
	v_cndmask_b32_e32 v8, v166, v8, vcc
	v_cmp_le_u32_e32 vcc, v100, v136
	v_cmp_gt_i32_e64 s[0:1], v100, v146
	s_and_b64 vcc, vcc, s[0:1]
	v_add_u32_e32 v100, 48, v0
	v_cndmask_b32_e32 v9, v166, v9, vcc
; DI float fexp2(float x) { return __builtin_amdgcn_exp2f(x); }
; DI float shx(float v, int m) { return __shfl_xor(v, m, 64); }
; template <int DQK, bool MASKED, int MODE, class MF>
; DI void attn_step(const bf16_t* sK, const bf16_t* sVt, const bf16x8 (&qf)[DQK / 16], f32x16& o0, f32x16& o1, float& m, float& l,
;                   float sc, const MF& mf, int lane, f32x16 (&s)[2], float invl, bool lanevalid = true) {
;     ...
;   float mxr = -3.0e38f;
; #pragma unroll
;   for (int sub = 0; sub < 2; ++sub)
; #pragma unroll
;     for (int q = 0; q < 16; ++q) {
;       if (MASKED) { const int kk = sub * 32 + 16 * (q >> 3) + 8 * h + (q & 7); s[sub][q] = mf(kk) ? s[sub][q] : -3.0e38f; }
;       if (MODE != 2) mxr = fmaxf(mxr, s[sub][q]);
;     }
;   float alpha = 1.f;
;   if (MODE != 2) {
;     float mx = fmaxf(m, mxr * sc);
;     mx = fmaxf(mx, shx(mx, 32));
;     if (!MASKED) mx = lanevalid ? mx : m;
;     alpha = fexp2(m - mx);
;     m = mx;
;   }
;   const float moff = (!MASKED && !lanevalid) ? 1.0e30f : m;
;   float ps = 0.f;
; #pragma unroll
;   for (int sub = 0; sub < 2; ++sub)
; #pragma unroll
;     for (int q = 0; q < 16; ++q) {
;       float pv = fexp2(__builtin_fmaf(s[sub][q], sc, -moff));
;       if (MASKED && MODE != 0) pv = (s[sub][q] > -1.0e38f) ? pv : 0.f;
;       if (MODE == 2) pv *= invl;
;       s[sub][q] = pv;
;       ps += pv;
;     }
;   if (MODE != 2) {
;     ps += shx(ps, 32);
;     l = l * alpha + ps;
;   }
;   if (MODE == 1) return;
;   if (MODE == 0) {
; #pragma unroll
;     for (int q = 0; q < 16; ++q) { o0[q] *= alpha; o1[q] *= alpha; }
	v_cmp_le_u32_e32 vcc, v100, v136
	v_cmp_gt_i32_e64 s[0:1], v100, v146
	s_and_b64 vcc, vcc, s[0:1]
	v_add_u32_e32 v100, 49, v0
	v_cndmask_b32_e32 v10, v166, v10, vcc
	v_cmp_le_u32_e32 vcc, v100, v136
	v_cmp_gt_i32_e64 s[0:1], v100, v146
	s_and_b64 vcc, vcc, s[0:1]
	v_cndmask_b32_e32 v101, v166, v11, vcc
	v_add_u32_e32 v11, 50, v0
	v_cmp_le_u32_e32 vcc, v11, v136
	v_cmp_gt_i32_e64 s[0:1], v11, v146
	s_and_b64 vcc, vcc, s[0:1]
	v_add_u32_e32 v11, 51, v0
	v_cndmask_b32_e32 v150, v166, v12, vcc
	v_cmp_le_u32_e32 vcc, v11, v136
	v_cmp_gt_i32_e64 s[0:1], v11, v146
	s_and_b64 vcc, vcc, s[0:1]
	v_add_u32_e32 v11, 52, v0
	v_cndmask_b32_e32 v151, v166, v13, vcc
	v_cmp_le_u32_e32 vcc, v11, v136
	v_cmp_gt_i32_e64 s[0:1], v11, v146
	s_and_b64 vcc, vcc, s[0:1]
	v_add_u32_e32 v11, 53, v0
	v_cndmask_b32_e32 v174, v166, v14, vcc
	v_cmp_le_u32_e32 vcc, v11, v136
	v_cmp_gt_i32_e64 s[0:1], v11, v146
	s_and_b64 vcc, vcc, s[0:1]
	v_add_u32_e32 v0, 54, v0
	v_cndmask_b32_e32 v178, v166, v15, vcc
	v_cmp_le_u32_e32 vcc, v0, v136
	v_cmp_gt_i32_e64 s[0:1], v0, v146
	s_and_b64 vcc, vcc, s[0:1]
	v_or_b32_e32 v0, 55, v99
	v_cndmask_b32_e32 v183, v166, v16, vcc
	v_cmp_le_u32_e32 vcc, v0, v136
	v_cmp_gt_i32_e64 s[0:1], v0, v146
	v_max3_f32 v0, v18, s8, v19
	v_max3_f32 v0, v0, v20, v21
	v_max3_f32 v0, v0, v22, v23
	v_max3_f32 v0, v0, v24, v25
	v_max3_f32 v0, v0, v26, v27
	v_max3_f32 v0, v0, v28, v29
	v_max3_f32 v0, v0, v30, v31
	v_max3_f32 v0, v0, v32, v33
	v_max3_f32 v0, v0, v2, v3
	v_max3_f32 v0, v0, v4, v5
	v_max3_f32 v0, v0, v6, v7
	v_max3_f32 v0, v0, v8, v9
	v_max3_f32 v0, v0, v10, v101
	s_and_b64 vcc, vcc, s[0:1]
	v_max3_f32 v0, v0, v150, v151
	v_cndmask_b32_e32 v99, v166, v17, vcc
	v_max3_f32 v0, v0, v174, v178
	v_max3_f32 v0, v0, v183, v99
	v_mul_f32_e32 v0, 0x3e38aa3b, v0
	v_max_f32_e32 v0, v149, v0
	v_mov_b32_e32 v11, v0
	v_mov_b32_e32 v247, v0
	s_nop 1
	v_permlane32_swap_b32_e32 v11, v247
	v_xor_b32_e32 v11, v11, v247
	v_xor_b32_e32 v11, v11, v0
	s_mov_b64 s[0:1], 0
	v_max_f32_e32 v11, v11, v11
	v_max_f32_e32 v0, v0, v11
	v_fma_f32 v11, v18, s33, -v0
	v_exp_f32_e32 v18, v11
	v_fma_f32 v11, v19, s33, -v0
	v_exp_f32_e32 v19, v11
	v_fma_f32 v11, v20, s33, -v0
	v_exp_f32_e32 v20, v11
	v_fma_f32 v13, v21, s33, -v0
	v_exp_f32_e32 v21, v13
	v_fma_f32 v13, v22, s33, -v0
	v_add_f32_e32 v12, 0, v18
	v_exp_f32_e32 v22, v13
	v_fma_f32 v13, v23, s33, -v0
	v_add_f32_e32 v12, v19, v12
	v_exp_f32_e32 v23, v13
	v_fma_f32 v13, v24, s33, -v0
	v_add_f32_e32 v12, v20, v12
	v_exp_f32_e32 v24, v13
	v_fma_f32 v13, v25, s33, -v0
	v_add_f32_e32 v12, v21, v12
	v_exp_f32_e32 v25, v13
	v_fma_f32 v13, v26, s33, -v0
	v_add_f32_e32 v12, v22, v12
	v_exp_f32_e32 v188, v13
	v_fma_f32 v13, v27, s33, -v0
	v_add_f32_e32 v12, v23, v12
	v_exp_f32_e32 v189, v13
	v_fma_f32 v13, v28, s33, -v0
	v_add_f32_e32 v12, v24, v12
	v_exp_f32_e32 v190, v13
	v_fma_f32 v13, v29, s33, -v0
	v_add_f32_e32 v12, v25, v12
	v_exp_f32_e32 v191, v13
	v_fma_f32 v13, v30, s33, -v0
	v_add_f32_e32 v12, v188, v12
	v_exp_f32_e32 v194, v13
	v_fma_f32 v13, v31, s33, -v0
	v_add_f32_e32 v12, v189, v12
	v_exp_f32_e32 v195, v13
	v_fma_f32 v13, v32, s33, -v0
	v_add_f32_e32 v12, v190, v12
	v_exp_f32_e32 v196, v13
	v_fma_f32 v13, v33, s33, -v0
	v_add_f32_e32 v12, v191, v12
	v_exp_f32_e32 v197, v13
	v_fma_f32 v2, v2, s33, -v0
	v_add_f32_e32 v12, v194, v12
	v_exp_f32_e32 v198, v2
	v_fma_f32 v2, v3, s33, -v0
	v_add_f32_e32 v12, v195, v12
	v_exp_f32_e32 v199, v2
	v_fma_f32 v2, v4, s33, -v0
	v_add_f32_e32 v12, v196, v12
	v_exp_f32_e32 v200, v2
	v_fma_f32 v3, v5, s33, -v0
	v_add_f32_e32 v2, v197, v12
	v_exp_f32_e32 v201, v3
	v_fma_f32 v3, v6, s33, -v0
	v_add_f32_e32 v2, v198, v2
	v_exp_f32_e32 v202, v3
	v_fma_f32 v3, v7, s33, -v0
	v_add_f32_e32 v2, v199, v2
	v_exp_f32_e32 v203, v3
	v_fma_f32 v3, v8, s33, -v0
	v_add_f32_e32 v2, v200, v2
	v_exp_f32_e32 v204, v3
	v_sub_f32_e32 v11, v148, v0
	v_add_f32_e32 v2, v201, v2
	v_add_f32_e32 v2, v202, v2
	v_exp_f32_e32 v100, v11
	v_add_f32_e32 v2, v203, v2
	v_add_f32_e32 v205, v204, v2
	v_fma_f32 v2, v9, s33, -v0
	v_exp_f32_e32 v206, v2
	v_fma_f32 v2, v10, s33, -v0
	v_exp_f32_e32 v207, v2
	v_pk_mul_f32 v[16:17], v[144:145], v[100:101] op_sel_hi:[1,0]
	v_pk_mul_f32 v[14:15], v[140:141], v[100:101] op_sel_hi:[1,0]
	v_pk_mul_f32 v[12:13], v[132:133], v[100:101] op_sel_hi:[1,0]
	v_pk_mul_f32 v[10:11], v[130:131], v[100:101] op_sel_hi:[1,0]
	v_pk_mul_f32 v[8:9], v[128:129], v[100:101] op_sel_hi:[1,0]
	v_pk_mul_f32 v[6:7], v[126:127], v[100:101] op_sel_hi:[1,0]
	v_pk_mul_f32 v[4:5], v[124:125], v[100:101] op_sel_hi:[1,0]
	v_pk_mul_f32 v[2:3], v[122:123], v[100:101] op_sel_hi:[1,0]
	v_pk_mul_f32 v[32:33], v[142:143], v[100:101] op_sel_hi:[1,0]
	v_cvt_pk_bf16_f32 v184, v18, v19
	v_cvt_pk_bf16_f32 v185, v20, v21
	v_cvt_pk_bf16_f32 v186, v22, v23
	v_cvt_pk_bf16_f32 v187, v24, v25
	v_pk_mul_f32 v[30:31], v[120:121], v[100:101] op_sel_hi:[1,0]
	v_pk_mul_f32 v[28:29], v[118:119], v[100:101] op_sel_hi:[1,0]
	v_pk_mul_f32 v[26:27], v[116:117], v[100:101] op_sel_hi:[1,0]
	v_pk_mul_f32 v[24:25], v[114:115], v[100:101] op_sel_hi:[1,0]
	v_pk_mul_f32 v[22:23], v[112:113], v[100:101] op_sel_hi:[1,0]
	v_pk_mul_f32 v[20:21], v[110:111], v[100:101] op_sel_hi:[1,0]
	v_pk_mul_f32 v[18:19], v[108:109], v[100:101] op_sel_hi:[1,0]
	s_waitcnt lgkmcnt(0)
; #define MFMA(a, b, c) __builtin_amdgcn_mfma_f32_32x32x16_bf16((a), (b), (c), 0, 0, 0)
; DI unsigned pack2(float a, float b) { f32x2_t v = {a, b}; bf16x2_t r = __builtin_convertvector(v, bf16x2_t); return __builtin_bit_cast(unsigned, r); }
; DI float shx(float v, int m) { return __shfl_xor(v, m, 64); }
; template <int DQK, bool MASKED, int MODE, class MF>
; DI void attn_step(const bf16_t* sK, const bf16_t* sVt, const bf16x8 (&qf)[DQK / 16], f32x16& o0, f32x16& o1, float& m, float& l,
;                   float sc, const MF& mf, int lane, f32x16 (&s)[2], float invl, bool lanevalid = true) {
;     ...
;   bf16x8 kf[2][DQK / 16];
; #pragma unroll
;   for (int sub = 0; sub < 2; ++sub)
; #pragma unroll
;     for (int ks = 0; ks < DQK / 16; ++ks) kf[sub][ks] = *(const bf16x8*)(sK + (sub * 32 + pr) * KST + ks * 16 + 8 * h);
;   __builtin_amdgcn_sched_barrier(0);
; #pragma unroll
;   for (int q = 0; q < 16; ++q) { s[0][q] = 0.f; s[1][q] = 0.f; }
; #pragma unroll
;   for (int ks = 0; ks < DQK / 16; ++ks) {
;     s[0] = MFMA(kf[0][ks], qf[ks], s[0]);
;     s[1] = MFMA(kf[1][ks], qf[ks], s[1]);
;   }
;     ...
;   if (MODE != 2) {
;     ps += shx(ps, 32);
;     l = l * alpha + ps;
;   }
;   if (MODE == 1) return;
;   if (MODE == 0) {
; #pragma unroll
;     for (int q = 0; q < 16; ++q) { o0[q] *= alpha; o1[q] *= alpha; }
;   }
; #pragma unroll
;   for (int sub = 0; sub < 2; ++sub)
; #pragma unroll
;     for (int s2 = 0; s2 < 2; ++s2) {
;       union { bf16x8 v; unsigned u[4]; } pb;
; #pragma unroll
;       for (int e = 0; e < 4; ++e) pb.u[e] = pack2(s[sub][8 * s2 + 2 * e], s[sub][8 * s2 + 2 * e + 1]);
;       o0 = MFMA(vf[sub][s2][0], pb.v, o0);
;       o1 = MFMA(vf[sub][s2][1], pb.v, o1);
;     }
	v_mfma_f32_32x32x16_bf16 v[2:17], v[94:97], v[184:187], v[2:17]
	v_fma_f32 v95, v101, s33, -v0
	v_mfma_f32_32x32x16_bf16 v[18:33], v[90:93], v[184:187], v[18:33]
	v_add_f32_e32 v90, v206, v205
	v_add_f32_e32 v94, v207, v90
	v_cvt_pk_bf16_f32 v90, v188, v189
	v_cvt_pk_bf16_f32 v91, v190, v191
	v_cvt_pk_bf16_f32 v92, v194, v195
	v_cvt_pk_bf16_f32 v93, v196, v197
	s_nop 1
	v_mfma_f32_32x32x16_bf16 v[2:17], v[70:73], v[90:93], v[2:17]
	v_exp_f32_e32 v70, v95
	v_fma_f32 v71, v150, s33, -v0
	v_exp_f32_e32 v71, v71
	v_fma_f32 v72, v151, s33, -v0
	v_exp_f32_e32 v72, v72
	v_add_f32_e32 v73, v70, v94
	v_add_f32_e32 v73, v71, v73
	v_mfma_f32_32x32x16_bf16 v[18:33], v[66:69], v[90:93], v[18:33]
	v_fma_f32 v66, v174, s33, -v0
	v_exp_f32_e32 v90, v66
	v_cvt_pk_bf16_f32 v66, v198, v199
	v_cvt_pk_bf16_f32 v67, v200, v201
	v_cvt_pk_bf16_f32 v68, v202, v203
	v_cvt_pk_bf16_f32 v69, v204, v206
	v_add_f32_e32 v73, v72, v73
	s_nop 0
	v_mfma_f32_32x32x16_bf16 v[2:17], v[62:65], v[66:69], v[2:17]
	v_fma_f32 v63, v178, s33, -v0
	v_exp_f32_e32 v63, v63
	v_fma_f32 v64, v183, s33, -v0
	v_exp_f32_e32 v64, v64
	v_fma_f32 v65, v99, s33, -v0
	v_exp_f32_e32 v65, v65
	v_add_f32_e32 v62, v90, v73
	v_mfma_f32_32x32x16_bf16 v[18:33], v[58:61], v[66:69], v[18:33]
	v_add_f32_e32 v58, v63, v62
	v_add_f32_e32 v58, v64, v58
	v_add_f32_e32 v62, v65, v58
	v_cvt_pk_bf16_f32 v58, v207, v70
	v_cvt_pk_bf16_f32 v59, v71, v72
	v_cvt_pk_bf16_f32 v60, v90, v63
	v_cvt_pk_bf16_f32 v61, v64, v65
	s_nop 1
	v_mfma_f32_32x32x16_bf16 v[2:17], v[38:41], v[58:61], v[2:17]
	v_mov_b32_e32 v38, v62
	v_mov_b32_e32 v247, v62
	s_nop 1
	v_permlane32_swap_b32_e32 v38, v247
	v_xor_b32_e32 v38, v38, v247
	v_xor_b32_e32 v38, v38, v62
	s_waitcnt lgkmcnt(0)
	v_add_f32_e32 v40, v62, v38
	v_fmac_f32_e32 v40, v147, v100
	v_mfma_f32_32x32x16_bf16 v[18:33], v[34:37], v[58:61], v[18:33]
.LBB0_1367:
	s_andn2_b64 vcc, exec, s[0:1]
	s_cbranch_vccnz .LBB0_1369
	v_lshl_add_u32 v0, s5, 1, v182
	s_nop 3
	ds_read_b128 v[2:5], v0
	s_nop 3
	ds_read_b128 v[18:21], v0 offset:32
	ds_read_b128 v[22:25], v0 offset:64
	ds_read_b128 v[58:61], v0 offset:96
	ds_read_b128 v[26:29], v0 offset:4608
	ds_read_b128 v[62:65], v0 offset:4640
	ds_read_b128 v[66:69], v0 offset:4672
	ds_read_b128 v[184:187], v0 offset:4704
	s_waitcnt lgkmcnt(7)
	v_mfma_f32_32x32x16_bf16 v[2:17], v[2:5], v[74:77], 0
	v_add3_u32 v0, v98, v175, v138
	s_waitcnt lgkmcnt(3)
	v_mfma_f32_32x32x16_bf16 v[26:41], v[26:29], v[74:77], 0
	v_mfma_f32_32x32x16_bf16 v[2:17], v[18:21], v[78:81], v[2:17]
	s_waitcnt lgkmcnt(2)
	v_mfma_f32_32x32x16_bf16 v[26:41], v[62:65], v[78:81], v[26:41]
	v_mfma_f32_32x32x16_bf16 v[2:17], v[22:25], v[82:85], v[2:17]
	v_add3_u32 v22, v98, v177, v138
	s_waitcnt lgkmcnt(1)
	v_mfma_f32_32x32x16_bf16 v[26:41], v[66:69], v[82:85], v[26:41]
	v_mfma_f32_32x32x16_bf16 v[2:17], v[58:61], v[86:89], v[2:17]
	ds_read_b128 v[18:21], v0 offset:9216
	ds_read_b128 v[94:97], v0 offset:9248
	ds_read_b128 v[98:101], v22 offset:9216
	ds_read_b128 v[90:93], v22 offset:9248
	ds_read_b128 v[70:73], v0 offset:9280
	ds_read_b128 v[62:65], v0 offset:9312
	ds_read_b128 v[66:69], v22 offset:9280
	ds_read_b128 v[58:61], v22 offset:9312
	s_waitcnt lgkmcnt(8)
; #define MFMA(a, b, c) __builtin_amdgcn_mfma_f32_32x32x16_bf16((a), (b), (c), 0, 0, 0)
; DI unsigned pack2(float a, float b) { f32x2_t v = {a, b}; bf16x2_t r = __builtin_convertvector(v, bf16x2_t); return __builtin_bit_cast(unsigned, r); }
; DI float fexp2(float x) { return __builtin_amdgcn_exp2f(x); }
; DI float shx(float v, int m) { return __shfl_xor(v, m, 64); }
; template <int DQK, bool MASKED, int MODE, class MF>
; DI void attn_step(const bf16_t* sK, const bf16_t* sVt, const bf16x8 (&qf)[DQK / 16], f32x16& o0, f32x16& o1, float& m, float& l,
;                   float sc, const MF& mf, int lane, f32x16 (&s)[2], float invl, bool lanevalid = true) {
;     ...
;   float mxr = -3.0e38f;
; #pragma unroll
;   for (int sub = 0; sub < 2; ++sub)
; #pragma unroll
;     for (int q = 0; q < 16; ++q) {
;       if (MASKED) { const int kk = sub * 32 + 16 * (q >> 3) + 8 * h + (q & 7); s[sub][q] = mf(kk) ? s[sub][q] : -3.0e38f; }
;       if (MODE != 2) mxr = fmaxf(mxr, s[sub][q]);
;     }
;   float alpha = 1.f;
;   if (MODE != 2) {
;     float mx = fmaxf(m, mxr * sc);
;     mx = fmaxf(mx, shx(mx, 32));
;     if (!MASKED) mx = lanevalid ? mx : m;
;     alpha = fexp2(m - mx);
;     m = mx;
;   }
;   const float moff = (!MASKED && !lanevalid) ? 1.0e30f : m;
;   float ps = 0.f;
; #pragma unroll
;   for (int sub = 0; sub < 2; ++sub)
; #pragma unroll
;     for (int q = 0; q < 16; ++q) {
;       float pv = fexp2(__builtin_fmaf(s[sub][q], sc, -moff));
;       if (MASKED && MODE != 0) pv = (s[sub][q] > -1.0e38f) ? pv : 0.f;
;       if (MODE == 2) pv *= invl;
;       s[sub][q] = pv;
;       ps += pv;
;     }
;   if (MODE != 2) {
;     ps += shx(ps, 32);
;     l = l * alpha + ps;
;   }
;   if (MODE == 1) return;
;   if (MODE == 0) {
; #pragma unroll
;     for (int q = 0; q < 16; ++q) { o0[q] *= alpha; o1[q] *= alpha; }
;   }
; #pragma unroll
;   for (int sub = 0; sub < 2; ++sub)
; #pragma unroll
;     for (int s2 = 0; s2 < 2; ++s2) {
;       union { bf16x8 v; unsigned u[4]; } pb;
; #pragma unroll
;       for (int e = 0; e < 4; ++e) pb.u[e] = pack2(s[sub][8 * s2 + 2 * e], s[sub][8 * s2 + 2 * e + 1]);
;       o0 = MFMA(vf[sub][s2][0], pb.v, o0);
;       o1 = MFMA(vf[sub][s2][1], pb.v, o1);
;     }
	v_mfma_f32_32x32x16_bf16 v[26:41], v[184:187], v[86:89], v[26:41]
	s_nop 1
	v_max3_f32 v0, v2, s8, v3
	v_max3_f32 v0, v0, v4, v5
	v_max3_f32 v0, v0, v6, v7
	v_max3_f32 v0, v0, v8, v9
	v_max3_f32 v0, v0, v10, v11
	v_max3_f32 v0, v0, v12, v13
	v_max3_f32 v0, v0, v14, v15
	v_max3_f32 v0, v0, v16, v17
	s_nop 1
	v_max3_f32 v0, v0, v26, v27
	v_max3_f32 v0, v0, v28, v29
	v_max3_f32 v0, v0, v30, v31
	v_max3_f32 v0, v0, v32, v33
	v_max3_f32 v0, v0, v34, v35
	v_max3_f32 v0, v0, v36, v37
	v_max3_f32 v0, v0, v38, v39
	v_max3_f32 v0, v0, v40, v41
	v_mul_f32_e32 v0, 0x3e38aa3b, v0
	v_max_f32_e32 v0, v149, v0
	v_mov_b32_e32 v22, v0
	v_mov_b32_e32 v247, v0
	s_nop 1
	v_permlane32_swap_b32_e32 v22, v247
	v_xor_b32_e32 v22, v22, v247
	v_xor_b32_e32 v22, v22, v0
	v_max_f32_e32 v22, v22, v22
	v_max_f32_e32 v0, v0, v22
	v_fma_f32 v2, v2, s33, -v0
	v_fma_f32 v3, v3, s33, -v0
	v_exp_f32_e32 v23, v2
	v_fma_f32 v4, v4, s33, -v0
	v_exp_f32_e32 v24, v3
	v_fma_f32 v5, v5, s33, -v0
	v_exp_f32_e32 v25, v4
	v_exp_f32_e32 v149, v5
	v_fma_f32 v3, v6, s33, -v0
	v_add_f32_e32 v2, 0, v23
	v_exp_f32_e32 v150, v3
	v_fma_f32 v3, v7, s33, -v0
	v_add_f32_e32 v2, v24, v2
	v_exp_f32_e32 v151, v3
	v_fma_f32 v3, v8, s33, -v0
	v_add_f32_e32 v2, v25, v2
	v_exp_f32_e32 v174, v3
	v_fma_f32 v3, v9, s33, -v0
	v_add_f32_e32 v2, v149, v2
	v_exp_f32_e32 v178, v3
	v_fma_f32 v3, v10, s33, -v0
	v_add_f32_e32 v2, v150, v2
	v_exp_f32_e32 v183, v3
	v_fma_f32 v3, v11, s33, -v0
	v_add_f32_e32 v2, v151, v2
	v_exp_f32_e32 v184, v3
	v_fma_f32 v3, v12, s33, -v0
	v_add_f32_e32 v2, v174, v2
	v_exp_f32_e32 v185, v3
	v_fma_f32 v3, v13, s33, -v0
	v_add_f32_e32 v2, v178, v2
	v_exp_f32_e32 v186, v3
	v_fma_f32 v3, v14, s33, -v0
	v_add_f32_e32 v2, v183, v2
	v_exp_f32_e32 v187, v3
	v_fma_f32 v3, v15, s33, -v0
	v_add_f32_e32 v2, v184, v2
	v_exp_f32_e32 v188, v3
	v_fma_f32 v3, v16, s33, -v0
	v_add_f32_e32 v2, v185, v2
	v_exp_f32_e32 v189, v3
	v_fma_f32 v3, v17, s33, -v0
	v_add_f32_e32 v2, v186, v2
	v_exp_f32_e32 v190, v3
	v_fma_f32 v3, v26, s33, -v0
	v_add_f32_e32 v2, v187, v2
	v_exp_f32_e32 v191, v3
	v_fma_f32 v3, v27, s33, -v0
	v_add_f32_e32 v2, v188, v2
	v_exp_f32_e32 v194, v3
	v_fma_f32 v3, v28, s33, -v0
	v_add_f32_e32 v2, v189, v2
	v_exp_f32_e32 v195, v3
	v_fma_f32 v3, v29, s33, -v0
	v_add_f32_e32 v2, v190, v2
	v_exp_f32_e32 v196, v3
	v_fma_f32 v3, v30, s33, -v0
	v_add_f32_e32 v2, v191, v2
	v_exp_f32_e32 v197, v3
	v_fma_f32 v3, v31, s33, -v0
	v_add_f32_e32 v2, v194, v2
	v_exp_f32_e32 v198, v3
	v_fma_f32 v3, v32, s33, -v0
	v_add_f32_e32 v2, v195, v2
	v_exp_f32_e32 v199, v3
	v_sub_f32_e32 v22, v148, v0
	v_add_f32_e32 v2, v196, v2
	v_add_f32_e32 v2, v197, v2
	v_exp_f32_e32 v148, v22
	v_add_f32_e32 v2, v198, v2
	v_add_f32_e32 v200, v199, v2
	v_fma_f32 v2, v33, s33, -v0
	v_exp_f32_e32 v201, v2
	v_fma_f32 v2, v34, s33, -v0
	v_exp_f32_e32 v202, v2
	v_pk_mul_f32 v[16:17], v[144:145], v[148:149] op_sel_hi:[1,0]
	v_pk_mul_f32 v[14:15], v[140:141], v[148:149] op_sel_hi:[1,0]
	v_pk_mul_f32 v[12:13], v[132:133], v[148:149] op_sel_hi:[1,0]
	v_pk_mul_f32 v[10:11], v[130:131], v[148:149] op_sel_hi:[1,0]
	v_pk_mul_f32 v[8:9], v[128:129], v[148:149] op_sel_hi:[1,0]
	v_pk_mul_f32 v[6:7], v[126:127], v[148:149] op_sel_hi:[1,0]
	v_pk_mul_f32 v[4:5], v[124:125], v[148:149] op_sel_hi:[1,0]
	v_pk_mul_f32 v[2:3], v[122:123], v[148:149] op_sel_hi:[1,0]
	v_cvt_pk_bf16_f32 v122, v23, v24
	v_cvt_pk_bf16_f32 v123, v25, v149
	v_cvt_pk_bf16_f32 v124, v150, v151
	v_cvt_pk_bf16_f32 v125, v174, v178
	v_pk_mul_f32 v[32:33], v[142:143], v[148:149] op_sel_hi:[1,0]
	v_pk_mul_f32 v[30:31], v[120:121], v[148:149] op_sel_hi:[1,0]
	s_waitcnt lgkmcnt(0)
	v_mfma_f32_32x32x16_bf16 v[2:17], v[18:21], v[122:125], v[2:17]
	v_mul_f32_e64 v28, v118, v148
	v_mul_f32_e64 v29, v119, v148
	v_mul_f32_e64 v26, v116, v148
	v_mul_f32_e64 v27, v117, v148
	v_mul_f32_e64 v24, v114, v148
	v_mul_f32_e64 v25, v115, v148
	v_pk_mul_f32 v[22:23], v[112:113], v[148:149] op_sel_hi:[1,0]
	v_pk_mul_f32 v[20:21], v[110:111], v[148:149] op_sel_hi:[1,0]
	v_pk_mul_f32 v[18:19], v[108:109], v[148:149] op_sel_hi:[1,0]
	v_fma_f32 v35, v35, s33, -v0
	v_add_f32_e32 v34, v201, v200
	v_mfma_f32_32x32x16_bf16 v[18:33], v[98:101], v[122:125], v[18:33]
	v_cvt_pk_bf16_f32 v98, v183, v184
	v_cvt_pk_bf16_f32 v99, v185, v186
	v_cvt_pk_bf16_f32 v100, v187, v188
	v_cvt_pk_bf16_f32 v101, v189, v190
	v_add_f32_e32 v34, v202, v34
	v_fma_f32 v39, v39, s33, -v0
	v_exp_f32_e32 v39, v39
	v_mfma_f32_32x32x16_bf16 v[2:17], v[94:97], v[98:101], v[2:17]
	v_exp_f32_e32 v94, v35
	v_fma_f32 v35, v36, s33, -v0
	v_exp_f32_e32 v95, v35
	v_fma_f32 v35, v37, s33, -v0
	v_exp_f32_e32 v96, v35
	v_add_f32_e32 v34, v94, v34
	v_add_f32_e32 v34, v95, v34
	v_mfma_f32_32x32x16_bf16 v[18:33], v[90:93], v[98:101], v[18:33]
	v_add_f32_e32 v90, v96, v34
	v_fma_f32 v34, v38, s33, -v0
	v_exp_f32_e32 v38, v34
	v_cvt_pk_bf16_f32 v34, v191, v194
	v_cvt_pk_bf16_f32 v35, v195, v196
	v_cvt_pk_bf16_f32 v36, v197, v198
	v_cvt_pk_bf16_f32 v37, v199, v201
	v_fma_f32 v40, v40, s33, -v0
	v_exp_f32_e32 v40, v40
	v_mfma_f32_32x32x16_bf16 v[2:17], v[70:73], v[34:37], v[2:17]
	v_fma_f32 v41, v41, s33, -v0
	v_exp_f32_e32 v41, v41
	v_add_f32_e32 v70, v38, v90
	v_mfma_f32_32x32x16_bf16 v[18:33], v[66:69], v[34:37], v[18:33]
	v_add_f32_e32 v34, v39, v70
	v_add_f32_e32 v34, v40, v34
	v_add_f32_e32 v66, v41, v34
	v_cvt_pk_bf16_f32 v34, v202, v94
	v_cvt_pk_bf16_f32 v35, v95, v96
	v_cvt_pk_bf16_f32 v36, v38, v39
	v_cvt_pk_bf16_f32 v37, v40, v41
	v_mov_b32_e32 v38, v66
	v_mov_b32_e32 v247, v66
	s_nop 1
	v_permlane32_swap_b32_e32 v38, v247
	v_xor_b32_e32 v38, v38, v247
	v_xor_b32_e32 v38, v38, v66
	s_waitcnt lgkmcnt(0)
	v_add_f32_e32 v40, v66, v38
	v_mfma_f32_32x32x16_bf16 v[2:17], v[62:65], v[34:37], v[2:17]
	v_fmac_f32_e32 v40, v147, v148
	v_mfma_f32_32x32x16_bf16 v[18:33], v[58:61], v[34:37], v[18:33]

; #define MFMA(a, b, c) __builtin_amdgcn_mfma_f32_32x32x16_bf16((a), (b), (c), 0, 0, 0)
; template <int DQK, bool MASKED, int MODE, class MF>
; DI void attn_step(const bf16_t* sK, const bf16_t* sVt, const bf16x8 (&qf)[DQK / 16], f32x16& o0, f32x16& o1, float& m, float& l,
;                   float sc, const MF& mf, int lane, f32x16 (&s)[2], float invl, bool lanevalid = true) {
;     ...
;   bf16x8 kf[2][DQK / 16];
; #pragma unroll
;   for (int sub = 0; sub < 2; ++sub)
; #pragma unroll
;     for (int ks = 0; ks < DQK / 16; ++ks) kf[sub][ks] = *(const bf16x8*)(sK + (sub * 32 + pr) * KST + ks * 16 + 8 * h);
;   __builtin_amdgcn_sched_barrier(0);
; #pragma unroll
;   for (int q = 0; q < 16; ++q) { s[0][q] = 0.f; s[1][q] = 0.f; }
; #pragma unroll
;   for (int ks = 0; ks < DQK / 16; ++ks) {
;     s[0] = MFMA(kf[0][ks], qf[ks], s[0]);
;     s[1] = MFMA(kf[1][ks], qf[ks], s[1]);
;   }
;   bf16x8 vf[2][2][2];
;   if (MODE != 1) {
; #pragma unroll
;     for (int sub = 0; sub < 2; ++sub)
; #pragma unroll
;       for (int s2 = 0; s2 < 2; ++s2) {
;         vf[sub][s2][0] = *(const bf16x8*)(sVt + r * 72 + sub * 32 + s2 * 16 + 8 * h);
;         vf[sub][s2][1] = *(const bf16x8*)(sVt + (32 + r) * 72 + sub * 32 + s2 * 16 + 8 * h);
;       }
;     __builtin_amdgcn_sched_barrier(0);
;   }
;   float mxr = -3.0e38f;
; #pragma unroll
;   for (int sub = 0; sub < 2; ++sub)
; #pragma unroll
;     for (int q = 0; q < 16; ++q) {
;       if (MASKED) { const int kk = sub * 32 + 16 * (q >> 3) + 8 * h + (q & 7); s[sub][q] = mf(kk) ? s[sub][q] : -3.0e38f; }
; DI void phase_attn_swa(const Params& P, const float* sinks, bf16_t* og, unsigned char* smem, int L, int G) {
;     ...
;       auto mf = [&](int kk) { const int key = key0 + kk; return key <= t && key > t - 128; };
;       attn_step<64, true, 0>(sK + cb * KVB64, sVt + cb * KVB64, qf, o0, o1, m, l, sc, mf, lane, s, 0.f);
.LBB0_1672:
	s_mulk_i32 s0, 0x4800
	v_add_u32_e32 v40, s0, v163
	ds_read_b128 v[32:35], v40
	ds_read_b128 v[96:99], v40 offset:32
	ds_read_b128 v[100:103], v40 offset:64
	ds_read_b128 v[104:107], v40 offset:96
	ds_read_b128 v[36:39], v40 offset:4608
	ds_read_b128 v[108:111], v40 offset:4640
	ds_read_b128 v[112:115], v40 offset:4672
	ds_read_b128 v[178:181], v40 offset:4704
	v_add_u32_e32 v116, s0, v137
	s_waitcnt lgkmcnt(7)
	v_mfma_f32_32x32x16_bf16 v[48:63], v[32:35], v[64:67], 0
	s_waitcnt lgkmcnt(3)
	v_mfma_f32_32x32x16_bf16 v[32:47], v[36:39], v[64:67], 0
	v_mfma_f32_32x32x16_bf16 v[48:63], v[96:99], v[68:71], v[48:63]
	v_add3_u32 v96, v116, v164, v171
	v_add3_u32 v97, v116, v165, v171
	s_waitcnt lgkmcnt(2)
	v_mfma_f32_32x32x16_bf16 v[32:47], v[108:111], v[68:71], v[32:47]
	v_mfma_f32_32x32x16_bf16 v[48:63], v[100:103], v[72:75], v[48:63]
	s_waitcnt lgkmcnt(1)
	v_mfma_f32_32x32x16_bf16 v[32:47], v[112:115], v[72:75], v[32:47]
	v_mfma_f32_32x32x16_bf16 v[48:63], v[104:107], v[76:79], v[48:63]
	ds_read_b128 v[124:127], v96 offset:9216
	ds_read_b128 v[116:119], v96 offset:9248
	ds_read_b128 v[120:123], v97 offset:9216
	ds_read_b128 v[112:115], v97 offset:9248
	ds_read_b128 v[108:111], v96 offset:9280
	ds_read_b128 v[100:103], v96 offset:9312
	ds_read_b128 v[104:107], v97 offset:9280
	ds_read_b128 v[96:99], v97 offset:9312
	s_waitcnt lgkmcnt(8)
	v_mfma_f32_32x32x16_bf16 v[32:47], v[178:181], v[76:79], v[32:47]
	v_add_u32_e32 v128, s8, v162
	v_cmp_le_u32_e32 vcc, v128, v150
	v_cmp_gt_i32_e64 s[0:1], v128, v151
	s_and_b64 vcc, vcc, s[0:1]
	v_cndmask_b32_e32 v48, v172, v48, vcc
	v_cmp_lt_u32_e32 vcc, v128, v150
	v_cmp_ge_i32_e64 s[0:1], v128, v151
	s_and_b64 vcc, vcc, s[0:1]
	v_add_u32_e32 v177, 2, v128
	v_cndmask_b32_e32 v49, v172, v49, vcc
	v_cmp_le_u32_e32 vcc, v177, v150
	v_cmp_gt_i32_e64 s[0:1], v177, v151
	s_and_b64 vcc, vcc, s[0:1]
	v_add_u32_e32 v177, 3, v128
	v_cndmask_b32_e32 v50, v172, v50, vcc
	v_cmp_le_u32_e32 vcc, v177, v150
	v_cmp_gt_i32_e64 s[0:1], v177, v151
	s_and_b64 vcc, vcc, s[0:1]
	v_add_u32_e32 v177, 4, v128
	v_cndmask_b32_e32 v51, v172, v51, vcc
	v_cmp_le_u32_e32 vcc, v177, v150
	v_cmp_gt_i32_e64 s[0:1], v177, v151
	s_and_b64 vcc, vcc, s[0:1]
	v_add_u32_e32 v177, 5, v128
	v_cndmask_b32_e32 v52, v172, v52, vcc
	v_cmp_le_u32_e32 vcc, v177, v150
	v_cmp_gt_i32_e64 s[0:1], v177, v151
	s_and_b64 vcc, vcc, s[0:1]
	v_add_u32_e32 v177, 6, v128
	v_cndmask_b32_e32 v53, v172, v53, vcc
	v_cmp_le_u32_e32 vcc, v177, v150
	v_cmp_gt_i32_e64 s[0:1], v177, v151
	v_add_u32_e32 v177, s8, v161
	s_and_b64 vcc, vcc, s[0:1]
	v_or_b32_e32 v178, 7, v177
	v_cndmask_b32_e32 v54, v172, v54, vcc
	v_cmp_le_u32_e32 vcc, v178, v150
	v_cmp_gt_i32_e64 s[0:1], v178, v151
	s_and_b64 vcc, vcc, s[0:1]
	v_add_u32_e32 v178, 16, v128
	v_cndmask_b32_e32 v55, v172, v55, vcc
	v_cmp_le_u32_e32 vcc, v178, v150
	v_cmp_gt_i32_e64 s[0:1], v178, v151
	s_and_b64 vcc, vcc, s[0:1]
	v_add_u32_e32 v178, 17, v128
	v_cndmask_b32_e32 v56, v172, v56, vcc
	v_cmp_le_u32_e32 vcc, v178, v150
	v_cmp_gt_i32_e64 s[0:1], v178, v151
	s_and_b64 vcc, vcc, s[0:1]
	v_add_u32_e32 v178, 18, v128
	v_cndmask_b32_e32 v57, v172, v57, vcc
	v_cmp_le_u32_e32 vcc, v178, v150
	v_cmp_gt_i32_e64 s[0:1], v178, v151
	s_and_b64 vcc, vcc, s[0:1]
	v_add_u32_e32 v178, 19, v128
	v_cndmask_b32_e32 v58, v172, v58, vcc
	v_cmp_le_u32_e32 vcc, v178, v150
	v_cmp_gt_i32_e64 s[0:1], v178, v151
	s_and_b64 vcc, vcc, s[0:1]
	v_add_u32_e32 v178, 20, v128
	v_cndmask_b32_e32 v59, v172, v59, vcc
	v_cmp_le_u32_e32 vcc, v178, v150
	v_cmp_gt_i32_e64 s[0:1], v178, v151
	s_and_b64 vcc, vcc, s[0:1]
	v_add_u32_e32 v178, 21, v128
	v_cndmask_b32_e32 v60, v172, v60, vcc
	v_cmp_le_u32_e32 vcc, v178, v150
	v_cmp_gt_i32_e64 s[0:1], v178, v151
	s_and_b64 vcc, vcc, s[0:1]
	v_add_u32_e32 v178, 22, v128
	v_cndmask_b32_e32 v61, v172, v61, vcc
	v_cmp_le_u32_e32 vcc, v178, v150
	v_cmp_gt_i32_e64 s[0:1], v178, v151
	s_and_b64 vcc, vcc, s[0:1]
	v_or_b32_e32 v178, 23, v177
	v_cndmask_b32_e32 v62, v172, v62, vcc
	v_cmp_le_u32_e32 vcc, v178, v150
	v_cmp_gt_i32_e64 s[0:1], v178, v151
	s_and_b64 vcc, vcc, s[0:1]
	v_add_u32_e32 v178, 32, v128
	v_cndmask_b32_e32 v63, v172, v63, vcc
	v_cmp_le_u32_e32 vcc, v178, v150
	v_cmp_gt_i32_e64 s[0:1], v178, v151
	s_and_b64 vcc, vcc, s[0:1]
	v_cndmask_b32_e32 v178, v172, v32, vcc
	v_add_u32_e32 v32, 33, v128
	v_cmp_le_u32_e32 vcc, v32, v150
	v_cmp_gt_i32_e64 s[0:1], v32, v151
	s_and_b64 vcc, vcc, s[0:1]
	v_add_u32_e32 v32, 34, v128
	v_cndmask_b32_e32 v33, v172, v33, vcc
	v_cmp_le_u32_e32 vcc, v32, v150
	v_cmp_gt_i32_e64 s[0:1], v32, v151
	s_and_b64 vcc, vcc, s[0:1]
	v_add_u32_e32 v32, 35, v128
	v_cndmask_b32_e32 v34, v172, v34, vcc
	v_cmp_le_u32_e32 vcc, v32, v150
	v_cmp_gt_i32_e64 s[0:1], v32, v151
	s_and_b64 vcc, vcc, s[0:1]
	v_add_u32_e32 v32, 36, v128
	v_cndmask_b32_e32 v35, v172, v35, vcc
	v_cmp_le_u32_e32 vcc, v32, v150
	v_cmp_gt_i32_e64 s[0:1], v32, v151
	s_and_b64 vcc, vcc, s[0:1]
	v_add_u32_e32 v32, 37, v128
	v_cndmask_b32_e32 v36, v172, v36, vcc
	v_cmp_le_u32_e32 vcc, v32, v150
	v_cmp_gt_i32_e64 s[0:1], v32, v151
	s_and_b64 vcc, vcc, s[0:1]
	v_add_u32_e32 v32, 38, v128
	v_cndmask_b32_e32 v37, v172, v37, vcc
	v_cmp_le_u32_e32 vcc, v32, v150
	v_cmp_gt_i32_e64 s[0:1], v32, v151
	s_and_b64 vcc, vcc, s[0:1]
	v_or_b32_e32 v32, 39, v177
	v_cndmask_b32_e32 v38, v172, v38, vcc
	v_cmp_le_u32_e32 vcc, v32, v150
	v_cmp_gt_i32_e64 s[0:1], v32, v151
	s_and_b64 vcc, vcc, s[0:1]
	v_add_u32_e32 v32, 48, v128
	v_cndmask_b32_e32 v39, v172, v39, vcc
	v_cmp_le_u32_e32 vcc, v32, v150
	v_cmp_gt_i32_e64 s[0:1], v32, v151
	s_and_b64 vcc, vcc, s[0:1]
	v_add_u32_e32 v32, 49, v128
	v_cndmask_b32_e32 v179, v172, v40, vcc
; DI float fexp2(float x) { return __builtin_amdgcn_exp2f(x); }
; DI float shx(float v, int m) { return __shfl_xor(v, m, 64); }
; template <int DQK, bool MASKED, int MODE, class MF>
; DI void attn_step(const bf16_t* sK, const bf16_t* sVt, const bf16x8 (&qf)[DQK / 16], f32x16& o0, f32x16& o1, float& m, float& l,
;                   float sc, const MF& mf, int lane, f32x16 (&s)[2], float invl, bool lanevalid = true) {
;     ...
;   float mxr = -3.0e38f;
; #pragma unroll
;   for (int sub = 0; sub < 2; ++sub)
; #pragma unroll
;     for (int q = 0; q < 16; ++q) {
;       if (MASKED) { const int kk = sub * 32 + 16 * (q >> 3) + 8 * h + (q & 7); s[sub][q] = mf(kk) ? s[sub][q] : -3.0e38f; }
;       if (MODE != 2) mxr = fmaxf(mxr, s[sub][q]);
;     }
;   float alpha = 1.f;
;   if (MODE != 2) {
;     float mx = fmaxf(m, mxr * sc);
;     mx = fmaxf(mx, shx(mx, 32));
;     if (!MASKED) mx = lanevalid ? mx : m;
;     alpha = fexp2(m - mx);
;     m = mx;
;   }
;   const float moff = (!MASKED && !lanevalid) ? 1.0e30f : m;
;   float ps = 0.f;
; #pragma unroll
;   for (int sub = 0; sub < 2; ++sub)
; #pragma unroll
;     for (int q = 0; q < 16; ++q) {
;       float pv = fexp2(__builtin_fmaf(s[sub][q], sc, -moff));
;       if (MASKED && MODE != 0) pv = (s[sub][q] > -1.0e38f) ? pv : 0.f;
;       if (MODE == 2) pv *= invl;
;       s[sub][q] = pv;
;       ps += pv;
;     }
;   if (MODE != 2) {
;     ps += shx(ps, 32);
;     l = l * alpha + ps;
;   }
;   if (MODE == 1) return;
;   if (MODE == 0) {
; #pragma unroll
;     for (int q = 0; q < 16; ++q) { o0[q] *= alpha; o1[q] *= alpha; }
	v_cmp_le_u32_e32 vcc, v32, v150
	v_cmp_gt_i32_e64 s[0:1], v32, v151
	s_and_b64 vcc, vcc, s[0:1]
	v_add_u32_e32 v32, 50, v128
	v_cndmask_b32_e32 v41, v172, v41, vcc
	v_cmp_le_u32_e32 vcc, v32, v150
	v_cmp_gt_i32_e64 s[0:1], v32, v151
	s_and_b64 vcc, vcc, s[0:1]
	v_add_u32_e32 v32, 51, v128
	v_cndmask_b32_e32 v42, v172, v42, vcc
	v_cmp_le_u32_e32 vcc, v32, v150
	v_cmp_gt_i32_e64 s[0:1], v32, v151
	s_and_b64 vcc, vcc, s[0:1]
	v_add_u32_e32 v32, 52, v128
	v_cndmask_b32_e32 v43, v172, v43, vcc
	v_cmp_le_u32_e32 vcc, v32, v150
	v_cmp_gt_i32_e64 s[0:1], v32, v151
	s_and_b64 vcc, vcc, s[0:1]
	v_add_u32_e32 v32, 53, v128
	v_cndmask_b32_e32 v44, v172, v44, vcc
	v_cmp_le_u32_e32 vcc, v32, v150
	v_cmp_gt_i32_e64 s[0:1], v32, v151
	s_and_b64 vcc, vcc, s[0:1]
	v_add_u32_e32 v32, 54, v128
	v_cndmask_b32_e32 v45, v172, v45, vcc
	v_cmp_le_u32_e32 vcc, v32, v150
	v_cmp_gt_i32_e64 s[0:1], v32, v151
	s_and_b64 vcc, vcc, s[0:1]
	v_or_b32_e32 v32, 55, v177
	v_cndmask_b32_e32 v46, v172, v46, vcc
	v_cmp_le_u32_e32 vcc, v32, v150
	v_cmp_gt_i32_e64 s[0:1], v32, v151
	v_max3_f32 v32, v48, s14, v49
	v_max3_f32 v32, v32, v50, v51
	v_max3_f32 v32, v32, v52, v53
	v_max3_f32 v32, v32, v54, v55
	v_max3_f32 v32, v32, v56, v57
	v_max3_f32 v32, v32, v58, v59
	v_max3_f32 v32, v32, v60, v61
	v_max3_f32 v32, v32, v62, v63
	v_max3_f32 v32, v32, v178, v33
	v_max3_f32 v32, v32, v34, v35
	v_max3_f32 v32, v32, v36, v37
	v_max3_f32 v32, v32, v38, v39
	v_max3_f32 v32, v32, v179, v41
	s_and_b64 vcc, vcc, s[0:1]
	v_max3_f32 v32, v32, v42, v43
	v_cndmask_b32_e32 v47, v172, v47, vcc
	v_max3_f32 v32, v32, v44, v45
	v_max3_f32 v32, v32, v46, v47
	v_mul_f32_e32 v32, 0x3e38aa3b, v32
	v_max_f32_e32 v40, v176, v176
	v_max_f32_e32 v32, v40, v32
	v_mov_b32_e32 v40, v32
	v_mov_b32_e32 v247, v32
	s_nop 1
	v_permlane32_swap_b32_e32 v40, v247
	v_xor_b32_e32 v40, v40, v247
	v_xor_b32_e32 v40, v40, v32
	s_add_i32 s18, s18, 1
	s_add_i32 s0, s17, s18
	s_add_i32 s8, s8, 64
	s_add_i32 s0, s0, -1
	v_max_f32_e32 v40, v40, v40
	v_max_f32_e32 v32, v32, v40
	v_fma_f32 v40, v48, s15, -v32
	v_exp_f32_e32 v48, v40
	v_fma_f32 v49, v49, s15, -v32
	v_exp_f32_e32 v49, v49
	v_fma_f32 v50, v50, s15, -v32
	v_exp_f32_e32 v50, v50
	v_fma_f32 v51, v51, s15, -v32
	v_exp_f32_e32 v51, v51
	v_fma_f32 v52, v52, s15, -v32
	v_add_f32_e32 v128, 0, v48
	v_exp_f32_e32 v52, v52
	v_fma_f32 v53, v53, s15, -v32
	v_add_f32_e32 v128, v49, v128
	v_exp_f32_e32 v53, v53
	v_fma_f32 v54, v54, s15, -v32
	v_add_f32_e32 v128, v50, v128
	v_exp_f32_e32 v54, v54
	v_fma_f32 v55, v55, s15, -v32
	v_add_f32_e32 v128, v51, v128
	v_exp_f32_e32 v55, v55
	v_fma_f32 v56, v56, s15, -v32
	v_add_f32_e32 v128, v52, v128
	v_exp_f32_e32 v56, v56
	v_fma_f32 v57, v57, s15, -v32
	v_add_f32_e32 v128, v53, v128
	v_exp_f32_e32 v57, v57
	v_fma_f32 v58, v58, s15, -v32
	v_add_f32_e32 v128, v54, v128
	v_exp_f32_e32 v58, v58
	v_fma_f32 v59, v59, s15, -v32
	v_add_f32_e32 v128, v55, v128
	v_exp_f32_e32 v59, v59
	v_fma_f32 v60, v60, s15, -v32
	v_add_f32_e32 v128, v56, v128
	v_exp_f32_e32 v60, v60
	v_fma_f32 v61, v61, s15, -v32
	v_add_f32_e32 v128, v57, v128
	v_exp_f32_e32 v61, v61
	v_fma_f32 v62, v62, s15, -v32
	v_add_f32_e32 v128, v58, v128
	v_exp_f32_e32 v62, v62
	v_fma_f32 v63, v63, s15, -v32
	v_sub_f32_e32 v40, v176, v32
	v_add_f32_e32 v128, v59, v128
	v_exp_f32_e32 v63, v63
	v_fma_f32 v176, v178, s15, -v32
	v_add_f32_e32 v128, v60, v128
	v_exp_f32_e32 v176, v176
	v_fma_f32 v33, v33, s15, -v32
	v_add_f32_e32 v128, v61, v128
	v_exp_f32_e32 v33, v33
	v_fma_f32 v34, v34, s15, -v32
	v_add_f32_e32 v128, v62, v128
	v_exp_f32_e32 v177, v34
	v_fma_f32 v34, v35, s15, -v32
	v_add_f32_e32 v128, v63, v128
	v_exp_f32_e32 v178, v34
	v_fma_f32 v34, v36, s15, -v32
	v_add_f32_e32 v128, v176, v128
	v_exp_f32_e32 v180, v34
	v_fma_f32 v35, v37, s15, -v32
	v_add_f32_e32 v34, v33, v128
	v_exp_f32_e32 v128, v35
	v_fma_f32 v35, v38, s15, -v32
	v_add_f32_e32 v34, v177, v34
	v_exp_f32_e32 v38, v35
	v_fma_f32 v35, v39, s15, -v32
	v_add_f32_e32 v34, v178, v34
	v_exp_f32_e32 v39, v35
	v_add_f32_e32 v34, v180, v34
	v_exp_f32_e32 v40, v40
	v_add_f32_e32 v34, v128, v34
	v_add_f32_e32 v34, v38, v34
	v_add_f32_e32 v181, v39, v34
	v_fma_f32 v34, v179, s15, -v32
	v_exp_f32_e32 v179, v34
	v_pk_mul_f32 v[14:15], v[14:15], v[40:41] op_sel_hi:[1,0]
	v_pk_mul_f32 v[12:13], v[12:13], v[40:41] op_sel_hi:[1,0]
	v_pk_mul_f32 v[10:11], v[10:11], v[40:41] op_sel_hi:[1,0]
	v_pk_mul_f32 v[8:9], v[8:9], v[40:41] op_sel_hi:[1,0]
	v_pk_mul_f32 v[6:7], v[6:7], v[40:41] op_sel_hi:[1,0]
	v_pk_mul_f32 v[4:5], v[4:5], v[40:41] op_sel_hi:[1,0]
	v_pk_mul_f32 v[2:3], v[2:3], v[40:41] op_sel_hi:[1,0]
	v_pk_mul_f32 v[0:1], v[0:1], v[40:41] op_sel_hi:[1,0]
	v_pk_mul_f32 v[30:31], v[30:31], v[40:41] op_sel_hi:[1,0]
	v_cvt_pk_bf16_f32 v34, v48, v49
	v_cvt_pk_bf16_f32 v35, v50, v51
	v_cvt_pk_bf16_f32 v36, v52, v53
	v_cvt_pk_bf16_f32 v37, v54, v55
	v_pk_mul_f32 v[28:29], v[28:29], v[40:41] op_sel_hi:[1,0]
	v_pk_mul_f32 v[26:27], v[26:27], v[40:41] op_sel_hi:[1,0]
	v_pk_mul_f32 v[24:25], v[24:25], v[40:41] op_sel_hi:[1,0]
	v_pk_mul_f32 v[22:23], v[22:23], v[40:41] op_sel_hi:[1,0]
	v_pk_mul_f32 v[20:21], v[20:21], v[40:41] op_sel_hi:[1,0]
	v_pk_mul_f32 v[18:19], v[18:19], v[40:41] op_sel_hi:[1,0]
	v_pk_mul_f32 v[16:17], v[16:17], v[40:41] op_sel_hi:[1,0]
	s_waitcnt lgkmcnt(0)
; #define MFMA(a, b, c) __builtin_amdgcn_mfma_f32_32x32x16_bf16((a), (b), (c), 0, 0, 0)
; DI unsigned pack2(float a, float b) { f32x2_t v = {a, b}; bf16x2_t r = __builtin_convertvector(v, bf16x2_t); return __builtin_bit_cast(unsigned, r); }
; DI float shx(float v, int m) { return __shfl_xor(v, m, 64); }
; template <int DQK, bool MASKED, int MODE, class MF>
; DI void attn_step(const bf16_t* sK, const bf16_t* sVt, const bf16x8 (&qf)[DQK / 16], f32x16& o0, f32x16& o1, float& m, float& l,
;                   float sc, const MF& mf, int lane, f32x16 (&s)[2], float invl, bool lanevalid = true) {
;     ...
;   if (MODE != 2) {
;     ps += shx(ps, 32);
;     l = l * alpha + ps;
;   }
;   if (MODE == 1) return;
;   if (MODE == 0) {
; #pragma unroll
;     for (int q = 0; q < 16; ++q) { o0[q] *= alpha; o1[q] *= alpha; }
;   }
; #pragma unroll
;   for (int sub = 0; sub < 2; ++sub)
; #pragma unroll
;     for (int s2 = 0; s2 < 2; ++s2) {
;       union { bf16x8 v; unsigned u[4]; } pb;
; #pragma unroll
;       for (int e = 0; e < 4; ++e) pb.u[e] = pack2(s[sub][8 * s2 + 2 * e], s[sub][8 * s2 + 2 * e + 1]);
;       o0 = MFMA(vf[sub][s2][0], pb.v, o0);
;       o1 = MFMA(vf[sub][s2][1], pb.v, o1);
;     }
; DI void phase_attn_swa(const Params& P, const float* sinks, bf16_t* og, unsigned char* smem, int L, int G) {
;     ...
;     for (int j = jlo; j <= jhi; ++j) {
;       const int key0 = j * 64, cb = (j - jlo) & 1;
;       __syncthreads();
;       if (j < jhi) kv64_store(R, sK + (cb ^ 1) * KVB64, sVt + (cb ^ 1) * KVB64, tid);
;       if (j + 1 < jhi) kv64_fetch(R, kb, 256, vb, SEQ, key0 + 128, true, tid);
;       __builtin_amdgcn_sched_barrier(0);
;       auto mf = [&](int kk) { const int key = key0 + kk; return key <= t && key > t - 128; };
;       attn_step<64, true, 0>(sK + cb * KVB64, sVt + cb * KVB64, qf, o0, o1, m, l, sc, mf, lane, s, 0.f);
;     }
	v_mfma_f32_32x32x16_bf16 v[0:15], v[124:127], v[34:37], v[0:15]
	v_fma_f32 v42, v42, s15, -v32
	v_exp_f32_e32 v42, v42
	v_fma_f32 v43, v43, s15, -v32
	v_exp_f32_e32 v43, v43
	v_fma_f32 v44, v44, s15, -v32
	v_add_f32_e32 v48, v179, v181
	v_exp_f32_e32 v44, v44
	v_mfma_f32_32x32x16_bf16 v[16:31], v[120:123], v[34:37], v[16:31]
	v_fma_f32 v34, v41, s15, -v32
	v_exp_f32_e32 v41, v34
	v_cvt_pk_bf16_f32 v34, v56, v57
	v_cvt_pk_bf16_f32 v35, v58, v59
	v_cvt_pk_bf16_f32 v36, v60, v61
	v_cvt_pk_bf16_f32 v37, v62, v63
	v_add_f32_e32 v48, v41, v48
	s_cmp_ge_u32 s0, s11
	v_mfma_f32_32x32x16_bf16 v[0:15], v[116:119], v[34:37], v[0:15]
	v_mfma_f32_32x32x16_bf16 v[16:31], v[112:115], v[34:37], v[16:31]
	v_add_f32_e32 v34, v42, v48
	v_add_f32_e32 v34, v43, v34
	v_add_f32_e32 v48, v44, v34
	v_cvt_pk_bf16_f32 v34, v176, v33
	v_cvt_pk_bf16_f32 v35, v177, v178
	v_cvt_pk_bf16_f32 v36, v180, v128
	v_cvt_pk_bf16_f32 v37, v38, v39
	v_fma_f32 v33, v45, s15, -v32
	v_fma_f32 v38, v46, s15, -v32
	v_mfma_f32_32x32x16_bf16 v[0:15], v[108:111], v[34:37], v[0:15]
	v_exp_f32_e32 v33, v33
	v_exp_f32_e32 v39, v38
	v_fma_f32 v38, v47, s15, -v32
	v_exp_f32_e32 v45, v38
	v_add_f32_e32 v38, v33, v48
	v_mfma_f32_32x32x16_bf16 v[16:31], v[104:107], v[34:37], v[16:31]
	v_add_f32_e32 v34, v39, v38
	v_cvt_pk_bf16_f32 v36, v179, v41
	v_cvt_pk_bf16_f32 v37, v42, v43
	v_cvt_pk_bf16_f32 v38, v44, v33
	v_cvt_pk_bf16_f32 v39, v39, v45
	v_add_f32_e32 v34, v45, v34
	v_mov_b32_e32 v35, v34
	v_mov_b32_e32 v247, v34
	s_nop 1
	v_permlane32_swap_b32_e32 v35, v247
	v_xor_b32_e32 v35, v35, v247
	v_xor_b32_e32 v35, v35, v34
	v_mfma_f32_32x32x16_bf16 v[0:15], v[100:103], v[36:39], v[0:15]
	s_waitcnt lgkmcnt(0)
	v_add_f32_e32 v34, v34, v35
	v_fmac_f32_e32 v34, v175, v40
	v_mfma_f32_32x32x16_bf16 v[16:31], v[96:99], v[36:39], v[16:31]
	s_cbranch_scc1 .LBB0_1659
	v_mov_b32_e32 v175, v34
	v_mov_b32_e32 v176, v32
	s_branch .LBB0_1668
